# GEMM epilogues de-serialised further: SwiGLU rstd LDS reads issued together, residual epilogue counted vmcnt before second-half math and sum-of-squares chains interleaved in pairs
# speedup vs baseline: 1.0053x; 1.0053x over previous
.LBB0_31:
	s_add_u32 s46, s50, 0x100
	s_addc_u32 s47, s51, 0
	s_add_i32 s6, 0, 0x10000
	v_add_u32_e32 v146, s6, v206
	ds_read_b128 v[128:131], v146
	ds_read_b128 v[132:135], v146 offset:1024
	ds_read_b128 v[136:139], v146 offset:2048
	ds_read_b128 v[146:149], v146 offset:3072
	s_cmp_eq_u32 s12, 40
	s_cselect_b32 s53, s31, s47
	s_cselect_b32 s52, s30, s46
	s_cselect_b32 s49, s35, s11
	s_cselect_b32 s48, s34, s10
	v_lshl_add_u64 v[214:215], s[50:51], 0, v[158:159]
	s_add_i32 m0, s58, 0xc000
	ds_read_b128 v[162:165], v208
	ds_read_b128 v[166:169], v208 offset:1024
	ds_read_b128 v[170:173], v208 offset:2048
	ds_read_b128 v[174:177], v208 offset:3072
	ds_read_b128 v[178:181], v208 offset:4096
	ds_read_b128 v[182:185], v208 offset:5120
	ds_read_b128 v[194:197], v208 offset:6144
	ds_read_b128 v[210:213], v208 offset:7168
	global_load_lds_dwordx4 v[214:215], off
	v_lshl_add_u64 v[214:215], s[50:51], 0, v[160:161]
	s_add_i32 m0, s58, 0xe000
	s_nop 0
	global_load_lds_dwordx4 v[214:215], off
	s_add_i32 s19, 0, 0x14000
	v_add_u32_e32 v192, s19, v206
	ds_read_b128 v[214:217], v192
	ds_read_b128 v[218:221], v192 offset:1024
	ds_read_b128 v[222:225], v192 offset:2048
	ds_read_b128 v[226:229], v192 offset:3072
	s_nop 0
	s_waitcnt vmcnt(8)
	s_waitcnt lgkmcnt(0)
	s_barrier
	v_mfma_f32_16x16x32_bf16 v[124:127], v[128:131], v[162:165], v[124:127]
	v_mfma_f32_16x16x32_bf16 v[120:123], v[136:139], v[162:165], v[120:123]
	v_mfma_f32_16x16x32_bf16 v[108:111], v[128:131], v[170:173], v[108:111]
	v_mfma_f32_16x16x32_bf16 v[104:107], v[136:139], v[170:173], v[104:107]
	v_mfma_f32_16x16x32_bf16 v[96:99], v[128:131], v[178:181], v[96:99]
	v_mfma_f32_16x16x32_bf16 v[88:91], v[136:139], v[178:181], v[88:91]
	v_mfma_f32_16x16x32_bf16 v[84:87], v[128:131], v[194:197], v[84:87]
	v_mfma_f32_16x16x32_bf16 v[80:83], v[136:139], v[194:197], v[80:83]
	v_mfma_f32_16x16x32_bf16 v[124:127], v[132:135], v[166:169], v[124:127]
	v_mfma_f32_16x16x32_bf16 v[120:123], v[146:149], v[166:169], v[120:123]
	v_mfma_f32_16x16x32_bf16 v[108:111], v[132:135], v[174:177], v[108:111]
	v_mfma_f32_16x16x32_bf16 v[104:107], v[146:149], v[174:177], v[104:107]
	v_mfma_f32_16x16x32_bf16 v[96:99], v[132:135], v[182:185], v[96:99]
	v_mfma_f32_16x16x32_bf16 v[88:91], v[146:149], v[182:185], v[88:91]
	v_mfma_f32_16x16x32_bf16 v[84:87], v[132:135], v[210:213], v[84:87]
	v_mfma_f32_16x16x32_bf16 v[80:83], v[146:149], v[210:213], v[80:83]
	v_mfma_f32_16x16x32_bf16 v[116:119], v[214:217], v[162:165], v[116:119]
	v_mfma_f32_16x16x32_bf16 v[112:115], v[222:225], v[162:165], v[112:115]
	v_mfma_f32_16x16x32_bf16 v[100:103], v[214:217], v[170:173], v[100:103]
	v_mfma_f32_16x16x32_bf16 v[92:95], v[222:225], v[170:173], v[92:95]
	v_mfma_f32_16x16x32_bf16 v[76:79], v[214:217], v[178:181], v[76:79]
	v_mfma_f32_16x16x32_bf16 v[72:75], v[222:225], v[178:181], v[72:75]
	v_mfma_f32_16x16x32_bf16 v[68:71], v[214:217], v[194:197], v[68:71]
	v_mfma_f32_16x16x32_bf16 v[64:67], v[222:225], v[194:197], v[64:67]
	v_mfma_f32_16x16x32_bf16 v[116:119], v[218:221], v[166:169], v[116:119]
	v_mfma_f32_16x16x32_bf16 v[112:115], v[226:229], v[166:169], v[112:115]
	v_mfma_f32_16x16x32_bf16 v[100:103], v[218:221], v[174:177], v[100:103]
	v_mfma_f32_16x16x32_bf16 v[92:95], v[226:229], v[174:177], v[92:95]
	v_mfma_f32_16x16x32_bf16 v[76:79], v[218:221], v[182:185], v[76:79]
	v_mfma_f32_16x16x32_bf16 v[72:75], v[226:229], v[182:185], v[72:75]
	v_mfma_f32_16x16x32_bf16 v[68:71], v[218:221], v[210:213], v[68:71]
	v_mfma_f32_16x16x32_bf16 v[64:67], v[226:229], v[210:213], v[64:67]
	s_barrier
	s_add_i32 s6, s6, s57
	v_lshl_add_u64 v[230:231], s[48:49], 0, v[140:141]
	s_mov_b32 m0, s6
	s_nop 0
	global_load_lds_dwordx4 v[230:231], off
	v_lshl_add_u64 v[232:233], s[48:49], 0, v[150:151]
	s_add_i32 m0, s6, 0x2000
	s_nop 0
	global_load_lds_dwordx4 v[232:233], off
	s_mov_b32 m0, s58
	v_lshl_add_u64 v[234:235], s[52:53], 0, v[154:155]
	ds_read_b128 v[162:165], v208 offset:16384
	ds_read_b128 v[166:169], v208 offset:17408
	ds_read_b128 v[170:173], v208 offset:18432
	ds_read_b128 v[174:177], v208 offset:19456
	ds_read_b128 v[178:181], v208 offset:20480
	ds_read_b128 v[182:185], v208 offset:21504
	ds_read_b128 v[194:197], v208 offset:22528
	ds_read_b128 v[210:213], v208 offset:23552
	global_load_lds_dwordx4 v[234:235], off
	v_lshl_add_u64 v[236:237], s[52:53], 0, v[152:153]
	s_mov_b32 m0, s59
	s_nop 0
	global_load_lds_dwordx4 v[236:237], off
	s_add_u32 s50, s48, 0xb0000
	s_addc_u32 s51, s49, 0
	s_add_i32 s6, s19, s57
	v_lshl_add_u64 v[250:251], s[50:51], 0, v[140:141]
	s_mov_b32 m0, s6
	s_nop 0
	global_load_lds_dwordx4 v[250:251], off
	v_lshl_add_u64 v[250:251], s[50:51], 0, v[150:151]
	s_add_i32 m0, s6, 0x2000
	s_nop 0
	global_load_lds_dwordx4 v[250:251], off
	s_waitcnt vmcnt(8)
	s_waitcnt lgkmcnt(0)
	s_barrier
	v_mfma_f32_16x16x32_bf16 v[60:63], v[128:131], v[162:165], v[60:63]
	v_mfma_f32_16x16x32_bf16 v[56:59], v[136:139], v[162:165], v[56:59]
	v_mfma_f32_16x16x32_bf16 v[48:51], v[128:131], v[170:173], v[48:51]
	v_mfma_f32_16x16x32_bf16 v[40:43], v[136:139], v[170:173], v[40:43]
	v_mfma_f32_16x16x32_bf16 v[32:35], v[128:131], v[178:181], v[32:35]
	v_mfma_f32_16x16x32_bf16 v[24:27], v[136:139], v[178:181], v[24:27]
	v_mfma_f32_16x16x32_bf16 v[16:19], v[128:131], v[194:197], v[16:19]
	v_mfma_f32_16x16x32_bf16 v[8:11], v[136:139], v[194:197], v[8:11]
	v_mfma_f32_16x16x32_bf16 v[60:63], v[132:135], v[166:169], v[60:63]
	v_mfma_f32_16x16x32_bf16 v[56:59], v[146:149], v[166:169], v[56:59]
	v_mfma_f32_16x16x32_bf16 v[48:51], v[132:135], v[174:177], v[48:51]
	v_mfma_f32_16x16x32_bf16 v[40:43], v[146:149], v[174:177], v[40:43]
	v_mfma_f32_16x16x32_bf16 v[32:35], v[132:135], v[182:185], v[32:35]
	v_mfma_f32_16x16x32_bf16 v[24:27], v[146:149], v[182:185], v[24:27]
	v_mfma_f32_16x16x32_bf16 v[16:19], v[132:135], v[210:213], v[16:19]
	v_mfma_f32_16x16x32_bf16 v[8:11], v[146:149], v[210:213], v[8:11]
	v_mfma_f32_16x16x32_bf16 v[52:55], v[214:217], v[162:165], v[52:55]
	v_mfma_f32_16x16x32_bf16 v[44:47], v[222:225], v[162:165], v[44:47]
	v_mfma_f32_16x16x32_bf16 v[36:39], v[214:217], v[170:173], v[36:39]
	v_mfma_f32_16x16x32_bf16 v[28:31], v[222:225], v[170:173], v[28:31]
	v_mfma_f32_16x16x32_bf16 v[20:23], v[214:217], v[178:181], v[20:23]
	v_mfma_f32_16x16x32_bf16 v[12:15], v[222:225], v[178:181], v[12:15]
	v_mfma_f32_16x16x32_bf16 v[4:7], v[214:217], v[194:197], v[4:7]
	v_mfma_f32_16x16x32_bf16 v[0:3], v[222:225], v[194:197], v[0:3]
	v_mfma_f32_16x16x32_bf16 v[52:55], v[218:221], v[166:169], v[52:55]
	v_mfma_f32_16x16x32_bf16 v[44:47], v[226:229], v[166:169], v[44:47]
	v_mfma_f32_16x16x32_bf16 v[36:39], v[218:221], v[174:177], v[36:39]
	v_mfma_f32_16x16x32_bf16 v[28:31], v[226:229], v[174:177], v[28:31]
	v_mfma_f32_16x16x32_bf16 v[20:23], v[218:221], v[182:185], v[20:23]
	v_mfma_f32_16x16x32_bf16 v[12:15], v[226:229], v[182:185], v[12:15]
	v_mfma_f32_16x16x32_bf16 v[4:7], v[218:221], v[210:213], v[4:7]
	v_mfma_f32_16x16x32_bf16 v[0:3], v[226:229], v[210:213], v[0:3]
	s_barrier
	s_add_i32 s6, 0, 0x18000
	v_add_u32_e32 v146, s6, v206
	ds_read_b128 v[128:131], v146
	ds_read_b128 v[132:135], v146 offset:1024
	ds_read_b128 v[136:139], v146 offset:2048
	ds_read_b128 v[146:149], v146 offset:3072
	s_add_u32 s50, s52, 0xb0000
	s_addc_u32 s51, s53, 0
	s_mov_b32 m0, s68
	v_lshl_add_u64 v[214:215], s[50:51], 0, v[154:155]
	ds_read_b128 v[162:165], v208 offset:32768
	ds_read_b128 v[166:169], v208 offset:33792
	ds_read_b128 v[170:173], v208 offset:34816
	ds_read_b128 v[174:177], v208 offset:35840
	ds_read_b128 v[178:181], v208 offset:36864
	ds_read_b128 v[182:185], v208 offset:37888
	ds_read_b128 v[194:197], v208 offset:38912
	ds_read_b128 v[210:213], v208 offset:39936
	global_load_lds_dwordx4 v[214:215], off
	v_lshl_add_u64 v[214:215], s[50:51], 0, v[152:153]
	s_mov_b32 m0, s69
	s_nop 0
	global_load_lds_dwordx4 v[214:215], off
	s_add_i32 s19, 0, 0x1c000
	v_add_u32_e32 v192, s19, v206
	ds_read_b128 v[214:217], v192
	ds_read_b128 v[218:221], v192 offset:1024
	ds_read_b128 v[222:225], v192 offset:2048
	ds_read_b128 v[226:229], v192 offset:3072
	s_waitcnt vmcnt(8)
	s_waitcnt lgkmcnt(0)
	s_barrier
	v_mfma_f32_16x16x32_bf16 v[124:127], v[128:131], v[162:165], v[124:127]
	v_mfma_f32_16x16x32_bf16 v[120:123], v[136:139], v[162:165], v[120:123]
	v_mfma_f32_16x16x32_bf16 v[108:111], v[128:131], v[170:173], v[108:111]
	v_mfma_f32_16x16x32_bf16 v[104:107], v[136:139], v[170:173], v[104:107]
	v_mfma_f32_16x16x32_bf16 v[96:99], v[128:131], v[178:181], v[96:99]
	v_mfma_f32_16x16x32_bf16 v[88:91], v[136:139], v[178:181], v[88:91]
	v_mfma_f32_16x16x32_bf16 v[84:87], v[128:131], v[194:197], v[84:87]
	v_mfma_f32_16x16x32_bf16 v[80:83], v[136:139], v[194:197], v[80:83]
	v_mfma_f32_16x16x32_bf16 v[124:127], v[132:135], v[166:169], v[124:127]
	v_mfma_f32_16x16x32_bf16 v[120:123], v[146:149], v[166:169], v[120:123]
	v_mfma_f32_16x16x32_bf16 v[108:111], v[132:135], v[174:177], v[108:111]
	v_mfma_f32_16x16x32_bf16 v[104:107], v[146:149], v[174:177], v[104:107]
	v_mfma_f32_16x16x32_bf16 v[96:99], v[132:135], v[182:185], v[96:99]
	v_mfma_f32_16x16x32_bf16 v[88:91], v[146:149], v[182:185], v[88:91]
	v_mfma_f32_16x16x32_bf16 v[84:87], v[132:135], v[210:213], v[84:87]
	v_mfma_f32_16x16x32_bf16 v[80:83], v[146:149], v[210:213], v[80:83]
	v_mfma_f32_16x16x32_bf16 v[116:119], v[214:217], v[162:165], v[116:119]
	v_mfma_f32_16x16x32_bf16 v[112:115], v[222:225], v[162:165], v[112:115]
	v_mfma_f32_16x16x32_bf16 v[100:103], v[214:217], v[170:173], v[100:103]
	v_mfma_f32_16x16x32_bf16 v[92:95], v[222:225], v[170:173], v[92:95]
	v_mfma_f32_16x16x32_bf16 v[76:79], v[214:217], v[178:181], v[76:79]
	v_mfma_f32_16x16x32_bf16 v[72:75], v[222:225], v[178:181], v[72:75]
	v_mfma_f32_16x16x32_bf16 v[68:71], v[214:217], v[194:197], v[68:71]
	v_mfma_f32_16x16x32_bf16 v[64:67], v[222:225], v[194:197], v[64:67]
	v_mfma_f32_16x16x32_bf16 v[116:119], v[218:221], v[166:169], v[116:119]
	v_mfma_f32_16x16x32_bf16 v[112:115], v[226:229], v[166:169], v[112:115]
	v_mfma_f32_16x16x32_bf16 v[100:103], v[218:221], v[174:177], v[100:103]
	v_mfma_f32_16x16x32_bf16 v[92:95], v[226:229], v[174:177], v[92:95]
	v_mfma_f32_16x16x32_bf16 v[76:79], v[218:221], v[182:185], v[76:79]
	v_mfma_f32_16x16x32_bf16 v[72:75], v[226:229], v[182:185], v[72:75]
	v_mfma_f32_16x16x32_bf16 v[68:71], v[218:221], v[210:213], v[68:71]
	v_mfma_f32_16x16x32_bf16 v[64:67], v[226:229], v[210:213], v[64:67]
	s_barrier
	s_add_i32 s6, s6, s57
	v_lshl_add_u64 v[230:231], v[230:231], 0, s[36:37]
	s_mov_b32 m0, s6
	s_nop 0
	global_load_lds_dwordx4 v[230:231], off
	v_lshl_add_u64 v[230:231], v[232:233], 0, s[36:37]
	s_add_i32 m0, s6, 0x2000
	s_nop 0
	global_load_lds_dwordx4 v[230:231], off
	s_mov_b32 m0, s70
	v_lshl_add_u64 v[230:231], v[234:235], 0, s[36:37]
	ds_read_b128 v[162:165], v208 offset:49152
	ds_read_b128 v[166:169], v208 offset:50176
	ds_read_b128 v[170:173], v208 offset:51200
	ds_read_b128 v[174:177], v208 offset:52224
	ds_read_b128 v[178:181], v208 offset:53248
	ds_read_b128 v[182:185], v208 offset:54272
	ds_read_b128 v[194:197], v208 offset:55296
	ds_read_b128 v[210:213], v208 offset:56320
	global_load_lds_dwordx4 v[230:231], off
	v_lshl_add_u64 v[230:231], v[236:237], 0, s[36:37]
	s_mov_b32 m0, s71
	s_nop 0
	global_load_lds_dwordx4 v[230:231], off
	s_add_u32 s48, s48, 0xb0080
	s_addc_u32 s49, s49, 0
	s_add_i32 s6, s19, s57
	v_lshl_add_u64 v[250:251], s[48:49], 0, v[140:141]
	s_mov_b32 m0, s6
	s_nop 0
	global_load_lds_dwordx4 v[250:251], off
	v_lshl_add_u64 v[250:251], s[48:49], 0, v[150:151]
	s_add_i32 m0, s6, 0x2000
	s_nop 0
	global_load_lds_dwordx4 v[250:251], off
	s_add_i32 s12, s12, 2
	s_add_u32 s10, s10, 0x100
	s_addc_u32 s11, s11, 0
	s_cmp_gt_u32 s12, 41
	s_mov_b64 s[50:51], s[46:47]
	s_waitcnt vmcnt(8)
	s_waitcnt lgkmcnt(0)
	s_barrier
	v_mfma_f32_16x16x32_bf16 v[60:63], v[128:131], v[162:165], v[60:63]
	v_mfma_f32_16x16x32_bf16 v[56:59], v[136:139], v[162:165], v[56:59]
	v_mfma_f32_16x16x32_bf16 v[48:51], v[128:131], v[170:173], v[48:51]
	v_mfma_f32_16x16x32_bf16 v[40:43], v[136:139], v[170:173], v[40:43]
	v_mfma_f32_16x16x32_bf16 v[32:35], v[128:131], v[178:181], v[32:35]
	v_mfma_f32_16x16x32_bf16 v[24:27], v[136:139], v[178:181], v[24:27]
	v_mfma_f32_16x16x32_bf16 v[16:19], v[128:131], v[194:197], v[16:19]
	v_mfma_f32_16x16x32_bf16 v[8:11], v[136:139], v[194:197], v[8:11]
	v_mfma_f32_16x16x32_bf16 v[60:63], v[132:135], v[166:169], v[60:63]
	v_mfma_f32_16x16x32_bf16 v[56:59], v[146:149], v[166:169], v[56:59]
	v_mfma_f32_16x16x32_bf16 v[48:51], v[132:135], v[174:177], v[48:51]
	v_mfma_f32_16x16x32_bf16 v[40:43], v[146:149], v[174:177], v[40:43]
	v_mfma_f32_16x16x32_bf16 v[32:35], v[132:135], v[182:185], v[32:35]
	v_mfma_f32_16x16x32_bf16 v[24:27], v[146:149], v[182:185], v[24:27]
	v_mfma_f32_16x16x32_bf16 v[16:19], v[132:135], v[210:213], v[16:19]
	v_mfma_f32_16x16x32_bf16 v[8:11], v[146:149], v[210:213], v[8:11]
	v_mfma_f32_16x16x32_bf16 v[52:55], v[214:217], v[162:165], v[52:55]
	v_mfma_f32_16x16x32_bf16 v[44:47], v[222:225], v[162:165], v[44:47]
	v_mfma_f32_16x16x32_bf16 v[36:39], v[214:217], v[170:173], v[36:39]
	v_mfma_f32_16x16x32_bf16 v[28:31], v[222:225], v[170:173], v[28:31]
	v_mfma_f32_16x16x32_bf16 v[20:23], v[214:217], v[178:181], v[20:23]
	v_mfma_f32_16x16x32_bf16 v[12:15], v[222:225], v[178:181], v[12:15]
	v_mfma_f32_16x16x32_bf16 v[4:7], v[214:217], v[194:197], v[4:7]
	v_mfma_f32_16x16x32_bf16 v[0:3], v[222:225], v[194:197], v[0:3]
	v_mfma_f32_16x16x32_bf16 v[52:55], v[218:221], v[166:169], v[52:55]
	v_mfma_f32_16x16x32_bf16 v[44:47], v[226:229], v[166:169], v[44:47]
	v_mfma_f32_16x16x32_bf16 v[36:39], v[218:221], v[174:177], v[36:39]
	v_mfma_f32_16x16x32_bf16 v[28:31], v[226:229], v[174:177], v[28:31]
	v_mfma_f32_16x16x32_bf16 v[20:23], v[218:221], v[182:185], v[20:23]
	v_mfma_f32_16x16x32_bf16 v[12:15], v[226:229], v[182:185], v[12:15]
	v_mfma_f32_16x16x32_bf16 v[4:7], v[218:221], v[210:213], v[4:7]
	v_mfma_f32_16x16x32_bf16 v[0:3], v[226:229], v[210:213], v[0:3]
	s_barrier
	s_cbranch_scc0 .LBB0_31
	s_mov_b32 s100, 1
	s_ashr_i32 s39, s38, 31
	v_lshl_or_b32 v128, s81, 8, v207
	s_lshl_b64 s[10:11], s[38:39], 8
	v_ashrrev_i32_e32 v129, 31, v128
	v_lshl_add_u64 v[168:169], s[10:11], 0, v[156:157]
	v_lshlrev_b64 v[170:171], 1, v[128:129]
	v_lshl_add_u64 v[174:175], s[4:5], 0, v[170:171]
	v_lshlrev_b64 v[172:173], 11, v[168:169]
	v_lshl_add_u64 v[128:129], v[174:175], 0, v[172:173]
	global_load_dwordx4 v[146:149], v[128:129], off
	global_load_dwordx4 v[182:185], v[128:129], off offset:256
	v_or_b32_e32 v166, 16, v168
	v_mov_b32_e32 v167, v169
	v_lshlrev_b64 v[176:177], 11, v[166:167]
	v_lshl_add_u64 v[128:129], v[174:175], 0, v[176:177]
	global_load_dwordx4 v[194:197], v[128:129], off
	global_load_dwordx4 v[210:213], v[128:129], off offset:256
	v_or_b32_e32 v164, 32, v168
	v_mov_b32_e32 v165, v169
	v_or_b32_e32 v162, 48, v168
	v_mov_b32_e32 v163, v169
	v_lshlrev_b64 v[180:181], 11, v[164:165]
	v_lshlrev_b64 v[178:179], 11, v[162:163]
	v_lshl_add_u64 v[128:129], v[174:175], 0, v[180:181]
	v_lshl_add_u64 v[130:131], v[174:175], 0, v[178:179]
	global_load_dwordx4 v[214:217], v[128:129], off
	global_load_dwordx4 v[136:139], v[128:129], off offset:256
	global_load_dwordx4 v[132:135], v[130:131], off
	s_nop 0
	global_load_dwordx4 v[128:131], v[130:131], off offset:256
	s_mov_b64 s[10:11], 0x90
	v_lshl_add_u64 v[172:173], s[28:29], 0, v[172:173]
	v_lshl_add_u64 v[172:173], v[172:173], 0, v[170:171]
	s_waitcnt vmcnt(0)
	v_lshlrev_b32_e32 v218, 16, v146
	v_and_b32_e32 v219, 0xffff0000, v146
	v_lshlrev_b32_e32 v220, 16, v148
	v_and_b32_e32 v221, 0xffff0000, v148
	v_lshlrev_b32_e32 v146, 16, v147
	v_and_b32_e32 v147, 0xffff0000, v147
	v_lshlrev_b32_e32 v222, 16, v182
	v_and_b32_e32 v223, 0xffff0000, v182
	v_lshlrev_b32_e32 v224, 16, v184
	v_and_b32_e32 v225, 0xffff0000, v184
	v_lshlrev_b32_e32 v182, 16, v183
	v_and_b32_e32 v183, 0xffff0000, v183
	v_pk_fma_f32 v[124:125], v[124:125], 0.5, v[218:219] op_sel_hi:[1,0,1]
	v_pk_fma_f32 v[120:121], v[120:121], 0.5, v[220:221] op_sel_hi:[1,0,1]
	v_pk_fma_f32 v[126:127], v[126:127], 0.5, v[146:147] op_sel_hi:[1,0,1]
	v_pk_fma_f32 v[116:117], v[116:117], 0.5, v[222:223] op_sel_hi:[1,0,1]
	v_pk_fma_f32 v[146:147], v[112:113], 0.5, v[224:225] op_sel_hi:[1,0,1]
	v_pk_fma_f32 v[118:119], v[118:119], 0.5, v[182:183] op_sel_hi:[1,0,1]
	v_pk_mul_f32 v[220:221], v[124:125], v[124:125]
	v_pk_mul_f32 v[222:223], v[126:127], v[126:127]
	v_cvt_pk_bf16_f32 v112, v124, v125
	v_cvt_pk_bf16_f32 v113, v126, v127
	v_pk_mul_f32 v[124:125], v[116:117], v[116:117]
	v_pk_mul_f32 v[126:127], v[118:119], v[118:119]
	v_pk_mul_f32 v[228:229], v[146:147], v[146:147]
	v_cvt_pk_bf16_f32 v116, v116, v117
	v_cvt_pk_bf16_f32 v117, v118, v119
	v_cvt_pk_bf16_f32 v118, v146, v147
	v_add_f32_e32 v146, v220, v221
	v_add_f32_e32 v146, v222, v146
	v_lshlrev_b32_e32 v148, 16, v149
	v_and_b32_e32 v149, 0xffff0000, v149
	v_pk_mul_f32 v[224:225], v[120:121], v[120:121]
	v_add_f32_e32 v146, v223, v146
	v_pk_fma_f32 v[122:123], v[122:123], 0.5, v[148:149] op_sel_hi:[1,0,1]
	v_add_f32_e32 v146, v224, v146
	v_pk_mul_f32 v[226:227], v[122:123], v[122:123]
	v_add_f32_e32 v146, v225, v146
	v_add_f32_e32 v146, v226, v146
	v_add_f32_e32 v146, v227, v146
	v_add_f32_e32 v124, v124, v146
	v_add_f32_e32 v124, v125, v124
	v_add_f32_e32 v124, v126, v124
	v_lshlrev_b32_e32 v184, 16, v185
	v_and_b32_e32 v185, 0xffff0000, v185
	v_add_f32_e32 v124, v127, v124
	v_pk_fma_f32 v[148:149], v[114:115], 0.5, v[184:185] op_sel_hi:[1,0,1]
	v_add_f32_e32 v124, v228, v124
	v_pk_mul_f32 v[230:231], v[148:149], v[148:149]
	v_add_f32_e32 v124, v229, v124
	v_add_f32_e32 v124, v230, v124
	v_add_f32_e32 v209, v231, v124
	v_lshlrev_b32_e32 v124, 16, v212
	v_and_b32_e32 v125, 0xffff0000, v212
	v_pk_fma_f32 v[124:125], v[92:93], 0.5, v[124:125] op_sel_hi:[1,0,1]
	v_lshlrev_b32_e32 v92, 16, v211
	v_and_b32_e32 v93, 0xffff0000, v211
	v_pk_fma_f32 v[102:103], v[102:103], 0.5, v[92:93] op_sel_hi:[1,0,1]
	v_lshlrev_b32_e32 v92, 16, v213
	v_and_b32_e32 v93, 0xffff0000, v213
	v_pk_fma_f32 v[126:127], v[94:95], 0.5, v[92:93] op_sel_hi:[1,0,1]
	v_lshlrev_b32_e32 v92, 16, v214
	v_and_b32_e32 v93, 0xffff0000, v214
	v_pk_fma_f32 v[92:93], v[96:97], 0.5, v[92:93] op_sel_hi:[1,0,1]
	v_lshlrev_b32_e32 v96, 16, v217
	v_and_b32_e32 v97, 0xffff0000, v217
	v_lshlrev_b32_e32 v94, 16, v216
	v_and_b32_e32 v95, 0xffff0000, v216
	v_pk_fma_f32 v[90:91], v[90:91], 0.5, v[96:97] op_sel_hi:[1,0,1]
	v_lshlrev_b32_e32 v96, 16, v136
	v_and_b32_e32 v97, 0xffff0000, v136
	v_lshlrev_b32_e32 v182, 16, v194
	v_and_b32_e32 v183, 0xffff0000, v194
	v_pk_fma_f32 v[88:89], v[88:89], 0.5, v[94:95] op_sel_hi:[1,0,1]
	v_lshlrev_b32_e32 v94, 16, v215
	v_and_b32_e32 v95, 0xffff0000, v215
	v_pk_fma_f32 v[96:97], v[76:77], 0.5, v[96:97] op_sel_hi:[1,0,1]
	v_lshl_add_u64 v[76:77], v[168:169], 0, s[36:37]
	v_lshlrev_b32_e32 v184, 16, v196
	v_and_b32_e32 v185, 0xffff0000, v196
	v_cvt_pk_bf16_f32 v114, v120, v121
	v_pk_fma_f32 v[120:121], v[108:109], 0.5, v[182:183] op_sel_hi:[1,0,1]
	v_pk_fma_f32 v[94:95], v[98:99], 0.5, v[94:95] op_sel_hi:[1,0,1]
	v_lshlrev_b64 v[182:183], 11, v[76:77]
	v_lshlrev_b32_e32 v98, 16, v138
	v_and_b32_e32 v99, 0xffff0000, v138
	v_pk_fma_f32 v[108:109], v[104:105], 0.5, v[184:185] op_sel_hi:[1,0,1]
	v_lshl_add_u64 v[184:185], v[174:175], 0, v[182:183]
	v_pk_fma_f32 v[98:99], v[72:73], 0.5, v[98:99] op_sel_hi:[1,0,1]
	v_lshlrev_b32_e32 v72, 16, v137
	v_and_b32_e32 v73, 0xffff0000, v137
	v_lshlrev_b32_e32 v218, 16, v210
	v_and_b32_e32 v219, 0xffff0000, v210
	global_load_dwordx4 v[210:213], v[184:185], off
	v_pk_fma_f32 v[136:137], v[78:79], 0.5, v[72:73] op_sel_hi:[1,0,1]
	v_lshlrev_b32_e32 v72, 16, v139
	v_and_b32_e32 v73, 0xffff0000, v139
	v_pk_fma_f32 v[138:139], v[74:75], 0.5, v[72:73] op_sel_hi:[1,0,1]
	v_lshlrev_b32_e32 v72, 16, v132
	v_and_b32_e32 v73, 0xffff0000, v132
	v_pk_fma_f32 v[74:75], v[84:85], 0.5, v[72:73] op_sel_hi:[1,0,1]
	v_lshlrev_b32_e32 v72, 16, v134
	v_and_b32_e32 v73, 0xffff0000, v134
	v_pk_fma_f32 v[78:79], v[80:81], 0.5, v[72:73] op_sel_hi:[1,0,1]
	v_lshlrev_b32_e32 v72, 16, v133
	v_and_b32_e32 v73, 0xffff0000, v133
	v_pk_fma_f32 v[100:101], v[100:101], 0.5, v[218:219] op_sel_hi:[1,0,1]
	global_load_dwordx4 v[218:221], v[184:185], off offset:256
	v_pk_fma_f32 v[80:81], v[86:87], 0.5, v[72:73] op_sel_hi:[1,0,1]
	v_lshlrev_b32_e32 v72, 16, v135
	v_and_b32_e32 v73, 0xffff0000, v135
	v_pk_fma_f32 v[82:83], v[82:83], 0.5, v[72:73] op_sel_hi:[1,0,1]
	v_lshl_add_u64 v[72:73], v[168:169], 0, s[10:11]
	v_lshlrev_b64 v[132:133], 11, v[72:73]
	v_lshl_add_u64 v[134:135], v[174:175], 0, v[132:133]
	v_lshlrev_b32_e32 v84, 16, v128
	v_and_b32_e32 v85, 0xffff0000, v128
	global_load_dwordx4 v[226:229], v[134:135], off
	global_load_dwordx4 v[234:237], v[134:135], off offset:256
	v_pk_fma_f32 v[84:85], v[68:69], 0.5, v[84:85] op_sel_hi:[1,0,1]
	v_lshlrev_b32_e32 v68, 16, v130
	v_and_b32_e32 v69, 0xffff0000, v130
	v_pk_fma_f32 v[86:87], v[64:65], 0.5, v[68:69] op_sel_hi:[1,0,1]
	v_lshlrev_b32_e32 v64, 16, v129
	v_and_b32_e32 v65, 0xffff0000, v129
	s_mov_b64 s[10:11], 0xa0
	v_pk_fma_f32 v[128:129], v[70:71], 0.5, v[64:65] op_sel_hi:[1,0,1]
	v_lshl_add_u64 v[70:71], v[168:169], 0, s[10:11]
	s_mov_b64 s[10:11], 0xb0
	v_lshlrev_b32_e32 v64, 16, v131
	v_and_b32_e32 v65, 0xffff0000, v131
	v_lshlrev_b64 v[134:135], 11, v[70:71]
	v_lshl_add_u64 v[68:69], v[168:169], 0, s[10:11]
	v_pk_fma_f32 v[130:131], v[66:67], 0.5, v[64:65] op_sel_hi:[1,0,1]
	v_lshl_add_u64 v[64:65], v[174:175], 0, v[134:135]
	v_lshlrev_b64 v[184:185], 11, v[68:69]
	global_load_dwordx4 v[238:241], v[64:65], off
	global_load_dwordx4 v[242:245], v[64:65], off offset:256
	v_lshl_add_u64 v[64:65], v[174:175], 0, v[184:185]
	global_load_dwordx4 v[246:249], v[64:65], off
	s_nop 0
	global_load_dwordx4 v[64:67], v[64:65], off offset:256
	v_lshlrev_b32_e32 v194, 16, v195
	v_and_b32_e32 v195, 0xffff0000, v195
	v_lshlrev_b32_e32 v196, 16, v197
	v_and_b32_e32 v197, 0xffff0000, v197
	v_cvt_pk_bf16_f32 v115, v122, v123
	v_cvt_pk_bf16_f32 v119, v148, v149
	v_pk_fma_f32 v[122:123], v[110:111], 0.5, v[194:195] op_sel_hi:[1,0,1]
	v_pk_fma_f32 v[110:111], v[106:107], 0.5, v[196:197] op_sel_hi:[1,0,1]
	global_store_dwordx4 v[172:173], v[112:115], off
	global_store_dwordx4 v[172:173], v[116:119], off offset:256
	v_cvt_pk_bf16_f32 v104, v120, v121
	v_lshl_add_u64 v[112:113], s[28:29], 0, v[176:177]
	v_cvt_pk_bf16_f32 v105, v122, v123
	v_cvt_pk_bf16_f32 v106, v108, v109
	v_cvt_pk_bf16_f32 v107, v110, v111
	v_lshl_add_u64 v[112:113], v[112:113], 0, v[170:171]
	v_cvt_pk_bf16_f32 v146, v100, v101
	v_cvt_pk_bf16_f32 v147, v102, v103
	v_cvt_pk_bf16_f32 v148, v124, v125
	v_cvt_pk_bf16_f32 v149, v126, v127
	global_store_dwordx4 v[112:113], v[104:107], off
	global_store_dwordx4 v[112:113], v[146:149], off offset:256
	v_cvt_pk_bf16_f32 v194, v92, v93
	v_lshl_add_u64 v[104:105], s[28:29], 0, v[180:181]
	v_cvt_pk_bf16_f32 v195, v94, v95
	v_cvt_pk_bf16_f32 v196, v88, v89
	v_cvt_pk_bf16_f32 v197, v90, v91
	v_lshl_add_u64 v[104:105], v[104:105], 0, v[170:171]
	v_cvt_pk_bf16_f32 v214, v96, v97
	v_cvt_pk_bf16_f32 v215, v136, v137
	v_cvt_pk_bf16_f32 v216, v98, v99
	v_cvt_pk_bf16_f32 v217, v138, v139
	global_store_dwordx4 v[104:105], v[194:197], off
	global_store_dwordx4 v[104:105], v[214:217], off offset:256
	v_lshl_add_u64 v[104:105], s[28:29], 0, v[178:179]
	v_cvt_pk_bf16_f32 v222, v74, v75
	v_cvt_pk_bf16_f32 v223, v80, v81
	v_cvt_pk_bf16_f32 v224, v78, v79
	v_cvt_pk_bf16_f32 v225, v82, v83
	v_lshl_add_u64 v[104:105], v[104:105], 0, v[170:171]
	v_cvt_pk_bf16_f32 v230, v84, v85
	v_cvt_pk_bf16_f32 v231, v128, v129
	v_cvt_pk_bf16_f32 v232, v86, v87
	v_cvt_pk_bf16_f32 v233, v130, v131
	global_store_dwordx4 v[104:105], v[222:225], off
	global_store_dwordx4 v[104:105], v[230:233], off offset:256
	s_waitcnt vmcnt(8)
	v_lshlrev_b32_e32 v104, 16, v210
	v_and_b32_e32 v105, 0xffff0000, v210
	v_pk_fma_f32 v[60:61], v[60:61], 0.5, v[104:105] op_sel_hi:[1,0,1]
	v_lshlrev_b32_e32 v104, 16, v212
	v_and_b32_e32 v105, 0xffff0000, v212
	v_pk_fma_f32 v[56:57], v[56:57], 0.5, v[104:105] op_sel_hi:[1,0,1]
	v_lshlrev_b32_e32 v104, 16, v211
	v_and_b32_e32 v105, 0xffff0000, v211
	v_pk_fma_f32 v[62:63], v[62:63], 0.5, v[104:105] op_sel_hi:[1,0,1]
	v_lshlrev_b32_e32 v104, 16, v213
	v_and_b32_e32 v105, 0xffff0000, v213
	v_pk_fma_f32 v[58:59], v[58:59], 0.5, v[104:105] op_sel_hi:[1,0,1]
	v_lshlrev_b32_e32 v104, 16, v218
	v_and_b32_e32 v105, 0xffff0000, v218
	v_pk_fma_f32 v[52:53], v[52:53], 0.5, v[104:105] op_sel_hi:[1,0,1]
	v_lshlrev_b32_e32 v104, 16, v220
	v_and_b32_e32 v105, 0xffff0000, v220
	v_pk_fma_f32 v[104:105], v[44:45], 0.5, v[104:105] op_sel_hi:[1,0,1]
	v_lshlrev_b32_e32 v44, 16, v219
	v_and_b32_e32 v45, 0xffff0000, v219
	v_pk_fma_f32 v[54:55], v[54:55], 0.5, v[44:45] op_sel_hi:[1,0,1]
	v_lshlrev_b32_e32 v44, 16, v221
	v_and_b32_e32 v45, 0xffff0000, v221
	v_pk_fma_f32 v[106:107], v[46:47], 0.5, v[44:45] op_sel_hi:[1,0,1]
	v_lshlrev_b32_e32 v44, 16, v226
	v_and_b32_e32 v45, 0xffff0000, v226
	v_pk_fma_f32 v[44:45], v[48:49], 0.5, v[44:45] op_sel_hi:[1,0,1]
	v_lshlrev_b32_e32 v48, 16, v229
	v_and_b32_e32 v49, 0xffff0000, v229
	v_pk_fma_f32 v[42:43], v[42:43], 0.5, v[48:49] op_sel_hi:[1,0,1]
	v_lshlrev_b32_e32 v48, 16, v234
	v_and_b32_e32 v49, 0xffff0000, v234
	v_pk_fma_f32 v[36:37], v[36:37], 0.5, v[48:49] op_sel_hi:[1,0,1]
	v_lshlrev_b32_e32 v48, 16, v236
	v_and_b32_e32 v49, 0xffff0000, v236
	v_lshlrev_b32_e32 v46, 16, v228
	v_and_b32_e32 v47, 0xffff0000, v228
	v_pk_fma_f32 v[48:49], v[28:29], 0.5, v[48:49] op_sel_hi:[1,0,1]
	v_lshlrev_b32_e32 v28, 16, v235
	v_and_b32_e32 v29, 0xffff0000, v235
	v_pk_fma_f32 v[40:41], v[40:41], 0.5, v[46:47] op_sel_hi:[1,0,1]
	v_lshlrev_b32_e32 v46, 16, v227
	v_and_b32_e32 v47, 0xffff0000, v227
	v_pk_fma_f32 v[38:39], v[38:39], 0.5, v[28:29] op_sel_hi:[1,0,1]
	v_lshlrev_b32_e32 v28, 16, v237
	v_and_b32_e32 v29, 0xffff0000, v237
	v_pk_fma_f32 v[46:47], v[50:51], 0.5, v[46:47] op_sel_hi:[1,0,1]
	v_pk_fma_f32 v[50:51], v[30:31], 0.5, v[28:29] op_sel_hi:[1,0,1]
	v_lshlrev_b32_e32 v28, 16, v238
	v_and_b32_e32 v29, 0xffff0000, v238
	v_lshlrev_b32_e32 v180, 16, v64
	v_and_b32_e32 v181, 0xffff0000, v64
	v_pk_fma_f32 v[28:29], v[32:33], 0.5, v[28:29] op_sel_hi:[1,0,1]
	v_lshlrev_b32_e32 v32, 16, v241
	v_and_b32_e32 v33, 0xffff0000, v241
	v_pk_fma_f32 v[4:5], v[4:5], 0.5, v[180:181] op_sel_hi:[1,0,1]
	v_lshlrev_b32_e32 v180, 16, v66
	v_and_b32_e32 v181, 0xffff0000, v66
	v_pk_fma_f32 v[26:27], v[26:27], 0.5, v[32:33] op_sel_hi:[1,0,1]
	v_lshlrev_b32_e32 v32, 16, v242
	v_and_b32_e32 v33, 0xffff0000, v242
	v_pk_fma_f32 v[0:1], v[0:1], 0.5, v[180:181] op_sel_hi:[1,0,1]
	v_lshl_add_u64 v[180:181], s[28:29], 0, v[182:183]
	v_cvt_pk_bf16_f32 v112, v60, v61
	v_cvt_pk_bf16_f32 v113, v62, v63
	v_cvt_pk_bf16_f32 v114, v56, v57
	v_cvt_pk_bf16_f32 v115, v58, v59
	v_pk_fma_f32 v[20:21], v[20:21], 0.5, v[32:33] op_sel_hi:[1,0,1]
	v_lshlrev_b32_e32 v32, 16, v244
	v_and_b32_e32 v33, 0xffff0000, v244
	v_lshl_add_u64 v[180:181], v[180:181], 0, v[170:171]
	v_cvt_pk_bf16_f32 v116, v52, v53
	v_cvt_pk_bf16_f32 v117, v54, v55
	v_cvt_pk_bf16_f32 v118, v104, v105
	v_cvt_pk_bf16_f32 v119, v106, v107
	v_lshlrev_b32_e32 v30, 16, v240
	v_and_b32_e32 v31, 0xffff0000, v240
	v_pk_fma_f32 v[32:33], v[12:13], 0.5, v[32:33] op_sel_hi:[1,0,1]
	v_lshlrev_b32_e32 v12, 16, v243
	v_and_b32_e32 v13, 0xffff0000, v243
	global_store_dwordx4 v[180:181], v[112:115], off
	global_store_dwordx4 v[180:181], v[116:119], off offset:256
	v_cvt_pk_bf16_f32 v146, v44, v45
	v_lshl_add_u64 v[112:113], s[28:29], 0, v[132:133]
	v_cvt_pk_bf16_f32 v147, v46, v47
	v_cvt_pk_bf16_f32 v148, v40, v41
	v_cvt_pk_bf16_f32 v149, v42, v43
	v_pk_fma_f32 v[24:25], v[24:25], 0.5, v[30:31] op_sel_hi:[1,0,1]
	v_lshlrev_b32_e32 v30, 16, v239
	v_and_b32_e32 v31, 0xffff0000, v239
	v_pk_fma_f32 v[22:23], v[22:23], 0.5, v[12:13] op_sel_hi:[1,0,1]
	v_lshlrev_b32_e32 v12, 16, v245
	v_and_b32_e32 v13, 0xffff0000, v245
	v_lshl_add_u64 v[112:113], v[112:113], 0, v[170:171]
	v_cvt_pk_bf16_f32 v172, v36, v37
	v_cvt_pk_bf16_f32 v173, v38, v39
	v_cvt_pk_bf16_f32 v174, v48, v49
	v_cvt_pk_bf16_f32 v175, v50, v51
	v_pk_fma_f32 v[30:31], v[34:35], 0.5, v[30:31] op_sel_hi:[1,0,1]
	v_pk_fma_f32 v[34:35], v[14:15], 0.5, v[12:13] op_sel_hi:[1,0,1]
	v_lshlrev_b32_e32 v12, 16, v246
	v_and_b32_e32 v13, 0xffff0000, v246
	v_lshlrev_b32_e32 v14, 16, v248
	v_and_b32_e32 v15, 0xffff0000, v248
	global_store_dwordx4 v[112:113], v[146:149], off
	global_store_dwordx4 v[112:113], v[172:175], off offset:256
	v_lshl_add_u64 v[112:113], s[28:29], 0, v[134:135]
	v_cvt_pk_bf16_f32 v176, v28, v29
	v_cvt_pk_bf16_f32 v177, v30, v31
	v_cvt_pk_bf16_f32 v178, v24, v25
	v_cvt_pk_bf16_f32 v179, v26, v27
	v_pk_fma_f32 v[12:13], v[16:17], 0.5, v[12:13] op_sel_hi:[1,0,1]
	v_pk_fma_f32 v[8:9], v[8:9], 0.5, v[14:15] op_sel_hi:[1,0,1]
	v_lshlrev_b32_e32 v14, 16, v247
	v_and_b32_e32 v15, 0xffff0000, v247
	v_lshlrev_b32_e32 v16, 16, v249
	v_and_b32_e32 v17, 0xffff0000, v249
	v_lshlrev_b32_e32 v64, 16, v65
	v_and_b32_e32 v65, 0xffff0000, v65
	v_lshl_add_u64 v[112:113], v[112:113], 0, v[170:171]
	v_cvt_pk_bf16_f32 v194, v20, v21
	v_cvt_pk_bf16_f32 v195, v22, v23
	v_cvt_pk_bf16_f32 v196, v32, v33
	v_cvt_pk_bf16_f32 v197, v34, v35
	v_pk_fma_f32 v[14:15], v[18:19], 0.5, v[14:15] op_sel_hi:[1,0,1]
	v_pk_fma_f32 v[10:11], v[10:11], 0.5, v[16:17] op_sel_hi:[1,0,1]
	v_pk_fma_f32 v[6:7], v[6:7], 0.5, v[64:65] op_sel_hi:[1,0,1]
	v_lshlrev_b32_e32 v64, 16, v67
	v_and_b32_e32 v65, 0xffff0000, v67
	global_store_dwordx4 v[112:113], v[176:179], off
	global_store_dwordx4 v[112:113], v[194:197], off offset:256
	v_lshl_add_u64 v[112:113], s[28:29], 0, v[184:185]
	v_cvt_pk_bf16_f32 v16, v12, v13
	v_cvt_pk_bf16_f32 v17, v14, v15
	v_cvt_pk_bf16_f32 v18, v8, v9
	v_cvt_pk_bf16_f32 v19, v10, v11
	v_pk_fma_f32 v[2:3], v[2:3], 0.5, v[64:65] op_sel_hi:[1,0,1]
	v_lshl_add_u64 v[112:113], v[112:113], 0, v[170:171]
	v_cvt_pk_bf16_f32 v64, v4, v5
	v_cvt_pk_bf16_f32 v65, v6, v7
	v_cvt_pk_bf16_f32 v66, v0, v1
	v_cvt_pk_bf16_f32 v67, v2, v3
	global_store_dwordx4 v[112:113], v[16:19], off
	global_store_dwordx4 v[112:113], v[64:67], off offset:256
	s_lshl_b32 s10, s81, 2
	v_and_b32_e32 v17, 64, v188
	v_xor_b32_e32 v16, 16, v188
	v_add_u32_e32 v17, 64, v17
	v_cmp_lt_i32_e32 vcc, v16, v17
	v_xor_b32_e32 v18, 32, v188
	s_ashr_i32 s11, s10, 31
	v_cndmask_b32_e32 v16, v188, v16, vcc
	v_lshlrev_b32_e32 v16, 2, v16
	v_mov_b32_e32 v132, v209
	v_cmp_lt_i32_e32 vcc, v18, v17
	s_lshl_b64 s[10:11], s[10:11], 2
	s_add_u32 s38, s73, s10
	v_cndmask_b32_e32 v17, v188, v18, vcc
	v_lshlrev_b32_e32 v17, 2, v17
	s_addc_u32 s39, s74, s11
	v_pk_mul_f32 v[18:19], v[120:121], v[120:121]
	v_pk_mul_f32 v[64:65], v[122:123], v[122:123]
	v_add_f32_e32 v18, v18, v19
	v_add_f32_e32 v18, v64, v18
	v_pk_mul_f32 v[66:67], v[108:109], v[108:109]
	v_add_f32_e32 v18, v65, v18
	v_add_f32_e32 v18, v66, v18
	v_pk_mul_f32 v[108:109], v[110:111], v[110:111]
	v_add_f32_e32 v18, v67, v18
	v_add_f32_e32 v18, v108, v18
	v_pk_mul_f32 v[100:101], v[100:101], v[100:101]
	v_add_f32_e32 v18, v109, v18
	v_add_f32_e32 v18, v100, v18
	v_pk_mul_f32 v[102:103], v[102:103], v[102:103]
	v_add_f32_e32 v18, v101, v18
	v_add_f32_e32 v18, v102, v18
	v_pk_mul_f32 v[110:111], v[124:125], v[124:125]
	v_add_f32_e32 v18, v103, v18
	v_add_f32_e32 v18, v110, v18
	v_pk_mul_f32 v[112:113], v[126:127], v[126:127]
	v_add_f32_e32 v18, v111, v18
	v_add_f32_e32 v18, v112, v18
	v_add_f32_e32 v18, v113, v18
	v_mov_b32_e32 v133, v18
	v_pk_mul_f32 v[18:19], v[92:93], v[92:93]
	v_pk_mul_f32 v[64:65], v[94:95], v[94:95]
	v_add_f32_e32 v18, v18, v19
	v_add_f32_e32 v18, v64, v18
	v_pk_mul_f32 v[66:67], v[88:89], v[88:89]
	v_add_f32_e32 v18, v65, v18
	v_add_f32_e32 v18, v66, v18
	v_pk_mul_f32 v[88:89], v[90:91], v[90:91]
	v_add_f32_e32 v18, v67, v18
	v_add_f32_e32 v18, v88, v18
	v_pk_mul_f32 v[90:91], v[96:97], v[96:97]
	v_add_f32_e32 v18, v89, v18
	v_add_f32_e32 v18, v90, v18
	v_pk_mul_f32 v[92:93], v[136:137], v[136:137]
	v_add_f32_e32 v18, v91, v18
	v_add_f32_e32 v18, v92, v18
	v_pk_mul_f32 v[94:95], v[98:99], v[98:99]
	v_add_f32_e32 v18, v93, v18
	v_add_f32_e32 v18, v94, v18
	v_pk_mul_f32 v[96:97], v[138:139], v[138:139]
	v_add_f32_e32 v18, v95, v18
	v_add_f32_e32 v18, v96, v18
	v_add_f32_e32 v18, v97, v18
	v_mov_b32_e32 v134, v18
	v_pk_mul_f32 v[18:19], v[74:75], v[74:75]
	v_pk_mul_f32 v[210:211], v[60:61], v[60:61]
	v_pk_mul_f32 v[64:65], v[80:81], v[80:81]
	v_pk_mul_f32 v[60:61], v[62:63], v[62:63]
	v_add_f32_e32 v18, v18, v19
	v_add_f32_e32 v210, v210, v211
	v_add_f32_e32 v18, v64, v18
	v_add_f32_e32 v210, v60, v210
	v_pk_mul_f32 v[66:67], v[78:79], v[78:79]
	v_pk_mul_f32 v[56:57], v[56:57], v[56:57]
	v_add_f32_e32 v18, v65, v18
	v_add_f32_e32 v210, v61, v210
	v_add_f32_e32 v18, v66, v18
	v_add_f32_e32 v210, v56, v210
	v_pk_mul_f32 v[74:75], v[82:83], v[82:83]
	v_pk_mul_f32 v[58:59], v[58:59], v[58:59]
	v_add_f32_e32 v18, v67, v18
	v_add_f32_e32 v210, v57, v210
	v_add_f32_e32 v18, v74, v18
	v_add_f32_e32 v210, v58, v210
	v_pk_mul_f32 v[78:79], v[84:85], v[84:85]
	v_pk_mul_f32 v[52:53], v[52:53], v[52:53]
	v_add_f32_e32 v18, v75, v18
	v_add_f32_e32 v210, v59, v210
	v_add_f32_e32 v18, v78, v18
	v_add_f32_e32 v210, v52, v210
	v_pk_mul_f32 v[80:81], v[128:129], v[128:129]
	v_pk_mul_f32 v[54:55], v[54:55], v[54:55]
	v_add_f32_e32 v18, v79, v18
	v_add_f32_e32 v210, v53, v210
	v_add_f32_e32 v18, v80, v18
	v_add_f32_e32 v210, v54, v210
	v_pk_mul_f32 v[82:83], v[86:87], v[86:87]
	v_pk_mul_f32 v[62:63], v[104:105], v[104:105]
	v_add_f32_e32 v18, v81, v18
	v_add_f32_e32 v210, v55, v210
	v_add_f32_e32 v18, v82, v18
	v_add_f32_e32 v210, v62, v210
	v_pk_mul_f32 v[84:85], v[130:131], v[130:131]
	v_pk_mul_f32 v[212:213], v[106:107], v[106:107]
	v_add_f32_e32 v18, v83, v18
	v_add_f32_e32 v210, v63, v210
	v_add_f32_e32 v18, v84, v18
	v_add_f32_e32 v210, v212, v210
	v_add_f32_e32 v18, v85, v18
	v_add_f32_e32 v210, v213, v210
	v_mov_b32_e32 v135, v18
	v_mov_b32_e32 v146, v210
	v_pk_mul_f32 v[18:19], v[44:45], v[44:45]
	v_pk_mul_f32 v[210:211], v[28:29], v[28:29]
	v_pk_mul_f32 v[44:45], v[46:47], v[46:47]
	v_pk_mul_f32 v[28:29], v[30:31], v[30:31]
	v_add_f32_e32 v18, v18, v19
	v_add_f32_e32 v210, v210, v211
	v_add_f32_e32 v18, v44, v18
	v_add_f32_e32 v210, v28, v210
	v_pk_mul_f32 v[40:41], v[40:41], v[40:41]
	v_pk_mul_f32 v[24:25], v[24:25], v[24:25]
	v_add_f32_e32 v18, v45, v18
	v_add_f32_e32 v210, v29, v210
	v_add_f32_e32 v18, v40, v18
	v_add_f32_e32 v210, v24, v210
	v_pk_mul_f32 v[42:43], v[42:43], v[42:43]
	v_pk_mul_f32 v[26:27], v[26:27], v[26:27]
	v_add_f32_e32 v18, v41, v18
	v_add_f32_e32 v210, v25, v210
	v_add_f32_e32 v18, v42, v18
	v_add_f32_e32 v210, v26, v210
	v_pk_mul_f32 v[36:37], v[36:37], v[36:37]
	v_pk_mul_f32 v[20:21], v[20:21], v[20:21]
	v_add_f32_e32 v18, v43, v18
	v_add_f32_e32 v210, v27, v210
	v_add_f32_e32 v18, v36, v18
	v_add_f32_e32 v210, v20, v210
	v_pk_mul_f32 v[38:39], v[38:39], v[38:39]
	v_pk_mul_f32 v[22:23], v[22:23], v[22:23]
	v_add_f32_e32 v18, v37, v18
	v_add_f32_e32 v210, v21, v210
	v_add_f32_e32 v18, v38, v18
	v_add_f32_e32 v210, v22, v210
	v_pk_mul_f32 v[46:47], v[48:49], v[48:49]
	v_pk_mul_f32 v[30:31], v[32:33], v[32:33]
	v_add_f32_e32 v18, v39, v18
	v_add_f32_e32 v210, v23, v210
	v_add_f32_e32 v18, v46, v18
	v_add_f32_e32 v210, v30, v210
	v_pk_mul_f32 v[48:49], v[50:51], v[50:51]
	v_pk_mul_f32 v[32:33], v[34:35], v[34:35]
	v_add_f32_e32 v18, v47, v18
	v_add_f32_e32 v210, v31, v210
	v_add_f32_e32 v18, v48, v18
	v_add_f32_e32 v210, v32, v210
	v_add_f32_e32 v18, v49, v18
	v_add_f32_e32 v210, v33, v210
	v_mov_b32_e32 v147, v18
	v_mov_b32_e32 v148, v210
	v_pk_mul_f32 v[12:13], v[12:13], v[12:13]
	v_pk_mul_f32 v[14:15], v[14:15], v[14:15]
	v_add_f32_e32 v12, v12, v13
	v_add_f32_e32 v12, v14, v12
	v_pk_mul_f32 v[8:9], v[8:9], v[8:9]
	v_add_f32_e32 v12, v15, v12
	v_add_f32_e32 v8, v8, v12
	v_pk_mul_f32 v[10:11], v[10:11], v[10:11]
	v_add_f32_e32 v8, v9, v8
	v_add_f32_e32 v8, v10, v8
	v_pk_mul_f32 v[4:5], v[4:5], v[4:5]
	v_add_f32_e32 v8, v11, v8
	v_add_f32_e32 v4, v4, v8
	v_pk_mul_f32 v[6:7], v[6:7], v[6:7]
	v_add_f32_e32 v4, v5, v4
	v_add_f32_e32 v4, v6, v4
	v_pk_mul_f32 v[0:1], v[0:1], v[0:1]
	v_add_f32_e32 v4, v7, v4
	v_add_f32_e32 v0, v0, v4
	v_pk_mul_f32 v[2:3], v[2:3], v[2:3]
	v_add_f32_e32 v0, v1, v0
	v_add_f32_e32 v0, v2, v0
	v_add_f32_e32 v0, v3, v0
	v_mov_b32_e32 v149, v0
	ds_bpermute_b32 v172, v16, v132
	ds_bpermute_b32 v173, v16, v133
	ds_bpermute_b32 v174, v16, v134
	ds_bpermute_b32 v175, v16, v135
	ds_bpermute_b32 v180, v16, v146
	ds_bpermute_b32 v181, v16, v147
	ds_bpermute_b32 v182, v16, v148
	ds_bpermute_b32 v183, v16, v149
	s_waitcnt lgkmcnt(0)
	v_add_f32_e32 v132, v132, v172
	v_add_f32_e32 v133, v133, v173
	v_add_f32_e32 v134, v134, v174
	v_add_f32_e32 v135, v135, v175
	v_add_f32_e32 v146, v146, v180
	v_add_f32_e32 v147, v147, v181
	v_add_f32_e32 v148, v148, v182
	v_add_f32_e32 v149, v149, v183
	ds_bpermute_b32 v172, v17, v132
	ds_bpermute_b32 v173, v17, v133
	ds_bpermute_b32 v174, v17, v134
	ds_bpermute_b32 v175, v17, v135
	ds_bpermute_b32 v180, v17, v146
	ds_bpermute_b32 v181, v17, v147
	ds_bpermute_b32 v182, v17, v148
	ds_bpermute_b32 v183, v17, v149
	s_and_saveexec_b64 s[46:47], s[42:43]
	s_cbranch_execz .LBB0_19
	s_waitcnt lgkmcnt(0)
	v_add_f32_e32 v132, v132, v172
	v_lshlrev_b64 v[18:19], 6, v[168:169]
	v_lshl_add_u64 v[18:19], s[38:39], 0, v[18:19]
	global_store_dword v[18:19], v132, off
	v_add_f32_e32 v133, v133, v173
	v_lshlrev_b64 v[18:19], 6, v[166:167]
	v_lshl_add_u64 v[18:19], s[38:39], 0, v[18:19]
	global_store_dword v[18:19], v133, off
	v_add_f32_e32 v134, v134, v174
	v_lshlrev_b64 v[18:19], 6, v[164:165]
	v_lshl_add_u64 v[18:19], s[38:39], 0, v[18:19]
	global_store_dword v[18:19], v134, off
	v_add_f32_e32 v135, v135, v175
	v_lshlrev_b64 v[18:19], 6, v[162:163]
	v_lshl_add_u64 v[18:19], s[38:39], 0, v[18:19]
	global_store_dword v[18:19], v135, off
	v_add_f32_e32 v146, v146, v180
	v_lshlrev_b64 v[18:19], 6, v[76:77]
	v_lshl_add_u64 v[18:19], s[38:39], 0, v[18:19]
	global_store_dword v[18:19], v146, off
	v_add_f32_e32 v147, v147, v181
	v_lshlrev_b64 v[18:19], 6, v[72:73]
	v_lshl_add_u64 v[18:19], s[38:39], 0, v[18:19]
	global_store_dword v[18:19], v147, off
	v_add_f32_e32 v148, v148, v182
	v_lshlrev_b64 v[18:19], 6, v[70:71]
	v_lshl_add_u64 v[18:19], s[38:39], 0, v[18:19]
	global_store_dword v[18:19], v148, off
	v_add_f32_e32 v149, v149, v183
	v_lshlrev_b64 v[18:19], 6, v[68:69]
	v_lshl_add_u64 v[18:19], s[38:39], 0, v[18:19]
	global_store_dword v[18:19], v149, off
	s_branch .LBB0_19

.LBB0_77:
	s_add_u32 s6, s26, s50
	s_addc_u32 s19, s27, s51
	s_add_u32 s6, s6, 0x100
	s_addc_u32 s19, s19, 0
	s_add_u32 s23, s10, s50
	s_addc_u32 s52, s11, s51
	s_add_i32 s82, 0, 0x10000
	v_add_u32_e32 v146, s82, v154
	ds_read_b128 v[158:161], v146
	ds_read_b128 v[162:165], v146 offset:1024
	ds_read_b128 v[166:169], v146 offset:2048
	ds_read_b128 v[170:173], v146 offset:3072
	s_cmpk_eq_i32 s50, 0x700
	s_cselect_b32 s55, s12, s19
	s_cselect_b32 s54, s31, s6
	s_cselect_b32 s53, s35, s52
	s_cselect_b32 s52, s39, s23
	v_lshl_add_u64 v[146:147], v[150:151], 0, s[50:51]
	s_add_i32 m0, s68, 0xc000
	ds_read_b128 v[174:177], v157
	ds_read_b128 v[178:181], v157 offset:1024
	ds_read_b128 v[182:185], v157 offset:2048
	ds_read_b128 v[206:209], v157 offset:3072
	ds_read_b128 v[210:213], v157 offset:4096
	ds_read_b128 v[214:217], v157 offset:5120
	ds_read_b128 v[218:221], v157 offset:6144
	ds_read_b128 v[222:225], v157 offset:7168
	global_load_lds_dwordx4 v[146:147], off
	v_lshl_add_u64 v[146:147], v[152:153], 0, s[50:51]
	s_add_i32 m0, s68, 0xe000
	s_nop 0
	global_load_lds_dwordx4 v[146:147], off
	s_add_i32 s6, 0, 0x14000
	v_add_u32_e32 v146, s6, v154
	ds_read_b128 v[226:229], v146
	ds_read_b128 v[230:233], v146 offset:1024
	ds_read_b128 v[234:237], v146 offset:2048
	ds_read_b128 v[238:241], v146 offset:3072
	s_nop 0
	s_waitcnt vmcnt(8)
	s_waitcnt lgkmcnt(0)
	s_barrier
	v_mfma_f32_16x16x32_bf16 v[124:127], v[158:161], v[174:177], v[124:127]
	v_mfma_f32_16x16x32_bf16 v[120:123], v[166:169], v[174:177], v[120:123]
	v_mfma_f32_16x16x32_bf16 v[116:119], v[158:161], v[182:185], v[116:119]
	v_mfma_f32_16x16x32_bf16 v[112:115], v[166:169], v[182:185], v[112:115]
	v_mfma_f32_16x16x32_bf16 v[108:111], v[158:161], v[210:213], v[108:111]
	v_mfma_f32_16x16x32_bf16 v[104:107], v[166:169], v[210:213], v[104:107]
	v_mfma_f32_16x16x32_bf16 v[100:103], v[158:161], v[218:221], v[100:103]
	v_mfma_f32_16x16x32_bf16 v[96:99], v[166:169], v[218:221], v[96:99]
	v_mfma_f32_16x16x32_bf16 v[124:127], v[162:165], v[178:181], v[124:127]
	v_mfma_f32_16x16x32_bf16 v[120:123], v[170:173], v[178:181], v[120:123]
	v_mfma_f32_16x16x32_bf16 v[116:119], v[162:165], v[206:209], v[116:119]
	v_mfma_f32_16x16x32_bf16 v[112:115], v[170:173], v[206:209], v[112:115]
	v_mfma_f32_16x16x32_bf16 v[108:111], v[162:165], v[214:217], v[108:111]
	v_mfma_f32_16x16x32_bf16 v[104:107], v[170:173], v[214:217], v[104:107]
	v_mfma_f32_16x16x32_bf16 v[100:103], v[162:165], v[222:225], v[100:103]
	v_mfma_f32_16x16x32_bf16 v[96:99], v[170:173], v[222:225], v[96:99]
	v_mfma_f32_16x16x32_bf16 v[92:95], v[226:229], v[174:177], v[92:95]
	v_mfma_f32_16x16x32_bf16 v[88:91], v[234:237], v[174:177], v[88:91]
	v_mfma_f32_16x16x32_bf16 v[84:87], v[226:229], v[182:185], v[84:87]
	v_mfma_f32_16x16x32_bf16 v[80:83], v[234:237], v[182:185], v[80:83]
	v_mfma_f32_16x16x32_bf16 v[76:79], v[226:229], v[210:213], v[76:79]
	v_mfma_f32_16x16x32_bf16 v[72:75], v[234:237], v[210:213], v[72:75]
	v_mfma_f32_16x16x32_bf16 v[68:71], v[226:229], v[218:221], v[68:71]
	v_mfma_f32_16x16x32_bf16 v[64:67], v[234:237], v[218:221], v[64:67]
	v_mfma_f32_16x16x32_bf16 v[92:95], v[230:233], v[178:181], v[92:95]
	v_mfma_f32_16x16x32_bf16 v[88:91], v[238:241], v[178:181], v[88:91]
	v_mfma_f32_16x16x32_bf16 v[84:87], v[230:233], v[206:209], v[84:87]
	v_mfma_f32_16x16x32_bf16 v[80:83], v[238:241], v[206:209], v[80:83]
	v_mfma_f32_16x16x32_bf16 v[76:79], v[230:233], v[214:217], v[76:79]
	v_mfma_f32_16x16x32_bf16 v[72:75], v[238:241], v[214:217], v[72:75]
	v_mfma_f32_16x16x32_bf16 v[68:71], v[230:233], v[222:225], v[68:71]
	v_mfma_f32_16x16x32_bf16 v[64:67], v[238:241], v[222:225], v[64:67]
	s_barrier
	s_add_i32 s19, s82, s59
	v_lshl_add_u64 v[146:147], s[52:53], 0, v[140:141]
	s_mov_b32 m0, s19
	v_lshl_add_u64 v[148:149], s[52:53], 0, v[132:133]
	global_load_lds_dwordx4 v[146:147], off
	s_add_i32 m0, s19, 0x2000
	s_nop 0
	global_load_lds_dwordx4 v[148:149], off
	s_mov_b32 m0, s68
	v_lshl_add_u64 v[194:195], s[54:55], 0, v[128:129]
	ds_read_b128 v[174:177], v157 offset:16384
	ds_read_b128 v[178:181], v157 offset:17408
	ds_read_b128 v[182:185], v157 offset:18432
	ds_read_b128 v[206:209], v157 offset:19456
	ds_read_b128 v[210:213], v157 offset:20480
	ds_read_b128 v[214:217], v157 offset:21504
	ds_read_b128 v[218:221], v157 offset:22528
	ds_read_b128 v[222:225], v157 offset:23552
	global_load_lds_dwordx4 v[194:195], off
	v_lshl_add_u64 v[196:197], s[54:55], 0, v[130:131]
	s_mov_b32 m0, s69
	s_nop 0
	global_load_lds_dwordx4 v[196:197], off
	s_add_u32 s82, s52, 0x40000
	s_addc_u32 s83, s53, 0
	s_add_i32 s6, s6, s59
	v_lshl_add_u64 v[250:251], s[82:83], 0, v[140:141]
	s_mov_b32 m0, s6
	s_nop 0
	global_load_lds_dwordx4 v[250:251], off
	v_lshl_add_u64 v[250:251], s[82:83], 0, v[132:133]
	s_add_i32 m0, s6, 0x2000
	s_nop 0
	global_load_lds_dwordx4 v[250:251], off
	s_nop 0
	s_waitcnt vmcnt(8)
	s_waitcnt lgkmcnt(0)
	s_barrier
	v_mfma_f32_16x16x32_bf16 v[60:63], v[158:161], v[174:177], v[60:63]
	v_mfma_f32_16x16x32_bf16 v[56:59], v[166:169], v[174:177], v[56:59]
	v_mfma_f32_16x16x32_bf16 v[52:55], v[158:161], v[182:185], v[52:55]
	v_mfma_f32_16x16x32_bf16 v[48:51], v[166:169], v[182:185], v[48:51]
	v_mfma_f32_16x16x32_bf16 v[44:47], v[158:161], v[210:213], v[44:47]
	v_mfma_f32_16x16x32_bf16 v[40:43], v[166:169], v[210:213], v[40:43]
	v_mfma_f32_16x16x32_bf16 v[36:39], v[158:161], v[218:221], v[36:39]
	v_mfma_f32_16x16x32_bf16 v[32:35], v[166:169], v[218:221], v[32:35]
	v_mfma_f32_16x16x32_bf16 v[60:63], v[162:165], v[178:181], v[60:63]
	v_mfma_f32_16x16x32_bf16 v[56:59], v[170:173], v[178:181], v[56:59]
	v_mfma_f32_16x16x32_bf16 v[52:55], v[162:165], v[206:209], v[52:55]
	v_mfma_f32_16x16x32_bf16 v[48:51], v[170:173], v[206:209], v[48:51]
	v_mfma_f32_16x16x32_bf16 v[44:47], v[162:165], v[214:217], v[44:47]
	v_mfma_f32_16x16x32_bf16 v[40:43], v[170:173], v[214:217], v[40:43]
	v_mfma_f32_16x16x32_bf16 v[36:39], v[162:165], v[222:225], v[36:39]
	v_mfma_f32_16x16x32_bf16 v[32:35], v[170:173], v[222:225], v[32:35]
	v_mfma_f32_16x16x32_bf16 v[28:31], v[226:229], v[174:177], v[28:31]
	v_mfma_f32_16x16x32_bf16 v[24:27], v[234:237], v[174:177], v[24:27]
	v_mfma_f32_16x16x32_bf16 v[20:23], v[226:229], v[182:185], v[20:23]
	v_mfma_f32_16x16x32_bf16 v[16:19], v[234:237], v[182:185], v[16:19]
	v_mfma_f32_16x16x32_bf16 v[12:15], v[226:229], v[210:213], v[12:15]
	v_mfma_f32_16x16x32_bf16 v[8:11], v[234:237], v[210:213], v[8:11]
	v_mfma_f32_16x16x32_bf16 v[4:7], v[226:229], v[218:221], v[4:7]
	v_mfma_f32_16x16x32_bf16 v[0:3], v[234:237], v[218:221], v[0:3]
	v_mfma_f32_16x16x32_bf16 v[28:31], v[230:233], v[178:181], v[28:31]
	v_mfma_f32_16x16x32_bf16 v[24:27], v[238:241], v[178:181], v[24:27]
	v_mfma_f32_16x16x32_bf16 v[20:23], v[230:233], v[206:209], v[20:23]
	v_mfma_f32_16x16x32_bf16 v[16:19], v[238:241], v[206:209], v[16:19]
	v_mfma_f32_16x16x32_bf16 v[12:15], v[230:233], v[214:217], v[12:15]
	v_mfma_f32_16x16x32_bf16 v[8:11], v[238:241], v[214:217], v[8:11]
	v_mfma_f32_16x16x32_bf16 v[4:7], v[230:233], v[222:225], v[4:7]
	v_mfma_f32_16x16x32_bf16 v[0:3], v[238:241], v[222:225], v[0:3]
	s_barrier
	s_add_i32 s6, 0, 0x18000
	v_add_u32_e32 v170, s6, v154
	ds_read_b128 v[158:161], v170
	ds_read_b128 v[162:165], v170 offset:1024
	ds_read_b128 v[166:169], v170 offset:2048
	ds_read_b128 v[170:173], v170 offset:3072
	s_add_u32 s54, s54, 0x40000
	s_addc_u32 s55, s55, 0
	s_mov_b32 m0, s70
	v_lshl_add_u64 v[226:227], s[54:55], 0, v[128:129]
	ds_read_b128 v[174:177], v157 offset:32768
	ds_read_b128 v[178:181], v157 offset:33792
	ds_read_b128 v[182:185], v157 offset:34816
	ds_read_b128 v[206:209], v157 offset:35840
	ds_read_b128 v[210:213], v157 offset:36864
	ds_read_b128 v[214:217], v157 offset:37888
	ds_read_b128 v[218:221], v157 offset:38912
	ds_read_b128 v[222:225], v157 offset:39936
	global_load_lds_dwordx4 v[226:227], off
	v_lshl_add_u64 v[226:227], s[54:55], 0, v[130:131]
	s_mov_b32 m0, s71
	s_nop 0
	global_load_lds_dwordx4 v[226:227], off
	s_add_i32 s19, 0, 0x1c000
	v_add_u32_e32 v192, s19, v154
	ds_read_b128 v[226:229], v192
	ds_read_b128 v[230:233], v192 offset:1024
	ds_read_b128 v[234:237], v192 offset:2048
	ds_read_b128 v[238:241], v192 offset:3072
	s_waitcnt vmcnt(8)
	s_waitcnt lgkmcnt(0)
	s_barrier
	v_mfma_f32_16x16x32_bf16 v[124:127], v[158:161], v[174:177], v[124:127]
	v_mfma_f32_16x16x32_bf16 v[120:123], v[166:169], v[174:177], v[120:123]
	v_mfma_f32_16x16x32_bf16 v[116:119], v[158:161], v[182:185], v[116:119]
	v_mfma_f32_16x16x32_bf16 v[112:115], v[166:169], v[182:185], v[112:115]
	v_mfma_f32_16x16x32_bf16 v[108:111], v[158:161], v[210:213], v[108:111]
	v_mfma_f32_16x16x32_bf16 v[104:107], v[166:169], v[210:213], v[104:107]
	v_mfma_f32_16x16x32_bf16 v[100:103], v[158:161], v[218:221], v[100:103]
	v_mfma_f32_16x16x32_bf16 v[96:99], v[166:169], v[218:221], v[96:99]
	v_mfma_f32_16x16x32_bf16 v[124:127], v[162:165], v[178:181], v[124:127]
	v_mfma_f32_16x16x32_bf16 v[120:123], v[170:173], v[178:181], v[120:123]
	v_mfma_f32_16x16x32_bf16 v[116:119], v[162:165], v[206:209], v[116:119]
	v_mfma_f32_16x16x32_bf16 v[112:115], v[170:173], v[206:209], v[112:115]
	v_mfma_f32_16x16x32_bf16 v[108:111], v[162:165], v[214:217], v[108:111]
	v_mfma_f32_16x16x32_bf16 v[104:107], v[170:173], v[214:217], v[104:107]
	v_mfma_f32_16x16x32_bf16 v[100:103], v[162:165], v[222:225], v[100:103]
	v_mfma_f32_16x16x32_bf16 v[96:99], v[170:173], v[222:225], v[96:99]
	v_mfma_f32_16x16x32_bf16 v[92:95], v[226:229], v[174:177], v[92:95]
	v_mfma_f32_16x16x32_bf16 v[88:91], v[234:237], v[174:177], v[88:91]
	v_mfma_f32_16x16x32_bf16 v[84:87], v[226:229], v[182:185], v[84:87]
	v_mfma_f32_16x16x32_bf16 v[80:83], v[234:237], v[182:185], v[80:83]
	v_mfma_f32_16x16x32_bf16 v[76:79], v[226:229], v[210:213], v[76:79]
	v_mfma_f32_16x16x32_bf16 v[72:75], v[234:237], v[210:213], v[72:75]
	v_mfma_f32_16x16x32_bf16 v[68:71], v[226:229], v[218:221], v[68:71]
	v_mfma_f32_16x16x32_bf16 v[64:67], v[234:237], v[218:221], v[64:67]
	v_mfma_f32_16x16x32_bf16 v[92:95], v[230:233], v[178:181], v[92:95]
	v_mfma_f32_16x16x32_bf16 v[88:91], v[238:241], v[178:181], v[88:91]
	v_mfma_f32_16x16x32_bf16 v[84:87], v[230:233], v[206:209], v[84:87]
	v_mfma_f32_16x16x32_bf16 v[80:83], v[238:241], v[206:209], v[80:83]
	v_mfma_f32_16x16x32_bf16 v[76:79], v[230:233], v[214:217], v[76:79]
	v_mfma_f32_16x16x32_bf16 v[72:75], v[238:241], v[214:217], v[72:75]
	v_mfma_f32_16x16x32_bf16 v[68:71], v[230:233], v[222:225], v[68:71]
	v_mfma_f32_16x16x32_bf16 v[64:67], v[238:241], v[222:225], v[64:67]
	s_barrier
	s_add_i32 s6, s6, s59
	v_lshl_add_u64 v[146:147], v[146:147], 0, s[36:37]
	s_mov_b32 m0, s6
	s_nop 0
	global_load_lds_dwordx4 v[146:147], off
	v_lshl_add_u64 v[146:147], v[148:149], 0, s[36:37]
	s_add_i32 m0, s6, 0x2000
	s_nop 0
	global_load_lds_dwordx4 v[146:147], off
	s_mov_b32 m0, s72
	v_lshl_add_u64 v[146:147], v[194:195], 0, s[36:37]
	ds_read_b128 v[174:177], v157 offset:49152
	ds_read_b128 v[178:181], v157 offset:50176
	ds_read_b128 v[182:185], v157 offset:51200
	ds_read_b128 v[206:209], v157 offset:52224
	ds_read_b128 v[210:213], v157 offset:53248
	ds_read_b128 v[214:217], v157 offset:54272
	ds_read_b128 v[218:221], v157 offset:55296
	ds_read_b128 v[222:225], v157 offset:56320
	global_load_lds_dwordx4 v[146:147], off
	v_lshl_add_u64 v[146:147], v[196:197], 0, s[36:37]
	s_mov_b32 m0, s73
	s_nop 0
	global_load_lds_dwordx4 v[146:147], off
	s_add_u32 s52, s52, 0x40080
	s_addc_u32 s53, s53, 0
	s_add_i32 s6, s19, s59
	v_lshl_add_u64 v[146:147], s[52:53], 0, v[140:141]
	s_mov_b32 m0, s6
	s_nop 0
	global_load_lds_dwordx4 v[146:147], off
	v_lshl_add_u64 v[146:147], s[52:53], 0, v[132:133]
	s_add_i32 m0, s6, 0x2000
	s_nop 0
	global_load_lds_dwordx4 v[146:147], off
	s_add_i32 s81, s81, 2
	s_add_u32 s50, s50, 0x100
	s_addc_u32 s51, s51, 0
	s_cmp_gt_u32 s81, 13
	s_nop 0
	s_waitcnt vmcnt(8)
	s_waitcnt lgkmcnt(0)
	s_barrier
	v_mfma_f32_16x16x32_bf16 v[60:63], v[158:161], v[174:177], v[60:63]
	v_mfma_f32_16x16x32_bf16 v[56:59], v[166:169], v[174:177], v[56:59]
	v_mfma_f32_16x16x32_bf16 v[52:55], v[158:161], v[182:185], v[52:55]
	v_mfma_f32_16x16x32_bf16 v[48:51], v[166:169], v[182:185], v[48:51]
	v_mfma_f32_16x16x32_bf16 v[44:47], v[158:161], v[210:213], v[44:47]
	v_mfma_f32_16x16x32_bf16 v[40:43], v[166:169], v[210:213], v[40:43]
	v_mfma_f32_16x16x32_bf16 v[36:39], v[158:161], v[218:221], v[36:39]
	v_mfma_f32_16x16x32_bf16 v[32:35], v[166:169], v[218:221], v[32:35]
	v_mfma_f32_16x16x32_bf16 v[60:63], v[162:165], v[178:181], v[60:63]
	v_mfma_f32_16x16x32_bf16 v[56:59], v[170:173], v[178:181], v[56:59]
	v_mfma_f32_16x16x32_bf16 v[52:55], v[162:165], v[206:209], v[52:55]
	v_mfma_f32_16x16x32_bf16 v[48:51], v[170:173], v[206:209], v[48:51]
	v_mfma_f32_16x16x32_bf16 v[44:47], v[162:165], v[214:217], v[44:47]
	v_mfma_f32_16x16x32_bf16 v[40:43], v[170:173], v[214:217], v[40:43]
	v_mfma_f32_16x16x32_bf16 v[36:39], v[162:165], v[222:225], v[36:39]
	v_mfma_f32_16x16x32_bf16 v[32:35], v[170:173], v[222:225], v[32:35]
	v_mfma_f32_16x16x32_bf16 v[28:31], v[226:229], v[174:177], v[28:31]
	v_mfma_f32_16x16x32_bf16 v[24:27], v[234:237], v[174:177], v[24:27]
	v_mfma_f32_16x16x32_bf16 v[20:23], v[226:229], v[182:185], v[20:23]
	v_mfma_f32_16x16x32_bf16 v[16:19], v[234:237], v[182:185], v[16:19]
	v_mfma_f32_16x16x32_bf16 v[12:15], v[226:229], v[210:213], v[12:15]
	v_mfma_f32_16x16x32_bf16 v[8:11], v[234:237], v[210:213], v[8:11]
	v_mfma_f32_16x16x32_bf16 v[4:7], v[226:229], v[218:221], v[4:7]
	v_mfma_f32_16x16x32_bf16 v[0:3], v[234:237], v[218:221], v[0:3]
	v_mfma_f32_16x16x32_bf16 v[28:31], v[230:233], v[178:181], v[28:31]
	v_mfma_f32_16x16x32_bf16 v[24:27], v[238:241], v[178:181], v[24:27]
	v_mfma_f32_16x16x32_bf16 v[20:23], v[230:233], v[206:209], v[20:23]
	v_mfma_f32_16x16x32_bf16 v[16:19], v[238:241], v[206:209], v[16:19]
	v_mfma_f32_16x16x32_bf16 v[12:15], v[230:233], v[214:217], v[12:15]
	v_mfma_f32_16x16x32_bf16 v[8:11], v[238:241], v[214:217], v[8:11]
	v_mfma_f32_16x16x32_bf16 v[4:7], v[230:233], v[222:225], v[4:7]
	v_mfma_f32_16x16x32_bf16 v[0:3], v[238:241], v[222:225], v[0:3]
	s_barrier
	s_cbranch_scc0 .LBB0_77
	s_mov_b32 s100, 1
	v_lshl_add_u32 v158, s75, 10, v155
	ds_read2_b32 v[146:147], v158 offset1:16
	ds_read2_b32 v[208:209], v158 offset0:32 offset1:48
	ds_read2_b32 v[210:211], v158 offset0:128 offset1:144
	ds_read2_b32 v[212:213], v158 offset0:160 offset1:176
	s_add_u32 s50, s10, 0xffffff00
	s_addc_u32 s51, s11, -1
	s_ashr_i32 s31, s30, 31
	s_lshl_b64 s[10:11], s[30:31], 8
	s_waitcnt lgkmcnt(0)
	v_mul_f32_e32 v184, 0xbfb8aa3b, v146
	v_mul_f32_e32 v206, v146, v146
	v_pk_mul_f32 v[168:169], v[124:125], v[184:185] op_sel_hi:[1,0]
	v_pk_mul_f32 v[170:171], v[126:127], v[184:185] op_sel_hi:[1,0]
	v_pk_mul_f32 v[172:173], v[120:121], v[184:185] op_sel_hi:[1,0]
	v_pk_mul_f32 v[174:175], v[122:123], v[184:185] op_sel_hi:[1,0]
	v_exp_f32_e32 v168, v168
	v_exp_f32_e32 v169, v169
	v_exp_f32_e32 v170, v170
	v_exp_f32_e32 v171, v171
	v_exp_f32_e32 v172, v172
	v_exp_f32_e32 v173, v173
	v_exp_f32_e32 v174, v174
	v_exp_f32_e32 v175, v175
	v_pk_mul_f32 v[176:177], v[124:125], v[92:93]
	v_pk_mul_f32 v[178:179], v[126:127], v[94:95]
	v_pk_mul_f32 v[180:181], v[120:121], v[88:89]
	v_pk_mul_f32 v[182:183], v[122:123], v[90:91]
	v_pk_add_f32 v[168:169], v[168:169], 1.0 op_sel_hi:[1,0]
	v_pk_add_f32 v[170:171], v[170:171], 1.0 op_sel_hi:[1,0]
	v_pk_add_f32 v[172:173], v[172:173], 1.0 op_sel_hi:[1,0]
	v_pk_add_f32 v[174:175], v[174:175], 1.0 op_sel_hi:[1,0]
	v_rcp_f32_e32 v168, v168
	v_rcp_f32_e32 v169, v169
	v_rcp_f32_e32 v170, v170
	v_rcp_f32_e32 v171, v171
	v_rcp_f32_e32 v172, v172
	v_rcp_f32_e32 v173, v173
	v_rcp_f32_e32 v174, v174
	v_rcp_f32_e32 v175, v175
	v_pk_mul_f32 v[176:177], v[176:177], v[206:207] op_sel_hi:[1,0]
	v_pk_mul_f32 v[178:179], v[178:179], v[206:207] op_sel_hi:[1,0]
	v_pk_mul_f32 v[180:181], v[180:181], v[206:207] op_sel_hi:[1,0]
	v_pk_mul_f32 v[182:183], v[182:183], v[206:207] op_sel_hi:[1,0]
	v_pk_mul_f32 v[176:177], v[176:177], v[168:169]
	v_pk_mul_f32 v[178:179], v[178:179], v[170:171]
	v_pk_mul_f32 v[180:181], v[180:181], v[172:173]
	v_pk_mul_f32 v[182:183], v[182:183], v[174:175]
	v_cvt_pk_bf16_f32 v160, v176, v177
	v_cvt_pk_bf16_f32 v161, v178, v179
	v_cvt_pk_bf16_f32 v162, v180, v181
	v_cvt_pk_bf16_f32 v163, v182, v183
	v_lshl_add_u64 v[152:153], v[134:135], 0, s[10:11]
	s_movk_i32 s6, 0x1600
	v_lshl_or_b32 v150, s74, 7, v156
	v_ashrrev_i32_e32 v151, 31, v150
	s_nop 1
	v_mov_b64_e32 v[148:149], s[28:29]
	v_mad_u64_u32 v[148:149], s[10:11], v152, s6, v[148:149]
	v_mov_b32_e32 v146, v149
	v_mad_u64_u32 v[152:153], s[10:11], v153, s6, v[146:147]
	v_mov_b32_e32 v149, v152
	v_mov_b32_e32 v146, v147
	v_lshl_add_u64 v[150:151], v[150:151], 1, v[148:149]
	global_store_dwordx4 v[150:151], v[160:163], off
	v_mul_f32_e32 v184, 0xbfb8aa3b, v146
	v_mul_f32_e32 v206, v146, v146
	v_pk_mul_f32 v[168:169], v[116:117], v[184:185] op_sel_hi:[1,0]
	v_pk_mul_f32 v[170:171], v[118:119], v[184:185] op_sel_hi:[1,0]
	v_pk_mul_f32 v[172:173], v[112:113], v[184:185] op_sel_hi:[1,0]
	v_pk_mul_f32 v[174:175], v[114:115], v[184:185] op_sel_hi:[1,0]
	v_exp_f32_e32 v168, v168
	v_exp_f32_e32 v169, v169
	v_exp_f32_e32 v170, v170
	v_exp_f32_e32 v171, v171
	v_exp_f32_e32 v172, v172
	v_exp_f32_e32 v173, v173
	v_exp_f32_e32 v174, v174
	v_exp_f32_e32 v175, v175
	v_pk_mul_f32 v[176:177], v[116:117], v[84:85]
	v_pk_mul_f32 v[178:179], v[118:119], v[86:87]
	v_pk_mul_f32 v[180:181], v[112:113], v[80:81]
	v_pk_mul_f32 v[182:183], v[114:115], v[82:83]
	v_pk_add_f32 v[168:169], v[168:169], 1.0 op_sel_hi:[1,0]
	v_pk_add_f32 v[170:171], v[170:171], 1.0 op_sel_hi:[1,0]
	v_pk_add_f32 v[172:173], v[172:173], 1.0 op_sel_hi:[1,0]
	v_pk_add_f32 v[174:175], v[174:175], 1.0 op_sel_hi:[1,0]
	v_rcp_f32_e32 v168, v168
	v_rcp_f32_e32 v169, v169
	v_rcp_f32_e32 v170, v170
	v_rcp_f32_e32 v171, v171
	v_rcp_f32_e32 v172, v172
	v_rcp_f32_e32 v173, v173
	v_rcp_f32_e32 v174, v174
	v_rcp_f32_e32 v175, v175
	v_pk_mul_f32 v[176:177], v[176:177], v[206:207] op_sel_hi:[1,0]
	v_pk_mul_f32 v[178:179], v[178:179], v[206:207] op_sel_hi:[1,0]
	v_pk_mul_f32 v[180:181], v[180:181], v[206:207] op_sel_hi:[1,0]
	v_pk_mul_f32 v[182:183], v[182:183], v[206:207] op_sel_hi:[1,0]
	v_pk_mul_f32 v[176:177], v[176:177], v[168:169]
	v_pk_mul_f32 v[178:179], v[178:179], v[170:171]
	v_pk_mul_f32 v[180:181], v[180:181], v[172:173]
	v_pk_mul_f32 v[182:183], v[182:183], v[174:175]
	v_cvt_pk_bf16_f32 v160, v176, v177
	v_cvt_pk_bf16_f32 v161, v178, v179
	v_cvt_pk_bf16_f32 v162, v180, v181
	v_cvt_pk_bf16_f32 v163, v182, v183
	s_mov_b32 s6, 0x16000
	s_nop 1
	v_add_co_u32_e32 v146, vcc, s6, v150
	s_nop 0
	v_addc_co_u32_e32 v147, vcc, 0, v151, vcc
	global_store_dwordx4 v[146:147], v[160:163], off
	v_mov_b32_e32 v146, v208
	v_mov_b32_e32 v147, v209
	s_mov_b32 s6, 0x2c000
	s_waitcnt lgkmcnt(0)
	v_mul_f32_e32 v184, 0xbfb8aa3b, v146
	v_mul_f32_e32 v206, v146, v146
	v_pk_mul_f32 v[168:169], v[108:109], v[184:185] op_sel_hi:[1,0]
	v_pk_mul_f32 v[170:171], v[110:111], v[184:185] op_sel_hi:[1,0]
	v_pk_mul_f32 v[172:173], v[104:105], v[184:185] op_sel_hi:[1,0]
	v_pk_mul_f32 v[174:175], v[106:107], v[184:185] op_sel_hi:[1,0]
	v_exp_f32_e32 v168, v168
	v_exp_f32_e32 v169, v169
	v_exp_f32_e32 v170, v170
	v_exp_f32_e32 v171, v171
	v_exp_f32_e32 v172, v172
	v_exp_f32_e32 v173, v173
	v_exp_f32_e32 v174, v174
	v_exp_f32_e32 v175, v175
	v_pk_mul_f32 v[176:177], v[108:109], v[76:77]
	v_pk_mul_f32 v[178:179], v[110:111], v[78:79]
	v_pk_mul_f32 v[180:181], v[104:105], v[72:73]
	v_pk_mul_f32 v[182:183], v[106:107], v[74:75]
	v_pk_add_f32 v[168:169], v[168:169], 1.0 op_sel_hi:[1,0]
	v_pk_add_f32 v[170:171], v[170:171], 1.0 op_sel_hi:[1,0]
	v_pk_add_f32 v[172:173], v[172:173], 1.0 op_sel_hi:[1,0]
	v_pk_add_f32 v[174:175], v[174:175], 1.0 op_sel_hi:[1,0]
	v_rcp_f32_e32 v168, v168
	v_rcp_f32_e32 v169, v169
	v_rcp_f32_e32 v170, v170
	v_rcp_f32_e32 v171, v171
	v_rcp_f32_e32 v172, v172
	v_rcp_f32_e32 v173, v173
	v_rcp_f32_e32 v174, v174
	v_rcp_f32_e32 v175, v175
	v_pk_mul_f32 v[176:177], v[176:177], v[206:207] op_sel_hi:[1,0]
	v_pk_mul_f32 v[178:179], v[178:179], v[206:207] op_sel_hi:[1,0]
	v_pk_mul_f32 v[180:181], v[180:181], v[206:207] op_sel_hi:[1,0]
	v_pk_mul_f32 v[182:183], v[182:183], v[206:207] op_sel_hi:[1,0]
	v_pk_mul_f32 v[176:177], v[176:177], v[168:169]
	v_pk_mul_f32 v[178:179], v[178:179], v[170:171]
	v_pk_mul_f32 v[180:181], v[180:181], v[172:173]
	v_pk_mul_f32 v[182:183], v[182:183], v[174:175]
	v_cvt_pk_bf16_f32 v160, v176, v177
	v_cvt_pk_bf16_f32 v161, v178, v179
	v_cvt_pk_bf16_f32 v162, v180, v181
	v_cvt_pk_bf16_f32 v163, v182, v183
	s_nop 1
	v_mov_b32_e32 v146, v147
	v_add_co_u32_e32 v148, vcc, s6, v150
	v_addc_co_u32_e32 v149, vcc, 0, v151, vcc
	global_store_dwordx4 v[148:149], v[160:163], off
	v_mul_f32_e32 v184, 0xbfb8aa3b, v146
	v_mul_f32_e32 v206, v146, v146
	v_pk_mul_f32 v[168:169], v[100:101], v[184:185] op_sel_hi:[1,0]
	v_pk_mul_f32 v[170:171], v[102:103], v[184:185] op_sel_hi:[1,0]
	v_pk_mul_f32 v[172:173], v[96:97], v[184:185] op_sel_hi:[1,0]
	v_pk_mul_f32 v[174:175], v[98:99], v[184:185] op_sel_hi:[1,0]
	v_exp_f32_e32 v168, v168
	v_exp_f32_e32 v169, v169
	v_exp_f32_e32 v170, v170
	v_exp_f32_e32 v171, v171
	v_exp_f32_e32 v172, v172
	v_exp_f32_e32 v173, v173
	v_exp_f32_e32 v174, v174
	v_exp_f32_e32 v175, v175
	v_pk_mul_f32 v[176:177], v[100:101], v[68:69]
	v_pk_mul_f32 v[178:179], v[102:103], v[70:71]
	v_pk_mul_f32 v[180:181], v[96:97], v[64:65]
	v_pk_mul_f32 v[182:183], v[98:99], v[66:67]
	v_pk_add_f32 v[168:169], v[168:169], 1.0 op_sel_hi:[1,0]
	v_pk_add_f32 v[170:171], v[170:171], 1.0 op_sel_hi:[1,0]
	v_pk_add_f32 v[172:173], v[172:173], 1.0 op_sel_hi:[1,0]
	v_pk_add_f32 v[174:175], v[174:175], 1.0 op_sel_hi:[1,0]
	v_rcp_f32_e32 v168, v168
	v_rcp_f32_e32 v169, v169
	v_rcp_f32_e32 v170, v170
	v_rcp_f32_e32 v171, v171
	v_rcp_f32_e32 v172, v172
	v_rcp_f32_e32 v173, v173
	v_rcp_f32_e32 v174, v174
	v_rcp_f32_e32 v175, v175
	v_pk_mul_f32 v[176:177], v[176:177], v[206:207] op_sel_hi:[1,0]
	v_pk_mul_f32 v[178:179], v[178:179], v[206:207] op_sel_hi:[1,0]
	v_pk_mul_f32 v[180:181], v[180:181], v[206:207] op_sel_hi:[1,0]
	v_pk_mul_f32 v[182:183], v[182:183], v[206:207] op_sel_hi:[1,0]
	v_pk_mul_f32 v[176:177], v[176:177], v[168:169]
	v_pk_mul_f32 v[178:179], v[178:179], v[170:171]
	v_pk_mul_f32 v[180:181], v[180:181], v[172:173]
	v_pk_mul_f32 v[182:183], v[182:183], v[174:175]
	v_cvt_pk_bf16_f32 v160, v176, v177
	v_cvt_pk_bf16_f32 v161, v178, v179
	v_cvt_pk_bf16_f32 v162, v180, v181
	v_cvt_pk_bf16_f32 v163, v182, v183
	s_mov_b32 s6, 0x42000
	s_nop 1
	v_add_co_u32_e32 v146, vcc, s6, v150
	s_nop 0
	v_addc_co_u32_e32 v147, vcc, 0, v151, vcc
	global_store_dwordx4 v[146:147], v[160:163], off
	v_mov_b32_e32 v146, v210
	v_mov_b32_e32 v147, v211
	s_mov_b32 s6, 0xb0000
	s_waitcnt lgkmcnt(0)
	v_mul_f32_e32 v184, 0xbfb8aa3b, v146
	v_mul_f32_e32 v206, v146, v146
	v_pk_mul_f32 v[168:169], v[60:61], v[184:185] op_sel_hi:[1,0]
	v_pk_mul_f32 v[170:171], v[62:63], v[184:185] op_sel_hi:[1,0]
	v_pk_mul_f32 v[172:173], v[56:57], v[184:185] op_sel_hi:[1,0]
	v_pk_mul_f32 v[174:175], v[58:59], v[184:185] op_sel_hi:[1,0]
	v_exp_f32_e32 v168, v168
	v_exp_f32_e32 v169, v169
	v_exp_f32_e32 v170, v170
	v_exp_f32_e32 v171, v171
	v_exp_f32_e32 v172, v172
	v_exp_f32_e32 v173, v173
	v_exp_f32_e32 v174, v174
	v_exp_f32_e32 v175, v175
	v_pk_mul_f32 v[176:177], v[60:61], v[28:29]
	v_pk_mul_f32 v[178:179], v[62:63], v[30:31]
	v_pk_mul_f32 v[180:181], v[56:57], v[24:25]
	v_pk_mul_f32 v[182:183], v[58:59], v[26:27]
	v_pk_add_f32 v[168:169], v[168:169], 1.0 op_sel_hi:[1,0]
	v_pk_add_f32 v[170:171], v[170:171], 1.0 op_sel_hi:[1,0]
	v_pk_add_f32 v[172:173], v[172:173], 1.0 op_sel_hi:[1,0]
	v_pk_add_f32 v[174:175], v[174:175], 1.0 op_sel_hi:[1,0]
	v_rcp_f32_e32 v168, v168
	v_rcp_f32_e32 v169, v169
	v_rcp_f32_e32 v170, v170
	v_rcp_f32_e32 v171, v171
	v_rcp_f32_e32 v172, v172
	v_rcp_f32_e32 v173, v173
	v_rcp_f32_e32 v174, v174
	v_rcp_f32_e32 v175, v175
	v_pk_mul_f32 v[176:177], v[176:177], v[206:207] op_sel_hi:[1,0]
	v_pk_mul_f32 v[178:179], v[178:179], v[206:207] op_sel_hi:[1,0]
	v_pk_mul_f32 v[180:181], v[180:181], v[206:207] op_sel_hi:[1,0]
	v_pk_mul_f32 v[182:183], v[182:183], v[206:207] op_sel_hi:[1,0]
	v_pk_mul_f32 v[176:177], v[176:177], v[168:169]
	v_pk_mul_f32 v[178:179], v[178:179], v[170:171]
	v_pk_mul_f32 v[180:181], v[180:181], v[172:173]
	v_pk_mul_f32 v[182:183], v[182:183], v[174:175]
	v_cvt_pk_bf16_f32 v160, v176, v177
	v_cvt_pk_bf16_f32 v161, v178, v179
	v_cvt_pk_bf16_f32 v162, v180, v181
	v_cvt_pk_bf16_f32 v163, v182, v183
	s_nop 1
	v_mov_b32_e32 v146, v147
	v_add_co_u32_e32 v148, vcc, s6, v150
	v_addc_co_u32_e32 v149, vcc, 0, v151, vcc
	global_store_dwordx4 v[148:149], v[160:163], off
	v_mul_f32_e32 v184, 0xbfb8aa3b, v146
	v_mul_f32_e32 v206, v146, v146
	v_pk_mul_f32 v[168:169], v[52:53], v[184:185] op_sel_hi:[1,0]
	v_pk_mul_f32 v[170:171], v[54:55], v[184:185] op_sel_hi:[1,0]
	v_pk_mul_f32 v[172:173], v[48:49], v[184:185] op_sel_hi:[1,0]
	v_pk_mul_f32 v[174:175], v[50:51], v[184:185] op_sel_hi:[1,0]
	v_exp_f32_e32 v168, v168
	v_exp_f32_e32 v169, v169
	v_exp_f32_e32 v170, v170
	v_exp_f32_e32 v171, v171
	v_exp_f32_e32 v172, v172
	v_exp_f32_e32 v173, v173
	v_exp_f32_e32 v174, v174
	v_exp_f32_e32 v175, v175
	v_pk_mul_f32 v[176:177], v[52:53], v[20:21]
	v_pk_mul_f32 v[178:179], v[54:55], v[22:23]
	v_pk_mul_f32 v[180:181], v[48:49], v[16:17]
	v_pk_mul_f32 v[182:183], v[50:51], v[18:19]
	v_pk_add_f32 v[168:169], v[168:169], 1.0 op_sel_hi:[1,0]
	v_pk_add_f32 v[170:171], v[170:171], 1.0 op_sel_hi:[1,0]
	v_pk_add_f32 v[172:173], v[172:173], 1.0 op_sel_hi:[1,0]
	v_pk_add_f32 v[174:175], v[174:175], 1.0 op_sel_hi:[1,0]
	v_rcp_f32_e32 v168, v168
	v_rcp_f32_e32 v169, v169
	v_rcp_f32_e32 v170, v170
	v_rcp_f32_e32 v171, v171
	v_rcp_f32_e32 v172, v172
	v_rcp_f32_e32 v173, v173
	v_rcp_f32_e32 v174, v174
	v_rcp_f32_e32 v175, v175
	v_pk_mul_f32 v[176:177], v[176:177], v[206:207] op_sel_hi:[1,0]
	v_pk_mul_f32 v[178:179], v[178:179], v[206:207] op_sel_hi:[1,0]
	v_pk_mul_f32 v[180:181], v[180:181], v[206:207] op_sel_hi:[1,0]
	v_pk_mul_f32 v[182:183], v[182:183], v[206:207] op_sel_hi:[1,0]
	v_pk_mul_f32 v[176:177], v[176:177], v[168:169]
	v_pk_mul_f32 v[178:179], v[178:179], v[170:171]
	v_pk_mul_f32 v[180:181], v[180:181], v[172:173]
	v_pk_mul_f32 v[182:183], v[182:183], v[174:175]
	v_cvt_pk_bf16_f32 v160, v176, v177
	v_cvt_pk_bf16_f32 v161, v178, v179
	v_cvt_pk_bf16_f32 v162, v180, v181
	v_cvt_pk_bf16_f32 v163, v182, v183
	s_mov_b32 s6, 0xc6000
	s_nop 1
	v_add_co_u32_e32 v146, vcc, s6, v150
	s_nop 0
	v_addc_co_u32_e32 v147, vcc, 0, v151, vcc
	global_store_dwordx4 v[146:147], v[160:163], off
	v_mov_b32_e32 v146, v212
	v_mov_b32_e32 v147, v213
	s_mov_b32 s6, 0xdc000
	s_waitcnt lgkmcnt(0)
	v_mul_f32_e32 v184, 0xbfb8aa3b, v146
	v_mul_f32_e32 v206, v146, v146
	v_pk_mul_f32 v[168:169], v[44:45], v[184:185] op_sel_hi:[1,0]
	v_pk_mul_f32 v[170:171], v[46:47], v[184:185] op_sel_hi:[1,0]
	v_pk_mul_f32 v[172:173], v[40:41], v[184:185] op_sel_hi:[1,0]
	v_pk_mul_f32 v[174:175], v[42:43], v[184:185] op_sel_hi:[1,0]
	v_exp_f32_e32 v168, v168
	v_exp_f32_e32 v169, v169
	v_exp_f32_e32 v170, v170
	v_exp_f32_e32 v171, v171
	v_exp_f32_e32 v172, v172
	v_exp_f32_e32 v173, v173
	v_exp_f32_e32 v174, v174
	v_exp_f32_e32 v175, v175
	v_pk_mul_f32 v[176:177], v[44:45], v[12:13]
	v_pk_mul_f32 v[178:179], v[46:47], v[14:15]
	v_pk_mul_f32 v[180:181], v[40:41], v[8:9]
	v_pk_mul_f32 v[182:183], v[42:43], v[10:11]
	v_pk_add_f32 v[168:169], v[168:169], 1.0 op_sel_hi:[1,0]
	v_pk_add_f32 v[170:171], v[170:171], 1.0 op_sel_hi:[1,0]
	v_pk_add_f32 v[172:173], v[172:173], 1.0 op_sel_hi:[1,0]
	v_pk_add_f32 v[174:175], v[174:175], 1.0 op_sel_hi:[1,0]
	v_rcp_f32_e32 v168, v168
	v_rcp_f32_e32 v169, v169
	v_rcp_f32_e32 v170, v170
	v_rcp_f32_e32 v171, v171
	v_rcp_f32_e32 v172, v172
	v_rcp_f32_e32 v173, v173
	v_rcp_f32_e32 v174, v174
	v_rcp_f32_e32 v175, v175
	v_pk_mul_f32 v[176:177], v[176:177], v[206:207] op_sel_hi:[1,0]
	v_pk_mul_f32 v[178:179], v[178:179], v[206:207] op_sel_hi:[1,0]
	v_pk_mul_f32 v[180:181], v[180:181], v[206:207] op_sel_hi:[1,0]
	v_pk_mul_f32 v[182:183], v[182:183], v[206:207] op_sel_hi:[1,0]
	v_pk_mul_f32 v[176:177], v[176:177], v[168:169]
	v_pk_mul_f32 v[178:179], v[178:179], v[170:171]
	v_pk_mul_f32 v[180:181], v[180:181], v[172:173]
	v_pk_mul_f32 v[182:183], v[182:183], v[174:175]
	v_cvt_pk_bf16_f32 v158, v176, v177
	v_cvt_pk_bf16_f32 v159, v178, v179
	v_cvt_pk_bf16_f32 v160, v180, v181
	v_cvt_pk_bf16_f32 v161, v182, v183
	s_nop 1
	v_mov_b32_e32 v146, v147
	v_add_co_u32_e32 v148, vcc, s6, v150
	v_addc_co_u32_e32 v149, vcc, 0, v151, vcc
	global_store_dwordx4 v[148:149], v[158:161], off
	v_mul_f32_e32 v184, 0xbfb8aa3b, v146
	v_mul_f32_e32 v206, v146, v146
	v_pk_mul_f32 v[168:169], v[36:37], v[184:185] op_sel_hi:[1,0]
	v_pk_mul_f32 v[170:171], v[38:39], v[184:185] op_sel_hi:[1,0]
	v_pk_mul_f32 v[172:173], v[32:33], v[184:185] op_sel_hi:[1,0]
	v_pk_mul_f32 v[174:175], v[34:35], v[184:185] op_sel_hi:[1,0]
	v_exp_f32_e32 v168, v168
	v_exp_f32_e32 v169, v169
	v_exp_f32_e32 v170, v170
	v_exp_f32_e32 v171, v171
	v_exp_f32_e32 v172, v172
	v_exp_f32_e32 v173, v173
	v_exp_f32_e32 v174, v174
	v_exp_f32_e32 v175, v175
	v_pk_mul_f32 v[176:177], v[36:37], v[4:5]
	v_pk_mul_f32 v[178:179], v[38:39], v[6:7]
	v_pk_mul_f32 v[180:181], v[32:33], v[0:1]
	v_pk_mul_f32 v[182:183], v[34:35], v[2:3]
	v_pk_add_f32 v[168:169], v[168:169], 1.0 op_sel_hi:[1,0]
	v_pk_add_f32 v[170:171], v[170:171], 1.0 op_sel_hi:[1,0]
	v_pk_add_f32 v[172:173], v[172:173], 1.0 op_sel_hi:[1,0]
	v_pk_add_f32 v[174:175], v[174:175], 1.0 op_sel_hi:[1,0]
	v_rcp_f32_e32 v168, v168
	v_rcp_f32_e32 v169, v169
	v_rcp_f32_e32 v170, v170
	v_rcp_f32_e32 v171, v171
	v_rcp_f32_e32 v172, v172
	v_rcp_f32_e32 v173, v173
	v_rcp_f32_e32 v174, v174
	v_rcp_f32_e32 v175, v175
	v_pk_mul_f32 v[176:177], v[176:177], v[206:207] op_sel_hi:[1,0]
	v_pk_mul_f32 v[178:179], v[178:179], v[206:207] op_sel_hi:[1,0]
	v_pk_mul_f32 v[180:181], v[180:181], v[206:207] op_sel_hi:[1,0]
	v_pk_mul_f32 v[182:183], v[182:183], v[206:207] op_sel_hi:[1,0]
	v_pk_mul_f32 v[176:177], v[176:177], v[168:169]
	v_pk_mul_f32 v[178:179], v[178:179], v[170:171]
	v_pk_mul_f32 v[180:181], v[180:181], v[172:173]
	v_pk_mul_f32 v[182:183], v[182:183], v[174:175]
	v_cvt_pk_bf16_f32 v158, v176, v177
	v_cvt_pk_bf16_f32 v159, v178, v179
	v_cvt_pk_bf16_f32 v160, v180, v181
	v_cvt_pk_bf16_f32 v161, v182, v183
	s_nop 1
	v_add_co_u32_e32 v146, vcc, 0xf2000, v150
	s_nop 0
	v_addc_co_u32_e32 v147, vcc, 0, v151, vcc
	s_andn2_b64 vcc, exec, s[44:45]
	global_store_dwordx4 v[146:147], v[158:161], off
	s_cbranch_vccz .LBB0_73
	s_mov_b64 s[46:47], s[50:51]
	s_andn2_b64 vcc, exec, s[42:43]
	s_mov_b64 s[50:51], s[46:47]
	s_cbranch_vccnz .LBB0_74

.LBB0_103:
	s_add_u32 s6, s54, 0xfffc0080
	s_addc_u32 s19, s55, -1
	s_add_i32 s23, 0, 0x10000
	v_add_u32_e32 v146, s23, v206
	ds_read_b128 v[128:131], v146
	ds_read_b128 v[132:135], v146 offset:1024
	ds_read_b128 v[136:139], v146 offset:2048
	ds_read_b128 v[146:149], v146 offset:3072
	s_cmp_eq_u32 s12, 12
	s_cselect_b32 s69, s47, s19
	s_cselect_b32 s68, s46, s6
	s_cselect_b32 s59, s49, s11
	s_cselect_b32 s58, s48, s10
	v_lshl_add_u64 v[192:193], s[54:55], 0, v[158:159]
	s_add_i32 m0, s72, 0xc000
	ds_read_b128 v[162:165], v208
	ds_read_b128 v[166:169], v208 offset:1024
	ds_read_b128 v[170:173], v208 offset:2048
	ds_read_b128 v[174:177], v208 offset:3072
	ds_read_b128 v[178:181], v208 offset:4096
	ds_read_b128 v[182:185], v208 offset:5120
	ds_read_b128 v[194:197], v208 offset:6144
	ds_read_b128 v[210:213], v208 offset:7168
	global_load_lds_dwordx4 v[192:193], off
	v_lshl_add_u64 v[192:193], s[54:55], 0, v[160:161]
	s_add_i32 m0, s72, 0xe000
	s_nop 0
	global_load_lds_dwordx4 v[192:193], off
	s_add_i32 s6, 0, 0x14000
	v_add_u32_e32 v192, s6, v206
	ds_read_b128 v[214:217], v192
	ds_read_b128 v[218:221], v192 offset:1024
	ds_read_b128 v[222:225], v192 offset:2048
	ds_read_b128 v[226:229], v192 offset:3072
	s_nop 0
	s_waitcnt vmcnt(8)
	s_waitcnt lgkmcnt(0)
	s_barrier
	v_mfma_f32_16x16x32_bf16 v[124:127], v[128:131], v[162:165], v[124:127]
	v_mfma_f32_16x16x32_bf16 v[120:123], v[136:139], v[162:165], v[120:123]
	v_mfma_f32_16x16x32_bf16 v[108:111], v[128:131], v[170:173], v[108:111]
	v_mfma_f32_16x16x32_bf16 v[104:107], v[136:139], v[170:173], v[104:107]
	v_mfma_f32_16x16x32_bf16 v[96:99], v[128:131], v[178:181], v[96:99]
	v_mfma_f32_16x16x32_bf16 v[88:91], v[136:139], v[178:181], v[88:91]
	v_mfma_f32_16x16x32_bf16 v[84:87], v[128:131], v[194:197], v[84:87]
	v_mfma_f32_16x16x32_bf16 v[80:83], v[136:139], v[194:197], v[80:83]
	v_mfma_f32_16x16x32_bf16 v[124:127], v[132:135], v[166:169], v[124:127]
	v_mfma_f32_16x16x32_bf16 v[120:123], v[146:149], v[166:169], v[120:123]
	v_mfma_f32_16x16x32_bf16 v[108:111], v[132:135], v[174:177], v[108:111]
	v_mfma_f32_16x16x32_bf16 v[104:107], v[146:149], v[174:177], v[104:107]
	v_mfma_f32_16x16x32_bf16 v[96:99], v[132:135], v[182:185], v[96:99]
	v_mfma_f32_16x16x32_bf16 v[88:91], v[146:149], v[182:185], v[88:91]
	v_mfma_f32_16x16x32_bf16 v[84:87], v[132:135], v[210:213], v[84:87]
	v_mfma_f32_16x16x32_bf16 v[80:83], v[146:149], v[210:213], v[80:83]
	v_mfma_f32_16x16x32_bf16 v[116:119], v[214:217], v[162:165], v[116:119]
	v_mfma_f32_16x16x32_bf16 v[112:115], v[222:225], v[162:165], v[112:115]
	v_mfma_f32_16x16x32_bf16 v[100:103], v[214:217], v[170:173], v[100:103]
	v_mfma_f32_16x16x32_bf16 v[92:95], v[222:225], v[170:173], v[92:95]
	v_mfma_f32_16x16x32_bf16 v[76:79], v[214:217], v[178:181], v[76:79]
	v_mfma_f32_16x16x32_bf16 v[72:75], v[222:225], v[178:181], v[72:75]
	v_mfma_f32_16x16x32_bf16 v[68:71], v[214:217], v[194:197], v[68:71]
	v_mfma_f32_16x16x32_bf16 v[64:67], v[222:225], v[194:197], v[64:67]
	v_mfma_f32_16x16x32_bf16 v[116:119], v[218:221], v[166:169], v[116:119]
	v_mfma_f32_16x16x32_bf16 v[112:115], v[226:229], v[166:169], v[112:115]
	v_mfma_f32_16x16x32_bf16 v[100:103], v[218:221], v[174:177], v[100:103]
	v_mfma_f32_16x16x32_bf16 v[92:95], v[226:229], v[174:177], v[92:95]
	v_mfma_f32_16x16x32_bf16 v[76:79], v[218:221], v[182:185], v[76:79]
	v_mfma_f32_16x16x32_bf16 v[72:75], v[226:229], v[182:185], v[72:75]
	v_mfma_f32_16x16x32_bf16 v[68:71], v[218:221], v[210:213], v[68:71]
	v_mfma_f32_16x16x32_bf16 v[64:67], v[226:229], v[210:213], v[64:67]
	s_barrier
	s_add_i32 s19, s23, s71
	v_lshl_add_u64 v[192:193], s[58:59], 0, v[140:141]
	s_mov_b32 m0, s19
	v_lshl_add_u64 v[230:231], s[58:59], 0, v[150:151]
	global_load_lds_dwordx4 v[192:193], off
	s_add_i32 m0, s19, 0x2000
	s_nop 0
	global_load_lds_dwordx4 v[230:231], off
	s_mov_b32 m0, s72
	v_lshl_add_u64 v[232:233], s[68:69], 0, v[154:155]
	ds_read_b128 v[162:165], v208 offset:16384
	ds_read_b128 v[166:169], v208 offset:17408
	ds_read_b128 v[170:173], v208 offset:18432
	ds_read_b128 v[174:177], v208 offset:19456
	ds_read_b128 v[178:181], v208 offset:20480
	ds_read_b128 v[182:185], v208 offset:21504
	ds_read_b128 v[194:197], v208 offset:22528
	ds_read_b128 v[210:213], v208 offset:23552
	global_load_lds_dwordx4 v[232:233], off
	v_lshl_add_u64 v[234:235], s[68:69], 0, v[152:153]
	s_mov_b32 m0, s73
	s_nop 0
	global_load_lds_dwordx4 v[234:235], off
	s_add_u32 s86, s58, 0x40000
	s_addc_u32 s87, s59, 0
	s_add_i32 s6, s6, s71
	v_lshl_add_u64 v[250:251], s[86:87], 0, v[140:141]
	s_mov_b32 m0, s6
	s_nop 0
	global_load_lds_dwordx4 v[250:251], off
	v_lshl_add_u64 v[250:251], s[86:87], 0, v[150:151]
	s_add_i32 m0, s6, 0x2000
	s_nop 0
	global_load_lds_dwordx4 v[250:251], off
	s_nop 0
	s_waitcnt vmcnt(8)
	s_waitcnt lgkmcnt(0)
	s_barrier
	v_mfma_f32_16x16x32_bf16 v[60:63], v[128:131], v[162:165], v[60:63]
	v_mfma_f32_16x16x32_bf16 v[56:59], v[136:139], v[162:165], v[56:59]
	v_mfma_f32_16x16x32_bf16 v[48:51], v[128:131], v[170:173], v[48:51]
	v_mfma_f32_16x16x32_bf16 v[40:43], v[136:139], v[170:173], v[40:43]
	v_mfma_f32_16x16x32_bf16 v[32:35], v[128:131], v[178:181], v[32:35]
	v_mfma_f32_16x16x32_bf16 v[24:27], v[136:139], v[178:181], v[24:27]
	v_mfma_f32_16x16x32_bf16 v[16:19], v[128:131], v[194:197], v[16:19]
	v_mfma_f32_16x16x32_bf16 v[8:11], v[136:139], v[194:197], v[8:11]
	v_mfma_f32_16x16x32_bf16 v[60:63], v[132:135], v[166:169], v[60:63]
	v_mfma_f32_16x16x32_bf16 v[56:59], v[146:149], v[166:169], v[56:59]
	v_mfma_f32_16x16x32_bf16 v[48:51], v[132:135], v[174:177], v[48:51]
	v_mfma_f32_16x16x32_bf16 v[40:43], v[146:149], v[174:177], v[40:43]
	v_mfma_f32_16x16x32_bf16 v[32:35], v[132:135], v[182:185], v[32:35]
	v_mfma_f32_16x16x32_bf16 v[24:27], v[146:149], v[182:185], v[24:27]
	v_mfma_f32_16x16x32_bf16 v[16:19], v[132:135], v[210:213], v[16:19]
	v_mfma_f32_16x16x32_bf16 v[8:11], v[146:149], v[210:213], v[8:11]
	v_mfma_f32_16x16x32_bf16 v[52:55], v[214:217], v[162:165], v[52:55]
	v_mfma_f32_16x16x32_bf16 v[44:47], v[222:225], v[162:165], v[44:47]
	v_mfma_f32_16x16x32_bf16 v[36:39], v[214:217], v[170:173], v[36:39]
	v_mfma_f32_16x16x32_bf16 v[28:31], v[222:225], v[170:173], v[28:31]
	v_mfma_f32_16x16x32_bf16 v[20:23], v[214:217], v[178:181], v[20:23]
	v_mfma_f32_16x16x32_bf16 v[12:15], v[222:225], v[178:181], v[12:15]
	v_mfma_f32_16x16x32_bf16 v[4:7], v[214:217], v[194:197], v[4:7]
	v_mfma_f32_16x16x32_bf16 v[0:3], v[222:225], v[194:197], v[0:3]
	v_mfma_f32_16x16x32_bf16 v[52:55], v[218:221], v[166:169], v[52:55]
	v_mfma_f32_16x16x32_bf16 v[44:47], v[226:229], v[166:169], v[44:47]
	v_mfma_f32_16x16x32_bf16 v[36:39], v[218:221], v[174:177], v[36:39]
	v_mfma_f32_16x16x32_bf16 v[28:31], v[226:229], v[174:177], v[28:31]
	v_mfma_f32_16x16x32_bf16 v[20:23], v[218:221], v[182:185], v[20:23]
	v_mfma_f32_16x16x32_bf16 v[12:15], v[226:229], v[182:185], v[12:15]
	v_mfma_f32_16x16x32_bf16 v[4:7], v[218:221], v[210:213], v[4:7]
	v_mfma_f32_16x16x32_bf16 v[0:3], v[226:229], v[210:213], v[0:3]
	s_barrier
	s_add_i32 s6, 0, 0x18000
	v_add_u32_e32 v146, s6, v206
	ds_read_b128 v[128:131], v146
	ds_read_b128 v[132:135], v146 offset:1024
	ds_read_b128 v[136:139], v146 offset:2048
	ds_read_b128 v[146:149], v146 offset:3072
	s_add_u32 s68, s68, 0x40000
	s_addc_u32 s69, s69, 0
	s_mov_b32 m0, s74
	v_lshl_add_u64 v[214:215], s[68:69], 0, v[154:155]
	ds_read_b128 v[162:165], v208 offset:32768
	ds_read_b128 v[166:169], v208 offset:33792
	ds_read_b128 v[170:173], v208 offset:34816
	ds_read_b128 v[174:177], v208 offset:35840
	ds_read_b128 v[178:181], v208 offset:36864
	ds_read_b128 v[182:185], v208 offset:37888
	ds_read_b128 v[194:197], v208 offset:38912
	ds_read_b128 v[210:213], v208 offset:39936
	global_load_lds_dwordx4 v[214:215], off
	v_lshl_add_u64 v[214:215], s[68:69], 0, v[152:153]
	s_mov_b32 m0, s75
	s_nop 0
	global_load_lds_dwordx4 v[214:215], off
	s_add_i32 s19, 0, 0x1c000
	v_add_u32_e32 v209, s19, v206
	ds_read_b128 v[214:217], v209
	ds_read_b128 v[218:221], v209 offset:1024
	ds_read_b128 v[222:225], v209 offset:2048
	ds_read_b128 v[226:229], v209 offset:3072
	s_waitcnt vmcnt(8)
	s_waitcnt lgkmcnt(0)
	s_barrier
	v_mfma_f32_16x16x32_bf16 v[124:127], v[128:131], v[162:165], v[124:127]
	v_mfma_f32_16x16x32_bf16 v[120:123], v[136:139], v[162:165], v[120:123]
	v_mfma_f32_16x16x32_bf16 v[108:111], v[128:131], v[170:173], v[108:111]
	v_mfma_f32_16x16x32_bf16 v[104:107], v[136:139], v[170:173], v[104:107]
	v_mfma_f32_16x16x32_bf16 v[96:99], v[128:131], v[178:181], v[96:99]
	v_mfma_f32_16x16x32_bf16 v[88:91], v[136:139], v[178:181], v[88:91]
	v_mfma_f32_16x16x32_bf16 v[84:87], v[128:131], v[194:197], v[84:87]
	v_mfma_f32_16x16x32_bf16 v[80:83], v[136:139], v[194:197], v[80:83]
	v_mfma_f32_16x16x32_bf16 v[124:127], v[132:135], v[166:169], v[124:127]
	v_mfma_f32_16x16x32_bf16 v[120:123], v[146:149], v[166:169], v[120:123]
	v_mfma_f32_16x16x32_bf16 v[108:111], v[132:135], v[174:177], v[108:111]
	v_mfma_f32_16x16x32_bf16 v[104:107], v[146:149], v[174:177], v[104:107]
	v_mfma_f32_16x16x32_bf16 v[96:99], v[132:135], v[182:185], v[96:99]
	v_mfma_f32_16x16x32_bf16 v[88:91], v[146:149], v[182:185], v[88:91]
	v_mfma_f32_16x16x32_bf16 v[84:87], v[132:135], v[210:213], v[84:87]
	v_mfma_f32_16x16x32_bf16 v[80:83], v[146:149], v[210:213], v[80:83]
	v_mfma_f32_16x16x32_bf16 v[116:119], v[214:217], v[162:165], v[116:119]
	v_mfma_f32_16x16x32_bf16 v[112:115], v[222:225], v[162:165], v[112:115]
	v_mfma_f32_16x16x32_bf16 v[100:103], v[214:217], v[170:173], v[100:103]
	v_mfma_f32_16x16x32_bf16 v[92:95], v[222:225], v[170:173], v[92:95]
	v_mfma_f32_16x16x32_bf16 v[76:79], v[214:217], v[178:181], v[76:79]
	v_mfma_f32_16x16x32_bf16 v[72:75], v[222:225], v[178:181], v[72:75]
	v_mfma_f32_16x16x32_bf16 v[68:71], v[214:217], v[194:197], v[68:71]
	v_mfma_f32_16x16x32_bf16 v[64:67], v[222:225], v[194:197], v[64:67]
	v_mfma_f32_16x16x32_bf16 v[116:119], v[218:221], v[166:169], v[116:119]
	v_mfma_f32_16x16x32_bf16 v[112:115], v[226:229], v[166:169], v[112:115]
	v_mfma_f32_16x16x32_bf16 v[100:103], v[218:221], v[174:177], v[100:103]
	v_mfma_f32_16x16x32_bf16 v[92:95], v[226:229], v[174:177], v[92:95]
	v_mfma_f32_16x16x32_bf16 v[76:79], v[218:221], v[182:185], v[76:79]
	v_mfma_f32_16x16x32_bf16 v[72:75], v[226:229], v[182:185], v[72:75]
	v_mfma_f32_16x16x32_bf16 v[68:71], v[218:221], v[210:213], v[68:71]
	v_mfma_f32_16x16x32_bf16 v[64:67], v[226:229], v[210:213], v[64:67]
	s_barrier
	s_add_i32 s6, s6, s71
	v_lshl_add_u64 v[192:193], v[192:193], 0, s[36:37]
	s_mov_b32 m0, s6
	s_nop 0
	global_load_lds_dwordx4 v[192:193], off
	v_lshl_add_u64 v[192:193], v[230:231], 0, s[36:37]
	s_add_i32 m0, s6, 0x2000
	s_nop 0
	global_load_lds_dwordx4 v[192:193], off
	s_mov_b32 m0, s80
	v_lshl_add_u64 v[192:193], v[232:233], 0, s[36:37]
	ds_read_b128 v[162:165], v208 offset:49152
	ds_read_b128 v[166:169], v208 offset:50176
	ds_read_b128 v[170:173], v208 offset:51200
	ds_read_b128 v[174:177], v208 offset:52224
	ds_read_b128 v[178:181], v208 offset:53248
	ds_read_b128 v[182:185], v208 offset:54272
	ds_read_b128 v[194:197], v208 offset:55296
	ds_read_b128 v[210:213], v208 offset:56320
	global_load_lds_dwordx4 v[192:193], off
	v_lshl_add_u64 v[192:193], v[234:235], 0, s[36:37]
	s_mov_b32 m0, s81
	s_nop 0
	global_load_lds_dwordx4 v[192:193], off
	s_add_u32 s58, s58, 0x40080
	s_addc_u32 s59, s59, 0
	s_add_i32 s6, s19, s71
	v_lshl_add_u64 v[250:251], s[58:59], 0, v[140:141]
	s_mov_b32 m0, s6
	s_nop 0
	global_load_lds_dwordx4 v[250:251], off
	v_lshl_add_u64 v[250:251], s[58:59], 0, v[150:151]
	s_add_i32 m0, s6, 0x2000
	s_nop 0
	global_load_lds_dwordx4 v[250:251], off
	s_add_i32 s12, s12, 2
	s_add_u32 s54, s54, 0x100
	s_addc_u32 s55, s55, 0
	s_add_u32 s10, s10, 0x100
	s_addc_u32 s11, s11, 0
	s_cmp_gt_u32 s12, 13
	s_waitcnt vmcnt(8)
	s_waitcnt lgkmcnt(0)
	s_barrier
	v_mfma_f32_16x16x32_bf16 v[60:63], v[128:131], v[162:165], v[60:63]
	v_mfma_f32_16x16x32_bf16 v[56:59], v[136:139], v[162:165], v[56:59]
	v_mfma_f32_16x16x32_bf16 v[48:51], v[128:131], v[170:173], v[48:51]
	v_mfma_f32_16x16x32_bf16 v[40:43], v[136:139], v[170:173], v[40:43]
	v_mfma_f32_16x16x32_bf16 v[32:35], v[128:131], v[178:181], v[32:35]
	v_mfma_f32_16x16x32_bf16 v[24:27], v[136:139], v[178:181], v[24:27]
	v_mfma_f32_16x16x32_bf16 v[16:19], v[128:131], v[194:197], v[16:19]
	v_mfma_f32_16x16x32_bf16 v[8:11], v[136:139], v[194:197], v[8:11]
	v_mfma_f32_16x16x32_bf16 v[60:63], v[132:135], v[166:169], v[60:63]
	v_mfma_f32_16x16x32_bf16 v[56:59], v[146:149], v[166:169], v[56:59]
	v_mfma_f32_16x16x32_bf16 v[48:51], v[132:135], v[174:177], v[48:51]
	v_mfma_f32_16x16x32_bf16 v[40:43], v[146:149], v[174:177], v[40:43]
	v_mfma_f32_16x16x32_bf16 v[32:35], v[132:135], v[182:185], v[32:35]
	v_mfma_f32_16x16x32_bf16 v[24:27], v[146:149], v[182:185], v[24:27]
	v_mfma_f32_16x16x32_bf16 v[16:19], v[132:135], v[210:213], v[16:19]
	v_mfma_f32_16x16x32_bf16 v[8:11], v[146:149], v[210:213], v[8:11]
	v_mfma_f32_16x16x32_bf16 v[52:55], v[214:217], v[162:165], v[52:55]
	v_mfma_f32_16x16x32_bf16 v[44:47], v[222:225], v[162:165], v[44:47]
	v_mfma_f32_16x16x32_bf16 v[36:39], v[214:217], v[170:173], v[36:39]
	v_mfma_f32_16x16x32_bf16 v[28:31], v[222:225], v[170:173], v[28:31]
	v_mfma_f32_16x16x32_bf16 v[20:23], v[214:217], v[178:181], v[20:23]
	v_mfma_f32_16x16x32_bf16 v[12:15], v[222:225], v[178:181], v[12:15]
	v_mfma_f32_16x16x32_bf16 v[4:7], v[214:217], v[194:197], v[4:7]
	v_mfma_f32_16x16x32_bf16 v[0:3], v[222:225], v[194:197], v[0:3]
	v_mfma_f32_16x16x32_bf16 v[52:55], v[218:221], v[166:169], v[52:55]
	v_mfma_f32_16x16x32_bf16 v[44:47], v[226:229], v[166:169], v[44:47]
	v_mfma_f32_16x16x32_bf16 v[36:39], v[218:221], v[174:177], v[36:39]
	v_mfma_f32_16x16x32_bf16 v[28:31], v[226:229], v[174:177], v[28:31]
	v_mfma_f32_16x16x32_bf16 v[20:23], v[218:221], v[182:185], v[20:23]
	v_mfma_f32_16x16x32_bf16 v[12:15], v[226:229], v[182:185], v[12:15]
	v_mfma_f32_16x16x32_bf16 v[4:7], v[218:221], v[210:213], v[4:7]
	v_mfma_f32_16x16x32_bf16 v[0:3], v[226:229], v[210:213], v[0:3]
	s_barrier
	s_cbranch_scc0 .LBB0_103
	s_mov_b32 s100, 1
	s_ashr_i32 s51, s50, 31
	s_ashr_i32 s53, s52, 31
	s_lshl_b64 s[10:11], s[50:51], 13
	s_lshl_b64 s[50:51], s[52:53], 8
	s_add_u32 s10, s50, s10
	v_lshl_or_b32 v128, s85, 8, v207
	s_addc_u32 s11, s51, s11
	v_ashrrev_i32_e32 v129, 31, v128
	v_lshl_add_u64 v[168:169], s[10:11], 0, v[156:157]
	v_lshlrev_b64 v[170:171], 1, v[128:129]
	v_lshl_add_u64 v[174:175], s[26:27], 0, v[170:171]
	v_lshlrev_b64 v[172:173], 11, v[168:169]
	v_or_b32_e32 v166, 16, v168
	v_mov_b32_e32 v167, v169
	v_lshl_add_u64 v[128:129], v[174:175], 0, v[172:173]
	v_lshlrev_b64 v[176:177], 11, v[166:167]
	global_load_dwordx4 v[146:149], v[128:129], off
	global_load_dwordx4 v[182:185], v[128:129], off offset:256
	v_lshl_add_u64 v[128:129], v[174:175], 0, v[176:177]
	global_load_dwordx4 v[194:197], v[128:129], off
	global_load_dwordx4 v[210:213], v[128:129], off offset:256
	v_or_b32_e32 v164, 32, v168
	v_mov_b32_e32 v165, v169
	v_or_b32_e32 v162, 48, v168
	v_mov_b32_e32 v163, v169
	v_lshlrev_b64 v[180:181], 11, v[164:165]
	v_lshlrev_b64 v[178:179], 11, v[162:163]
	v_lshl_add_u64 v[128:129], v[174:175], 0, v[180:181]
	v_lshl_add_u64 v[130:131], v[174:175], 0, v[178:179]
	global_load_dwordx4 v[214:217], v[128:129], off
	global_load_dwordx4 v[136:139], v[128:129], off offset:256
	global_load_dwordx4 v[132:135], v[130:131], off
	s_nop 0
	global_load_dwordx4 v[128:131], v[130:131], off offset:256
	s_mov_b64 s[10:11], 0x90
	v_lshl_add_u64 v[172:173], s[28:29], 0, v[172:173]
	v_lshl_add_u64 v[172:173], v[172:173], 0, v[170:171]
	s_waitcnt vmcnt(0)
	v_lshlrev_b32_e32 v192, 16, v146
	v_and_b32_e32 v193, 0xffff0000, v146
	v_lshlrev_b32_e32 v218, 16, v148
	v_and_b32_e32 v219, 0xffff0000, v148
	v_lshlrev_b32_e32 v146, 16, v147
	v_and_b32_e32 v147, 0xffff0000, v147
	v_lshlrev_b32_e32 v148, 16, v149
	v_and_b32_e32 v149, 0xffff0000, v149
	v_lshlrev_b32_e32 v220, 16, v182
	v_and_b32_e32 v221, 0xffff0000, v182
	v_lshlrev_b32_e32 v222, 16, v184
	v_and_b32_e32 v223, 0xffff0000, v184
	v_lshlrev_b32_e32 v182, 16, v183
	v_and_b32_e32 v183, 0xffff0000, v183
	v_lshlrev_b32_e32 v184, 16, v185
	v_and_b32_e32 v185, 0xffff0000, v185
	v_pk_add_f32 v[124:125], v[124:125], v[192:193]
	v_pk_add_f32 v[126:127], v[126:127], v[146:147]
	v_pk_add_f32 v[122:123], v[122:123], v[148:149]
	v_pk_add_f32 v[116:117], v[116:117], v[220:221]
	v_pk_add_f32 v[146:147], v[112:113], v[222:223]
	v_pk_add_f32 v[118:119], v[118:119], v[182:183]
	v_pk_add_f32 v[148:149], v[114:115], v[184:185]
	v_lshlrev_b32_e32 v182, 16, v194
	v_and_b32_e32 v183, 0xffff0000, v194
	v_lshlrev_b32_e32 v184, 16, v196
	v_and_b32_e32 v185, 0xffff0000, v196
	v_lshlrev_b32_e32 v192, 16, v195
	v_and_b32_e32 v193, 0xffff0000, v195
	v_lshlrev_b32_e32 v194, 16, v197
	v_and_b32_e32 v195, 0xffff0000, v197
	v_pk_mul_f32 v[196:197], v[124:125], v[124:125]
	v_pk_add_f32 v[120:121], v[120:121], v[218:219]
	v_pk_mul_f32 v[218:219], v[126:127], v[126:127]
	v_cvt_pk_bf16_f32 v112, v124, v125
	v_cvt_pk_bf16_f32 v113, v126, v127
	v_pk_mul_f32 v[124:125], v[116:117], v[116:117]
	v_pk_mul_f32 v[126:127], v[118:119], v[118:119]
	v_pk_mul_f32 v[224:225], v[146:147], v[146:147]
	v_cvt_pk_bf16_f32 v116, v116, v117
	v_cvt_pk_bf16_f32 v117, v118, v119
	v_cvt_pk_bf16_f32 v118, v146, v147
	v_add_f32_e32 v146, v196, v197
	v_add_f32_e32 v146, v218, v146
	v_pk_mul_f32 v[220:221], v[120:121], v[120:121]
	v_add_f32_e32 v146, v219, v146
	v_add_f32_e32 v146, v220, v146
	v_pk_mul_f32 v[222:223], v[122:123], v[122:123]
	v_add_f32_e32 v146, v221, v146
	v_add_f32_e32 v146, v222, v146
	v_add_f32_e32 v146, v223, v146
	v_add_f32_e32 v124, v124, v146
	v_add_f32_e32 v124, v125, v124
	v_add_f32_e32 v124, v126, v124
	v_add_f32_e32 v124, v127, v124
	v_add_f32_e32 v124, v224, v124
	v_pk_mul_f32 v[226:227], v[148:149], v[148:149]
	v_add_f32_e32 v124, v225, v124
	v_add_f32_e32 v124, v226, v124
	v_add_f32_e32 v209, v227, v124
	v_lshlrev_b32_e32 v124, 16, v210
	v_and_b32_e32 v125, 0xffff0000, v210
	v_pk_add_f32 v[100:101], v[100:101], v[124:125]
	v_lshlrev_b32_e32 v124, 16, v212
	v_and_b32_e32 v125, 0xffff0000, v212
	v_pk_add_f32 v[124:125], v[92:93], v[124:125]
	v_lshlrev_b32_e32 v92, 16, v211
	v_and_b32_e32 v93, 0xffff0000, v211
	v_pk_add_f32 v[102:103], v[102:103], v[92:93]
	v_lshlrev_b32_e32 v92, 16, v213
	v_and_b32_e32 v93, 0xffff0000, v213
	v_pk_add_f32 v[126:127], v[94:95], v[92:93]
	v_lshlrev_b32_e32 v92, 16, v214
	v_and_b32_e32 v93, 0xffff0000, v214
	v_pk_add_f32 v[92:93], v[96:97], v[92:93]
	v_lshlrev_b32_e32 v96, 16, v217
	v_and_b32_e32 v97, 0xffff0000, v217
	v_lshlrev_b32_e32 v94, 16, v216
	v_and_b32_e32 v95, 0xffff0000, v216
	v_pk_add_f32 v[90:91], v[90:91], v[96:97]
	v_lshlrev_b32_e32 v96, 16, v136
	v_and_b32_e32 v97, 0xffff0000, v136
	v_pk_add_f32 v[88:89], v[88:89], v[94:95]
	v_lshlrev_b32_e32 v94, 16, v215
	v_and_b32_e32 v95, 0xffff0000, v215
	v_pk_add_f32 v[96:97], v[76:77], v[96:97]
	v_lshl_add_u64 v[76:77], v[168:169], 0, s[36:37]
	v_cvt_pk_bf16_f32 v114, v120, v121
	v_pk_add_f32 v[120:121], v[108:109], v[182:183]
	v_pk_add_f32 v[94:95], v[98:99], v[94:95]
	v_lshlrev_b64 v[182:183], 11, v[76:77]
	v_lshlrev_b32_e32 v98, 16, v138
	v_and_b32_e32 v99, 0xffff0000, v138
	v_pk_add_f32 v[108:109], v[104:105], v[184:185]
	v_lshl_add_u64 v[184:185], v[174:175], 0, v[182:183]
	v_pk_add_f32 v[98:99], v[72:73], v[98:99]
	v_lshlrev_b32_e32 v72, 16, v137
	v_and_b32_e32 v73, 0xffff0000, v137
	global_load_dwordx4 v[210:213], v[184:185], off
	global_load_dwordx4 v[218:221], v[184:185], off offset:256
	v_pk_add_f32 v[136:137], v[78:79], v[72:73]
	v_lshlrev_b32_e32 v72, 16, v139
	v_and_b32_e32 v73, 0xffff0000, v139
	v_pk_add_f32 v[138:139], v[74:75], v[72:73]
	v_lshlrev_b32_e32 v72, 16, v132
	v_and_b32_e32 v73, 0xffff0000, v132
	v_pk_add_f32 v[74:75], v[84:85], v[72:73]
	v_lshlrev_b32_e32 v72, 16, v134
	v_and_b32_e32 v73, 0xffff0000, v134
	v_pk_add_f32 v[78:79], v[80:81], v[72:73]
	v_lshlrev_b32_e32 v72, 16, v133
	v_and_b32_e32 v73, 0xffff0000, v133
	v_pk_add_f32 v[80:81], v[86:87], v[72:73]
	v_lshlrev_b32_e32 v72, 16, v135
	v_and_b32_e32 v73, 0xffff0000, v135
	v_pk_add_f32 v[82:83], v[82:83], v[72:73]
	v_lshl_add_u64 v[72:73], v[168:169], 0, s[10:11]
	v_lshlrev_b64 v[132:133], 11, v[72:73]
	v_lshl_add_u64 v[134:135], v[174:175], 0, v[132:133]
	v_lshlrev_b32_e32 v84, 16, v128
	v_and_b32_e32 v85, 0xffff0000, v128
	global_load_dwordx4 v[226:229], v[134:135], off
	global_load_dwordx4 v[234:237], v[134:135], off offset:256
	v_pk_add_f32 v[84:85], v[68:69], v[84:85]
	v_lshlrev_b32_e32 v68, 16, v130
	v_and_b32_e32 v69, 0xffff0000, v130
	v_pk_add_f32 v[86:87], v[64:65], v[68:69]
	v_lshlrev_b32_e32 v64, 16, v129
	v_and_b32_e32 v65, 0xffff0000, v129
	s_mov_b64 s[10:11], 0xa0
	v_pk_add_f32 v[128:129], v[70:71], v[64:65]
	v_lshl_add_u64 v[70:71], v[168:169], 0, s[10:11]
	s_mov_b64 s[10:11], 0xb0
	v_lshlrev_b32_e32 v64, 16, v131
	v_and_b32_e32 v65, 0xffff0000, v131
	v_lshlrev_b64 v[134:135], 11, v[70:71]
	v_lshl_add_u64 v[68:69], v[168:169], 0, s[10:11]
	v_pk_add_f32 v[130:131], v[66:67], v[64:65]
	v_lshl_add_u64 v[64:65], v[174:175], 0, v[134:135]
	v_lshlrev_b64 v[184:185], 11, v[68:69]
	global_load_dwordx4 v[238:241], v[64:65], off
	global_load_dwordx4 v[242:245], v[64:65], off offset:256
	v_lshl_add_u64 v[64:65], v[174:175], 0, v[184:185]
	global_load_dwordx4 v[246:249], v[64:65], off
	s_nop 0
	global_load_dwordx4 v[64:67], v[64:65], off offset:256
	v_cvt_pk_bf16_f32 v115, v122, v123
	v_cvt_pk_bf16_f32 v119, v148, v149
	v_pk_add_f32 v[110:111], v[110:111], v[192:193]
	v_pk_add_f32 v[122:123], v[106:107], v[194:195]
	global_store_dwordx4 v[172:173], v[112:115], off
	global_store_dwordx4 v[172:173], v[116:119], off offset:256
	v_cvt_pk_bf16_f32 v104, v120, v121
	v_lshl_add_u64 v[112:113], s[28:29], 0, v[176:177]
	v_cvt_pk_bf16_f32 v105, v110, v111
	v_cvt_pk_bf16_f32 v106, v108, v109
	v_cvt_pk_bf16_f32 v107, v122, v123
	v_lshl_add_u64 v[112:113], v[112:113], 0, v[170:171]
	v_cvt_pk_bf16_f32 v146, v100, v101
	v_cvt_pk_bf16_f32 v147, v102, v103
	v_cvt_pk_bf16_f32 v148, v124, v125
	v_cvt_pk_bf16_f32 v149, v126, v127
	global_store_dwordx4 v[112:113], v[104:107], off
	global_store_dwordx4 v[112:113], v[146:149], off offset:256
	v_cvt_pk_bf16_f32 v194, v92, v93
	v_lshl_add_u64 v[104:105], s[28:29], 0, v[180:181]
	v_cvt_pk_bf16_f32 v195, v94, v95
	v_cvt_pk_bf16_f32 v196, v88, v89
	v_cvt_pk_bf16_f32 v197, v90, v91
	v_lshl_add_u64 v[104:105], v[104:105], 0, v[170:171]
	v_cvt_pk_bf16_f32 v214, v96, v97
	v_cvt_pk_bf16_f32 v215, v136, v137
	v_cvt_pk_bf16_f32 v216, v98, v99
	v_cvt_pk_bf16_f32 v217, v138, v139
	global_store_dwordx4 v[104:105], v[194:197], off
	global_store_dwordx4 v[104:105], v[214:217], off offset:256
	v_lshl_add_u64 v[104:105], s[28:29], 0, v[178:179]
	v_cvt_pk_bf16_f32 v222, v74, v75
	v_cvt_pk_bf16_f32 v223, v80, v81
	v_cvt_pk_bf16_f32 v224, v78, v79
	v_cvt_pk_bf16_f32 v225, v82, v83
	v_lshl_add_u64 v[104:105], v[104:105], 0, v[170:171]
	v_cvt_pk_bf16_f32 v230, v84, v85
	v_cvt_pk_bf16_f32 v231, v128, v129
	v_cvt_pk_bf16_f32 v232, v86, v87
	v_cvt_pk_bf16_f32 v233, v130, v131
	global_store_dwordx4 v[104:105], v[222:225], off
	global_store_dwordx4 v[104:105], v[230:233], off offset:256
	s_waitcnt vmcnt(8)
	v_lshlrev_b32_e32 v104, 16, v210
	v_and_b32_e32 v105, 0xffff0000, v210
	v_pk_add_f32 v[60:61], v[60:61], v[104:105]
	v_lshlrev_b32_e32 v104, 16, v212
	v_and_b32_e32 v105, 0xffff0000, v212
	v_pk_add_f32 v[56:57], v[56:57], v[104:105]
	v_lshlrev_b32_e32 v104, 16, v211
	v_and_b32_e32 v105, 0xffff0000, v211
	v_pk_add_f32 v[62:63], v[62:63], v[104:105]
	v_lshlrev_b32_e32 v104, 16, v213
	v_and_b32_e32 v105, 0xffff0000, v213
	v_pk_add_f32 v[58:59], v[58:59], v[104:105]
	v_lshlrev_b32_e32 v104, 16, v218
	v_and_b32_e32 v105, 0xffff0000, v218
	v_pk_add_f32 v[52:53], v[52:53], v[104:105]
	v_lshlrev_b32_e32 v104, 16, v220
	v_and_b32_e32 v105, 0xffff0000, v220
	v_pk_add_f32 v[104:105], v[44:45], v[104:105]
	v_lshlrev_b32_e32 v44, 16, v219
	v_and_b32_e32 v45, 0xffff0000, v219
	v_pk_add_f32 v[54:55], v[54:55], v[44:45]
	v_lshlrev_b32_e32 v44, 16, v221
	v_and_b32_e32 v45, 0xffff0000, v221
	v_pk_add_f32 v[106:107], v[46:47], v[44:45]
	v_lshlrev_b32_e32 v44, 16, v226
	v_and_b32_e32 v45, 0xffff0000, v226
	v_pk_add_f32 v[44:45], v[48:49], v[44:45]
	v_lshlrev_b32_e32 v48, 16, v229
	v_and_b32_e32 v49, 0xffff0000, v229
	v_pk_add_f32 v[42:43], v[42:43], v[48:49]
	v_lshlrev_b32_e32 v48, 16, v234
	v_and_b32_e32 v49, 0xffff0000, v234
	v_pk_add_f32 v[36:37], v[36:37], v[48:49]
	v_lshlrev_b32_e32 v48, 16, v236
	v_and_b32_e32 v49, 0xffff0000, v236
	v_lshlrev_b32_e32 v46, 16, v228
	v_and_b32_e32 v47, 0xffff0000, v228
	v_pk_add_f32 v[48:49], v[28:29], v[48:49]
	v_lshlrev_b32_e32 v28, 16, v235
	v_and_b32_e32 v29, 0xffff0000, v235
	v_pk_add_f32 v[40:41], v[40:41], v[46:47]
	v_lshlrev_b32_e32 v46, 16, v227
	v_and_b32_e32 v47, 0xffff0000, v227
	v_pk_add_f32 v[38:39], v[38:39], v[28:29]
	v_lshlrev_b32_e32 v28, 16, v237
	v_and_b32_e32 v29, 0xffff0000, v237
	v_pk_add_f32 v[46:47], v[50:51], v[46:47]
	v_pk_add_f32 v[50:51], v[30:31], v[28:29]
	v_lshlrev_b32_e32 v28, 16, v238
	v_and_b32_e32 v29, 0xffff0000, v238
	v_lshlrev_b32_e32 v180, 16, v64
	v_and_b32_e32 v181, 0xffff0000, v64
	v_pk_add_f32 v[28:29], v[32:33], v[28:29]
	v_lshlrev_b32_e32 v32, 16, v241
	v_and_b32_e32 v33, 0xffff0000, v241
	v_pk_add_f32 v[4:5], v[4:5], v[180:181]
	v_lshlrev_b32_e32 v180, 16, v66
	v_and_b32_e32 v181, 0xffff0000, v66
	v_pk_add_f32 v[26:27], v[26:27], v[32:33]
	v_lshlrev_b32_e32 v32, 16, v242
	v_and_b32_e32 v33, 0xffff0000, v242
	v_pk_add_f32 v[0:1], v[0:1], v[180:181]
	v_lshl_add_u64 v[180:181], s[28:29], 0, v[182:183]
	v_cvt_pk_bf16_f32 v112, v60, v61
	v_cvt_pk_bf16_f32 v113, v62, v63
	v_cvt_pk_bf16_f32 v114, v56, v57
	v_cvt_pk_bf16_f32 v115, v58, v59
	v_pk_add_f32 v[20:21], v[20:21], v[32:33]
	v_lshlrev_b32_e32 v32, 16, v244
	v_and_b32_e32 v33, 0xffff0000, v244
	v_lshl_add_u64 v[180:181], v[180:181], 0, v[170:171]
	v_cvt_pk_bf16_f32 v116, v52, v53
	v_cvt_pk_bf16_f32 v117, v54, v55
	v_cvt_pk_bf16_f32 v118, v104, v105
	v_cvt_pk_bf16_f32 v119, v106, v107
	v_lshlrev_b32_e32 v30, 16, v240
	v_and_b32_e32 v31, 0xffff0000, v240
	v_pk_add_f32 v[32:33], v[12:13], v[32:33]
	v_lshlrev_b32_e32 v12, 16, v243
	v_and_b32_e32 v13, 0xffff0000, v243
	global_store_dwordx4 v[180:181], v[112:115], off
	global_store_dwordx4 v[180:181], v[116:119], off offset:256
	v_cvt_pk_bf16_f32 v146, v44, v45
	v_lshl_add_u64 v[112:113], s[28:29], 0, v[132:133]
	v_cvt_pk_bf16_f32 v147, v46, v47
	v_cvt_pk_bf16_f32 v148, v40, v41
	v_cvt_pk_bf16_f32 v149, v42, v43
	v_pk_add_f32 v[24:25], v[24:25], v[30:31]
	v_lshlrev_b32_e32 v30, 16, v239
	v_and_b32_e32 v31, 0xffff0000, v239
	v_pk_add_f32 v[22:23], v[22:23], v[12:13]
	v_lshlrev_b32_e32 v12, 16, v245
	v_and_b32_e32 v13, 0xffff0000, v245
	v_lshl_add_u64 v[112:113], v[112:113], 0, v[170:171]
	v_cvt_pk_bf16_f32 v172, v36, v37
	v_cvt_pk_bf16_f32 v173, v38, v39
	v_cvt_pk_bf16_f32 v174, v48, v49
	v_cvt_pk_bf16_f32 v175, v50, v51
	v_pk_add_f32 v[30:31], v[34:35], v[30:31]
	v_pk_add_f32 v[34:35], v[14:15], v[12:13]
	v_lshlrev_b32_e32 v12, 16, v246
	v_and_b32_e32 v13, 0xffff0000, v246
	v_lshlrev_b32_e32 v14, 16, v248
	v_and_b32_e32 v15, 0xffff0000, v248
	global_store_dwordx4 v[112:113], v[146:149], off
	global_store_dwordx4 v[112:113], v[172:175], off offset:256
	v_lshl_add_u64 v[112:113], s[28:29], 0, v[134:135]
	v_cvt_pk_bf16_f32 v176, v28, v29
	v_cvt_pk_bf16_f32 v177, v30, v31
	v_cvt_pk_bf16_f32 v178, v24, v25
	v_cvt_pk_bf16_f32 v179, v26, v27
	v_pk_add_f32 v[12:13], v[16:17], v[12:13]
	v_pk_add_f32 v[8:9], v[8:9], v[14:15]
	v_lshlrev_b32_e32 v14, 16, v247
	v_and_b32_e32 v15, 0xffff0000, v247
	v_lshlrev_b32_e32 v16, 16, v249
	v_and_b32_e32 v17, 0xffff0000, v249
	v_lshlrev_b32_e32 v64, 16, v65
	v_and_b32_e32 v65, 0xffff0000, v65
	v_lshl_add_u64 v[112:113], v[112:113], 0, v[170:171]
	v_cvt_pk_bf16_f32 v194, v20, v21
	v_cvt_pk_bf16_f32 v195, v22, v23
	v_cvt_pk_bf16_f32 v196, v32, v33
	v_cvt_pk_bf16_f32 v197, v34, v35
	v_pk_add_f32 v[14:15], v[18:19], v[14:15]
	v_pk_add_f32 v[10:11], v[10:11], v[16:17]
	v_pk_add_f32 v[6:7], v[6:7], v[64:65]
	v_lshlrev_b32_e32 v64, 16, v67
	v_and_b32_e32 v65, 0xffff0000, v67
	global_store_dwordx4 v[112:113], v[176:179], off
	global_store_dwordx4 v[112:113], v[194:197], off offset:256
	v_lshl_add_u64 v[112:113], s[28:29], 0, v[184:185]
	v_cvt_pk_bf16_f32 v16, v12, v13
	v_cvt_pk_bf16_f32 v17, v14, v15
	v_cvt_pk_bf16_f32 v18, v8, v9
	v_cvt_pk_bf16_f32 v19, v10, v11
	v_pk_add_f32 v[2:3], v[2:3], v[64:65]
	v_lshl_add_u64 v[112:113], v[112:113], 0, v[170:171]
	v_cvt_pk_bf16_f32 v64, v4, v5
	v_cvt_pk_bf16_f32 v65, v6, v7
	v_cvt_pk_bf16_f32 v66, v0, v1
	v_cvt_pk_bf16_f32 v67, v2, v3
	global_store_dwordx4 v[112:113], v[16:19], off
	global_store_dwordx4 v[112:113], v[64:67], off offset:256
	s_lshl_b32 s10, s85, 2
	v_and_b32_e32 v17, 64, v188
	v_xor_b32_e32 v16, 16, v188
	v_add_u32_e32 v17, 64, v17
	v_cmp_lt_i32_e32 vcc, v16, v17
	v_xor_b32_e32 v18, 32, v188
	s_ashr_i32 s11, s10, 31
	v_cndmask_b32_e32 v16, v188, v16, vcc
	v_lshlrev_b32_e32 v16, 2, v16
	v_mov_b32_e32 v132, v209
	v_cmp_lt_i32_e32 vcc, v18, v17
	s_lshl_b64 s[10:11], s[10:11], 2
	s_add_u32 s50, s83, s10
	v_cndmask_b32_e32 v17, v188, v18, vcc
	v_lshlrev_b32_e32 v17, 2, v17
	s_addc_u32 s51, s84, s11
	v_pk_mul_f32 v[18:19], v[120:121], v[120:121]
	v_pk_mul_f32 v[64:65], v[110:111], v[110:111]
	v_add_f32_e32 v18, v18, v19
	v_add_f32_e32 v18, v64, v18
	v_pk_mul_f32 v[66:67], v[108:109], v[108:109]
	v_add_f32_e32 v18, v65, v18
	v_add_f32_e32 v18, v66, v18
	v_pk_mul_f32 v[108:109], v[122:123], v[122:123]
	v_add_f32_e32 v18, v67, v18
	v_add_f32_e32 v18, v108, v18
	v_pk_mul_f32 v[100:101], v[100:101], v[100:101]
	v_add_f32_e32 v18, v109, v18
	v_add_f32_e32 v18, v100, v18
	v_pk_mul_f32 v[102:103], v[102:103], v[102:103]
	v_add_f32_e32 v18, v101, v18
	v_add_f32_e32 v18, v102, v18
	v_pk_mul_f32 v[110:111], v[124:125], v[124:125]
	v_add_f32_e32 v18, v103, v18
	v_add_f32_e32 v18, v110, v18
	v_pk_mul_f32 v[112:113], v[126:127], v[126:127]
	v_add_f32_e32 v18, v111, v18
	v_add_f32_e32 v18, v112, v18
	v_add_f32_e32 v18, v113, v18
	v_mov_b32_e32 v133, v18
	v_pk_mul_f32 v[18:19], v[92:93], v[92:93]
	v_pk_mul_f32 v[64:65], v[94:95], v[94:95]
	v_add_f32_e32 v18, v18, v19
	v_add_f32_e32 v18, v64, v18
	v_pk_mul_f32 v[66:67], v[88:89], v[88:89]
	v_add_f32_e32 v18, v65, v18
	v_add_f32_e32 v18, v66, v18
	v_pk_mul_f32 v[88:89], v[90:91], v[90:91]
	v_add_f32_e32 v18, v67, v18
	v_add_f32_e32 v18, v88, v18
	v_pk_mul_f32 v[90:91], v[96:97], v[96:97]
	v_add_f32_e32 v18, v89, v18
	v_add_f32_e32 v18, v90, v18
	v_pk_mul_f32 v[92:93], v[136:137], v[136:137]
	v_add_f32_e32 v18, v91, v18
	v_add_f32_e32 v18, v92, v18
	v_pk_mul_f32 v[94:95], v[98:99], v[98:99]
	v_add_f32_e32 v18, v93, v18
	v_add_f32_e32 v18, v94, v18
	v_pk_mul_f32 v[96:97], v[138:139], v[138:139]
	v_add_f32_e32 v18, v95, v18
	v_add_f32_e32 v18, v96, v18
	v_add_f32_e32 v18, v97, v18
	v_mov_b32_e32 v134, v18
	v_pk_mul_f32 v[18:19], v[74:75], v[74:75]
	v_pk_mul_f32 v[192:193], v[60:61], v[60:61]
	v_pk_mul_f32 v[64:65], v[80:81], v[80:81]
	v_pk_mul_f32 v[60:61], v[62:63], v[62:63]
	v_add_f32_e32 v18, v18, v19
	v_add_f32_e32 v192, v192, v193
	v_add_f32_e32 v18, v64, v18
	v_add_f32_e32 v192, v60, v192
	v_pk_mul_f32 v[66:67], v[78:79], v[78:79]
	v_pk_mul_f32 v[56:57], v[56:57], v[56:57]
	v_add_f32_e32 v18, v65, v18
	v_add_f32_e32 v192, v61, v192
	v_add_f32_e32 v18, v66, v18
	v_add_f32_e32 v192, v56, v192
	v_pk_mul_f32 v[74:75], v[82:83], v[82:83]
	v_pk_mul_f32 v[58:59], v[58:59], v[58:59]
	v_add_f32_e32 v18, v67, v18
	v_add_f32_e32 v192, v57, v192
	v_add_f32_e32 v18, v74, v18
	v_add_f32_e32 v192, v58, v192
	v_pk_mul_f32 v[78:79], v[84:85], v[84:85]
	v_pk_mul_f32 v[52:53], v[52:53], v[52:53]
	v_add_f32_e32 v18, v75, v18
	v_add_f32_e32 v192, v59, v192
	v_add_f32_e32 v18, v78, v18
	v_add_f32_e32 v192, v52, v192
	v_pk_mul_f32 v[80:81], v[128:129], v[128:129]
	v_pk_mul_f32 v[54:55], v[54:55], v[54:55]
	v_add_f32_e32 v18, v79, v18
	v_add_f32_e32 v192, v53, v192
	v_add_f32_e32 v18, v80, v18
	v_add_f32_e32 v192, v54, v192
	v_pk_mul_f32 v[82:83], v[86:87], v[86:87]
	v_pk_mul_f32 v[62:63], v[104:105], v[104:105]
	v_add_f32_e32 v18, v81, v18
	v_add_f32_e32 v192, v55, v192
	v_add_f32_e32 v18, v82, v18
	v_add_f32_e32 v192, v62, v192
	v_pk_mul_f32 v[84:85], v[130:131], v[130:131]
	v_pk_mul_f32 v[210:211], v[106:107], v[106:107]
	v_add_f32_e32 v18, v83, v18
	v_add_f32_e32 v192, v63, v192
	v_add_f32_e32 v18, v84, v18
	v_add_f32_e32 v192, v210, v192
	v_add_f32_e32 v18, v85, v18
	v_add_f32_e32 v192, v211, v192
	v_mov_b32_e32 v135, v18
	v_mov_b32_e32 v146, v192
	v_pk_mul_f32 v[18:19], v[44:45], v[44:45]
	v_pk_mul_f32 v[192:193], v[28:29], v[28:29]
	v_pk_mul_f32 v[44:45], v[46:47], v[46:47]
	v_pk_mul_f32 v[28:29], v[30:31], v[30:31]
	v_add_f32_e32 v18, v18, v19
	v_add_f32_e32 v192, v192, v193
	v_add_f32_e32 v18, v44, v18
	v_add_f32_e32 v192, v28, v192
	v_pk_mul_f32 v[40:41], v[40:41], v[40:41]
	v_pk_mul_f32 v[24:25], v[24:25], v[24:25]
	v_add_f32_e32 v18, v45, v18
	v_add_f32_e32 v192, v29, v192
	v_add_f32_e32 v18, v40, v18
	v_add_f32_e32 v192, v24, v192
	v_pk_mul_f32 v[42:43], v[42:43], v[42:43]
	v_pk_mul_f32 v[26:27], v[26:27], v[26:27]
	v_add_f32_e32 v18, v41, v18
	v_add_f32_e32 v192, v25, v192
	v_add_f32_e32 v18, v42, v18
	v_add_f32_e32 v192, v26, v192
	v_pk_mul_f32 v[36:37], v[36:37], v[36:37]
	v_pk_mul_f32 v[20:21], v[20:21], v[20:21]
	v_add_f32_e32 v18, v43, v18
	v_add_f32_e32 v192, v27, v192
	v_add_f32_e32 v18, v36, v18
	v_add_f32_e32 v192, v20, v192
	v_pk_mul_f32 v[38:39], v[38:39], v[38:39]
	v_pk_mul_f32 v[22:23], v[22:23], v[22:23]
	v_add_f32_e32 v18, v37, v18
	v_add_f32_e32 v192, v21, v192
	v_add_f32_e32 v18, v38, v18
	v_add_f32_e32 v192, v22, v192
	v_pk_mul_f32 v[46:47], v[48:49], v[48:49]
	v_pk_mul_f32 v[30:31], v[32:33], v[32:33]
	v_add_f32_e32 v18, v39, v18
	v_add_f32_e32 v192, v23, v192
	v_add_f32_e32 v18, v46, v18
	v_add_f32_e32 v192, v30, v192
	v_pk_mul_f32 v[48:49], v[50:51], v[50:51]
	v_pk_mul_f32 v[32:33], v[34:35], v[34:35]
	v_add_f32_e32 v18, v47, v18
	v_add_f32_e32 v192, v31, v192
	v_add_f32_e32 v18, v48, v18
	v_add_f32_e32 v192, v32, v192
	v_add_f32_e32 v18, v49, v18
	v_add_f32_e32 v192, v33, v192
	v_mov_b32_e32 v147, v18
	v_mov_b32_e32 v148, v192
	v_pk_mul_f32 v[12:13], v[12:13], v[12:13]
	v_pk_mul_f32 v[14:15], v[14:15], v[14:15]
	v_add_f32_e32 v12, v12, v13
	v_add_f32_e32 v12, v14, v12
	v_pk_mul_f32 v[8:9], v[8:9], v[8:9]
	v_add_f32_e32 v12, v15, v12
	v_add_f32_e32 v8, v8, v12
	v_pk_mul_f32 v[10:11], v[10:11], v[10:11]
	v_add_f32_e32 v8, v9, v8
	v_add_f32_e32 v8, v10, v8
	v_pk_mul_f32 v[4:5], v[4:5], v[4:5]
	v_add_f32_e32 v8, v11, v8
	v_add_f32_e32 v4, v4, v8
	v_pk_mul_f32 v[6:7], v[6:7], v[6:7]
	v_add_f32_e32 v4, v5, v4
	v_add_f32_e32 v4, v6, v4
	v_pk_mul_f32 v[0:1], v[0:1], v[0:1]
	v_add_f32_e32 v4, v7, v4
	v_add_f32_e32 v0, v0, v4
	v_pk_mul_f32 v[2:3], v[2:3], v[2:3]
	v_add_f32_e32 v0, v1, v0
	v_add_f32_e32 v0, v2, v0
	v_add_f32_e32 v0, v3, v0
	v_mov_b32_e32 v149, v0
	ds_bpermute_b32 v172, v16, v132
	ds_bpermute_b32 v173, v16, v133
	ds_bpermute_b32 v174, v16, v134
	ds_bpermute_b32 v175, v16, v135
	ds_bpermute_b32 v180, v16, v146
	ds_bpermute_b32 v181, v16, v147
	ds_bpermute_b32 v182, v16, v148
	ds_bpermute_b32 v183, v16, v149
	s_waitcnt lgkmcnt(0)
	v_add_f32_e32 v132, v132, v172
	v_add_f32_e32 v133, v133, v173
	v_add_f32_e32 v134, v134, v174
	v_add_f32_e32 v135, v135, v175
	v_add_f32_e32 v146, v146, v180
	v_add_f32_e32 v147, v147, v181
	v_add_f32_e32 v148, v148, v182
	v_add_f32_e32 v149, v149, v183
	ds_bpermute_b32 v172, v17, v132
	ds_bpermute_b32 v173, v17, v133
	ds_bpermute_b32 v174, v17, v134
	ds_bpermute_b32 v175, v17, v135
	ds_bpermute_b32 v180, v17, v146
	ds_bpermute_b32 v181, v17, v147
	ds_bpermute_b32 v182, v17, v148
	ds_bpermute_b32 v183, v17, v149
	s_and_saveexec_b64 s[52:53], s[42:43]
	s_cbranch_execz .LBB0_91
	s_waitcnt lgkmcnt(0)
	v_add_f32_e32 v132, v132, v172
	v_lshlrev_b64 v[18:19], 6, v[168:169]
	v_lshl_add_u64 v[18:19], s[50:51], 0, v[18:19]
	global_store_dword v[18:19], v132, off
	v_add_f32_e32 v133, v133, v173
	v_lshlrev_b64 v[18:19], 6, v[166:167]
	v_lshl_add_u64 v[18:19], s[50:51], 0, v[18:19]
	global_store_dword v[18:19], v133, off
	v_add_f32_e32 v134, v134, v174
	v_lshlrev_b64 v[18:19], 6, v[164:165]
	v_lshl_add_u64 v[18:19], s[50:51], 0, v[18:19]
	global_store_dword v[18:19], v134, off
	v_add_f32_e32 v135, v135, v175
	v_lshlrev_b64 v[18:19], 6, v[162:163]
	v_lshl_add_u64 v[18:19], s[50:51], 0, v[18:19]
	global_store_dword v[18:19], v135, off
	v_add_f32_e32 v146, v146, v180
	v_lshlrev_b64 v[18:19], 6, v[76:77]
	v_lshl_add_u64 v[18:19], s[50:51], 0, v[18:19]
	global_store_dword v[18:19], v146, off
	v_add_f32_e32 v147, v147, v181
	v_lshlrev_b64 v[18:19], 6, v[72:73]
	v_lshl_add_u64 v[18:19], s[50:51], 0, v[18:19]
	global_store_dword v[18:19], v147, off
	v_add_f32_e32 v148, v148, v182
	v_lshlrev_b64 v[18:19], 6, v[70:71]
	v_lshl_add_u64 v[18:19], s[50:51], 0, v[18:19]
	global_store_dword v[18:19], v148, off
	v_add_f32_e32 v149, v149, v183
	v_lshlrev_b64 v[18:19], 6, v[68:69]
	v_lshl_add_u64 v[18:19], s[50:51], 0, v[18:19]
	global_store_dword v[18:19], v149, off
	s_branch .LBB0_91

.LBB0_248:
	s_add_u32 s6, s52, 0xfffc0080
	s_addc_u32 s19, s53, -1
	s_add_i32 s23, 0, 0x10000
	v_add_u32_e32 v146, s23, v206
	ds_read_b128 v[128:131], v146
	ds_read_b128 v[132:135], v146 offset:1024
	ds_read_b128 v[136:139], v146 offset:2048
	ds_read_b128 v[146:149], v146 offset:3072
	s_cmp_eq_u32 s82, 12
	s_cselect_b32 s59, s10, s19
	s_cselect_b32 s58, s11, s6
	s_cselect_b32 s55, s12, s51
	s_cselect_b32 s54, s35, s39
	v_lshl_add_u64 v[214:215], s[52:53], 0, v[158:159]
	s_add_i32 m0, s68, 0xc000
	ds_read_b128 v[162:165], v208
	ds_read_b128 v[166:169], v208 offset:1024
	ds_read_b128 v[170:173], v208 offset:2048
	ds_read_b128 v[174:177], v208 offset:3072
	ds_read_b128 v[178:181], v208 offset:4096
	ds_read_b128 v[182:185], v208 offset:5120
	ds_read_b128 v[194:197], v208 offset:6144
	ds_read_b128 v[210:213], v208 offset:7168
	global_load_lds_dwordx4 v[214:215], off
	v_lshl_add_u64 v[214:215], s[52:53], 0, v[160:161]
	s_add_i32 m0, s68, 0xe000
	s_nop 0
	global_load_lds_dwordx4 v[214:215], off
	s_add_i32 s6, 0, 0x14000
	v_add_u32_e32 v192, s6, v206
	ds_read_b128 v[214:217], v192
	ds_read_b128 v[218:221], v192 offset:1024
	ds_read_b128 v[222:225], v192 offset:2048
	ds_read_b128 v[226:229], v192 offset:3072
	s_nop 0
	s_waitcnt vmcnt(8)
	s_waitcnt lgkmcnt(0)
	s_barrier
	v_mfma_f32_16x16x32_bf16 v[124:127], v[128:131], v[162:165], v[124:127]
	v_mfma_f32_16x16x32_bf16 v[120:123], v[136:139], v[162:165], v[120:123]
	v_mfma_f32_16x16x32_bf16 v[108:111], v[128:131], v[170:173], v[108:111]
	v_mfma_f32_16x16x32_bf16 v[104:107], v[136:139], v[170:173], v[104:107]
	v_mfma_f32_16x16x32_bf16 v[96:99], v[128:131], v[178:181], v[96:99]
	v_mfma_f32_16x16x32_bf16 v[88:91], v[136:139], v[178:181], v[88:91]
	v_mfma_f32_16x16x32_bf16 v[84:87], v[128:131], v[194:197], v[84:87]
	v_mfma_f32_16x16x32_bf16 v[80:83], v[136:139], v[194:197], v[80:83]
	v_mfma_f32_16x16x32_bf16 v[124:127], v[132:135], v[166:169], v[124:127]
	v_mfma_f32_16x16x32_bf16 v[120:123], v[146:149], v[166:169], v[120:123]
	v_mfma_f32_16x16x32_bf16 v[108:111], v[132:135], v[174:177], v[108:111]
	v_mfma_f32_16x16x32_bf16 v[104:107], v[146:149], v[174:177], v[104:107]
	v_mfma_f32_16x16x32_bf16 v[96:99], v[132:135], v[182:185], v[96:99]
	v_mfma_f32_16x16x32_bf16 v[88:91], v[146:149], v[182:185], v[88:91]
	v_mfma_f32_16x16x32_bf16 v[84:87], v[132:135], v[210:213], v[84:87]
	v_mfma_f32_16x16x32_bf16 v[80:83], v[146:149], v[210:213], v[80:83]
	v_mfma_f32_16x16x32_bf16 v[116:119], v[214:217], v[162:165], v[116:119]
	v_mfma_f32_16x16x32_bf16 v[112:115], v[222:225], v[162:165], v[112:115]
	v_mfma_f32_16x16x32_bf16 v[100:103], v[214:217], v[170:173], v[100:103]
	v_mfma_f32_16x16x32_bf16 v[92:95], v[222:225], v[170:173], v[92:95]
	v_mfma_f32_16x16x32_bf16 v[76:79], v[214:217], v[178:181], v[76:79]
	v_mfma_f32_16x16x32_bf16 v[72:75], v[222:225], v[178:181], v[72:75]
	v_mfma_f32_16x16x32_bf16 v[68:71], v[214:217], v[194:197], v[68:71]
	v_mfma_f32_16x16x32_bf16 v[64:67], v[222:225], v[194:197], v[64:67]
	v_mfma_f32_16x16x32_bf16 v[116:119], v[218:221], v[166:169], v[116:119]
	v_mfma_f32_16x16x32_bf16 v[112:115], v[226:229], v[166:169], v[112:115]
	v_mfma_f32_16x16x32_bf16 v[100:103], v[218:221], v[174:177], v[100:103]
	v_mfma_f32_16x16x32_bf16 v[92:95], v[226:229], v[174:177], v[92:95]
	v_mfma_f32_16x16x32_bf16 v[76:79], v[218:221], v[182:185], v[76:79]
	v_mfma_f32_16x16x32_bf16 v[72:75], v[226:229], v[182:185], v[72:75]
	v_mfma_f32_16x16x32_bf16 v[68:71], v[218:221], v[210:213], v[68:71]
	v_mfma_f32_16x16x32_bf16 v[64:67], v[226:229], v[210:213], v[64:67]
	s_barrier
	s_add_i32 s19, s23, s57
	v_lshl_add_u64 v[230:231], s[54:55], 0, v[140:141]
	s_mov_b32 m0, s19
	s_nop 0
	global_load_lds_dwordx4 v[230:231], off
	v_lshl_add_u64 v[232:233], s[54:55], 0, v[150:151]
	s_add_i32 m0, s19, 0x2000
	s_nop 0
	global_load_lds_dwordx4 v[232:233], off
	s_mov_b32 m0, s68
	v_lshl_add_u64 v[234:235], s[58:59], 0, v[154:155]
	ds_read_b128 v[162:165], v208 offset:16384
	ds_read_b128 v[166:169], v208 offset:17408
	ds_read_b128 v[170:173], v208 offset:18432
	ds_read_b128 v[174:177], v208 offset:19456
	ds_read_b128 v[178:181], v208 offset:20480
	ds_read_b128 v[182:185], v208 offset:21504
	ds_read_b128 v[194:197], v208 offset:22528
	ds_read_b128 v[210:213], v208 offset:23552
	global_load_lds_dwordx4 v[234:235], off
	v_lshl_add_u64 v[236:237], s[58:59], 0, v[152:153]
	s_mov_b32 m0, s69
	s_nop 0
	global_load_lds_dwordx4 v[236:237], off
	s_add_u32 s84, s54, 0x40000
	s_addc_u32 s85, s55, 0
	s_add_i32 s6, s6, s57
	v_lshl_add_u64 v[250:251], s[84:85], 0, v[140:141]
	s_mov_b32 m0, s6
	s_nop 0
	global_load_lds_dwordx4 v[250:251], off
	v_lshl_add_u64 v[250:251], s[84:85], 0, v[150:151]
	s_add_i32 m0, s6, 0x2000
	s_nop 0
	global_load_lds_dwordx4 v[250:251], off
	s_waitcnt vmcnt(8)
	s_waitcnt lgkmcnt(0)
	s_barrier
	v_mfma_f32_16x16x32_bf16 v[60:63], v[128:131], v[162:165], v[60:63]
	v_mfma_f32_16x16x32_bf16 v[56:59], v[136:139], v[162:165], v[56:59]
	v_mfma_f32_16x16x32_bf16 v[48:51], v[128:131], v[170:173], v[48:51]
	v_mfma_f32_16x16x32_bf16 v[40:43], v[136:139], v[170:173], v[40:43]
	v_mfma_f32_16x16x32_bf16 v[32:35], v[128:131], v[178:181], v[32:35]
	v_mfma_f32_16x16x32_bf16 v[24:27], v[136:139], v[178:181], v[24:27]
	v_mfma_f32_16x16x32_bf16 v[16:19], v[128:131], v[194:197], v[16:19]
	v_mfma_f32_16x16x32_bf16 v[8:11], v[136:139], v[194:197], v[8:11]
	v_mfma_f32_16x16x32_bf16 v[60:63], v[132:135], v[166:169], v[60:63]
	v_mfma_f32_16x16x32_bf16 v[56:59], v[146:149], v[166:169], v[56:59]
	v_mfma_f32_16x16x32_bf16 v[48:51], v[132:135], v[174:177], v[48:51]
	v_mfma_f32_16x16x32_bf16 v[40:43], v[146:149], v[174:177], v[40:43]
	v_mfma_f32_16x16x32_bf16 v[32:35], v[132:135], v[182:185], v[32:35]
	v_mfma_f32_16x16x32_bf16 v[24:27], v[146:149], v[182:185], v[24:27]
	v_mfma_f32_16x16x32_bf16 v[16:19], v[132:135], v[210:213], v[16:19]
	v_mfma_f32_16x16x32_bf16 v[8:11], v[146:149], v[210:213], v[8:11]
	v_mfma_f32_16x16x32_bf16 v[52:55], v[214:217], v[162:165], v[52:55]
	v_mfma_f32_16x16x32_bf16 v[44:47], v[222:225], v[162:165], v[44:47]
	v_mfma_f32_16x16x32_bf16 v[36:39], v[214:217], v[170:173], v[36:39]
	v_mfma_f32_16x16x32_bf16 v[28:31], v[222:225], v[170:173], v[28:31]
	v_mfma_f32_16x16x32_bf16 v[20:23], v[214:217], v[178:181], v[20:23]
	v_mfma_f32_16x16x32_bf16 v[12:15], v[222:225], v[178:181], v[12:15]
	v_mfma_f32_16x16x32_bf16 v[4:7], v[214:217], v[194:197], v[4:7]
	v_mfma_f32_16x16x32_bf16 v[0:3], v[222:225], v[194:197], v[0:3]
	v_mfma_f32_16x16x32_bf16 v[52:55], v[218:221], v[166:169], v[52:55]
	v_mfma_f32_16x16x32_bf16 v[44:47], v[226:229], v[166:169], v[44:47]
	v_mfma_f32_16x16x32_bf16 v[36:39], v[218:221], v[174:177], v[36:39]
	v_mfma_f32_16x16x32_bf16 v[28:31], v[226:229], v[174:177], v[28:31]
	v_mfma_f32_16x16x32_bf16 v[20:23], v[218:221], v[182:185], v[20:23]
	v_mfma_f32_16x16x32_bf16 v[12:15], v[226:229], v[182:185], v[12:15]
	v_mfma_f32_16x16x32_bf16 v[4:7], v[218:221], v[210:213], v[4:7]
	v_mfma_f32_16x16x32_bf16 v[0:3], v[226:229], v[210:213], v[0:3]
	s_barrier
	s_add_i32 s6, 0, 0x18000
	v_add_u32_e32 v146, s6, v206
	ds_read_b128 v[128:131], v146
	ds_read_b128 v[132:135], v146 offset:1024
	ds_read_b128 v[136:139], v146 offset:2048
	ds_read_b128 v[146:149], v146 offset:3072
	s_add_u32 s58, s58, 0x40000
	s_addc_u32 s59, s59, 0
	s_mov_b32 m0, s70
	v_lshl_add_u64 v[214:215], s[58:59], 0, v[154:155]
	ds_read_b128 v[162:165], v208 offset:32768
	ds_read_b128 v[166:169], v208 offset:33792
	ds_read_b128 v[170:173], v208 offset:34816
	ds_read_b128 v[174:177], v208 offset:35840
	ds_read_b128 v[178:181], v208 offset:36864
	ds_read_b128 v[182:185], v208 offset:37888
	ds_read_b128 v[194:197], v208 offset:38912
	ds_read_b128 v[210:213], v208 offset:39936
	global_load_lds_dwordx4 v[214:215], off
	v_lshl_add_u64 v[214:215], s[58:59], 0, v[152:153]
	s_mov_b32 m0, s71
	s_nop 0
	global_load_lds_dwordx4 v[214:215], off
	s_add_i32 s19, 0, 0x1c000
	v_add_u32_e32 v192, s19, v206
	ds_read_b128 v[214:217], v192
	ds_read_b128 v[218:221], v192 offset:1024
	ds_read_b128 v[222:225], v192 offset:2048
	ds_read_b128 v[226:229], v192 offset:3072
	s_waitcnt vmcnt(8)
	s_waitcnt lgkmcnt(0)
	s_barrier
	v_mfma_f32_16x16x32_bf16 v[124:127], v[128:131], v[162:165], v[124:127]
	v_mfma_f32_16x16x32_bf16 v[120:123], v[136:139], v[162:165], v[120:123]
	v_mfma_f32_16x16x32_bf16 v[108:111], v[128:131], v[170:173], v[108:111]
	v_mfma_f32_16x16x32_bf16 v[104:107], v[136:139], v[170:173], v[104:107]
	v_mfma_f32_16x16x32_bf16 v[96:99], v[128:131], v[178:181], v[96:99]
	v_mfma_f32_16x16x32_bf16 v[88:91], v[136:139], v[178:181], v[88:91]
	v_mfma_f32_16x16x32_bf16 v[84:87], v[128:131], v[194:197], v[84:87]
	v_mfma_f32_16x16x32_bf16 v[80:83], v[136:139], v[194:197], v[80:83]
	v_mfma_f32_16x16x32_bf16 v[124:127], v[132:135], v[166:169], v[124:127]
	v_mfma_f32_16x16x32_bf16 v[120:123], v[146:149], v[166:169], v[120:123]
	v_mfma_f32_16x16x32_bf16 v[108:111], v[132:135], v[174:177], v[108:111]
	v_mfma_f32_16x16x32_bf16 v[104:107], v[146:149], v[174:177], v[104:107]
	v_mfma_f32_16x16x32_bf16 v[96:99], v[132:135], v[182:185], v[96:99]
	v_mfma_f32_16x16x32_bf16 v[88:91], v[146:149], v[182:185], v[88:91]
	v_mfma_f32_16x16x32_bf16 v[84:87], v[132:135], v[210:213], v[84:87]
	v_mfma_f32_16x16x32_bf16 v[80:83], v[146:149], v[210:213], v[80:83]
	v_mfma_f32_16x16x32_bf16 v[116:119], v[214:217], v[162:165], v[116:119]
	v_mfma_f32_16x16x32_bf16 v[112:115], v[222:225], v[162:165], v[112:115]
	v_mfma_f32_16x16x32_bf16 v[100:103], v[214:217], v[170:173], v[100:103]
	v_mfma_f32_16x16x32_bf16 v[92:95], v[222:225], v[170:173], v[92:95]
	v_mfma_f32_16x16x32_bf16 v[76:79], v[214:217], v[178:181], v[76:79]
	v_mfma_f32_16x16x32_bf16 v[72:75], v[222:225], v[178:181], v[72:75]
	v_mfma_f32_16x16x32_bf16 v[68:71], v[214:217], v[194:197], v[68:71]
	v_mfma_f32_16x16x32_bf16 v[64:67], v[222:225], v[194:197], v[64:67]
	v_mfma_f32_16x16x32_bf16 v[116:119], v[218:221], v[166:169], v[116:119]
	v_mfma_f32_16x16x32_bf16 v[112:115], v[226:229], v[166:169], v[112:115]
	v_mfma_f32_16x16x32_bf16 v[100:103], v[218:221], v[174:177], v[100:103]
	v_mfma_f32_16x16x32_bf16 v[92:95], v[226:229], v[174:177], v[92:95]
	v_mfma_f32_16x16x32_bf16 v[76:79], v[218:221], v[182:185], v[76:79]
	v_mfma_f32_16x16x32_bf16 v[72:75], v[226:229], v[182:185], v[72:75]
	v_mfma_f32_16x16x32_bf16 v[68:71], v[218:221], v[210:213], v[68:71]
	v_mfma_f32_16x16x32_bf16 v[64:67], v[226:229], v[210:213], v[64:67]
	s_barrier
	s_add_i32 s6, s6, s57
	v_lshl_add_u64 v[230:231], v[230:231], 0, s[36:37]
	s_mov_b32 m0, s6
	s_nop 0
	global_load_lds_dwordx4 v[230:231], off
	v_lshl_add_u64 v[230:231], v[232:233], 0, s[36:37]
	s_add_i32 m0, s6, 0x2000
	s_nop 0
	global_load_lds_dwordx4 v[230:231], off
	s_mov_b32 m0, s72
	v_lshl_add_u64 v[230:231], v[234:235], 0, s[36:37]
	ds_read_b128 v[162:165], v208 offset:49152
	ds_read_b128 v[166:169], v208 offset:50176
	ds_read_b128 v[170:173], v208 offset:51200
	ds_read_b128 v[174:177], v208 offset:52224
	ds_read_b128 v[178:181], v208 offset:53248
	ds_read_b128 v[182:185], v208 offset:54272
	ds_read_b128 v[194:197], v208 offset:55296
	ds_read_b128 v[210:213], v208 offset:56320
	global_load_lds_dwordx4 v[230:231], off
	v_lshl_add_u64 v[230:231], v[236:237], 0, s[36:37]
	s_mov_b32 m0, s73
	s_nop 0
	global_load_lds_dwordx4 v[230:231], off
	s_add_u32 s54, s54, 0x40080
	s_addc_u32 s55, s55, 0
	s_add_i32 s6, s19, s57
	v_lshl_add_u64 v[250:251], s[54:55], 0, v[140:141]
	s_mov_b32 m0, s6
	s_nop 0
	global_load_lds_dwordx4 v[250:251], off
	v_lshl_add_u64 v[250:251], s[54:55], 0, v[150:151]
	s_add_i32 m0, s6, 0x2000
	s_nop 0
	global_load_lds_dwordx4 v[250:251], off
	s_add_i32 s82, s82, 2
	s_add_u32 s52, s52, 0x100
	s_addc_u32 s53, s53, 0
	s_add_u32 s39, s39, 0x100
	s_addc_u32 s51, s51, 0
	s_cmp_gt_u32 s82, 13
	s_waitcnt vmcnt(8)
	s_waitcnt lgkmcnt(0)
	s_barrier
	v_mfma_f32_16x16x32_bf16 v[60:63], v[128:131], v[162:165], v[60:63]
	v_mfma_f32_16x16x32_bf16 v[56:59], v[136:139], v[162:165], v[56:59]
	v_mfma_f32_16x16x32_bf16 v[48:51], v[128:131], v[170:173], v[48:51]
	v_mfma_f32_16x16x32_bf16 v[40:43], v[136:139], v[170:173], v[40:43]
	v_mfma_f32_16x16x32_bf16 v[32:35], v[128:131], v[178:181], v[32:35]
	v_mfma_f32_16x16x32_bf16 v[24:27], v[136:139], v[178:181], v[24:27]
	v_mfma_f32_16x16x32_bf16 v[16:19], v[128:131], v[194:197], v[16:19]
	v_mfma_f32_16x16x32_bf16 v[8:11], v[136:139], v[194:197], v[8:11]
	v_mfma_f32_16x16x32_bf16 v[60:63], v[132:135], v[166:169], v[60:63]
	v_mfma_f32_16x16x32_bf16 v[56:59], v[146:149], v[166:169], v[56:59]
	v_mfma_f32_16x16x32_bf16 v[48:51], v[132:135], v[174:177], v[48:51]
	v_mfma_f32_16x16x32_bf16 v[40:43], v[146:149], v[174:177], v[40:43]
	v_mfma_f32_16x16x32_bf16 v[32:35], v[132:135], v[182:185], v[32:35]
	v_mfma_f32_16x16x32_bf16 v[24:27], v[146:149], v[182:185], v[24:27]
	v_mfma_f32_16x16x32_bf16 v[16:19], v[132:135], v[210:213], v[16:19]
	v_mfma_f32_16x16x32_bf16 v[8:11], v[146:149], v[210:213], v[8:11]
	v_mfma_f32_16x16x32_bf16 v[52:55], v[214:217], v[162:165], v[52:55]
	v_mfma_f32_16x16x32_bf16 v[44:47], v[222:225], v[162:165], v[44:47]
	v_mfma_f32_16x16x32_bf16 v[36:39], v[214:217], v[170:173], v[36:39]
	v_mfma_f32_16x16x32_bf16 v[28:31], v[222:225], v[170:173], v[28:31]
	v_mfma_f32_16x16x32_bf16 v[20:23], v[214:217], v[178:181], v[20:23]
	v_mfma_f32_16x16x32_bf16 v[12:15], v[222:225], v[178:181], v[12:15]
	v_mfma_f32_16x16x32_bf16 v[4:7], v[214:217], v[194:197], v[4:7]
	v_mfma_f32_16x16x32_bf16 v[0:3], v[222:225], v[194:197], v[0:3]
	v_mfma_f32_16x16x32_bf16 v[52:55], v[218:221], v[166:169], v[52:55]
	v_mfma_f32_16x16x32_bf16 v[44:47], v[226:229], v[166:169], v[44:47]
	v_mfma_f32_16x16x32_bf16 v[36:39], v[218:221], v[174:177], v[36:39]
	v_mfma_f32_16x16x32_bf16 v[28:31], v[226:229], v[174:177], v[28:31]
	v_mfma_f32_16x16x32_bf16 v[20:23], v[218:221], v[182:185], v[20:23]
	v_mfma_f32_16x16x32_bf16 v[12:15], v[226:229], v[182:185], v[12:15]
	v_mfma_f32_16x16x32_bf16 v[4:7], v[218:221], v[210:213], v[4:7]
	v_mfma_f32_16x16x32_bf16 v[0:3], v[226:229], v[210:213], v[0:3]
	s_barrier
	s_cbranch_scc0 .LBB0_248
	s_mov_b32 s100, 1
	s_ashr_i32 s51, s50, 31
	v_lshl_or_b32 v128, s81, 8, v207
	s_lshl_b64 s[10:11], s[50:51], 8
	v_ashrrev_i32_e32 v129, 31, v128
	v_lshl_add_u64 v[168:169], s[10:11], 0, v[156:157]
	v_lshlrev_b64 v[170:171], 1, v[128:129]
	v_lshl_add_u64 v[174:175], s[28:29], 0, v[170:171]
	v_lshlrev_b64 v[172:173], 11, v[168:169]
	v_lshl_add_u64 v[128:129], v[174:175], 0, v[172:173]
	global_load_dwordx4 v[146:149], v[128:129], off
	global_load_dwordx4 v[182:185], v[128:129], off offset:256
	v_or_b32_e32 v166, 16, v168
	v_mov_b32_e32 v167, v169
	v_lshlrev_b64 v[176:177], 11, v[166:167]
	v_lshl_add_u64 v[128:129], v[174:175], 0, v[176:177]
	global_load_dwordx4 v[194:197], v[128:129], off
	global_load_dwordx4 v[210:213], v[128:129], off offset:256
	v_or_b32_e32 v164, 32, v168
	v_mov_b32_e32 v165, v169
	v_or_b32_e32 v162, 48, v168
	v_mov_b32_e32 v163, v169
	v_lshlrev_b64 v[180:181], 11, v[164:165]
	v_lshlrev_b64 v[178:179], 11, v[162:163]
	v_lshl_add_u64 v[128:129], v[174:175], 0, v[180:181]
	v_lshl_add_u64 v[130:131], v[174:175], 0, v[178:179]
	global_load_dwordx4 v[214:217], v[128:129], off
	global_load_dwordx4 v[136:139], v[128:129], off offset:256
	global_load_dwordx4 v[132:135], v[130:131], off
	s_nop 0
	global_load_dwordx4 v[128:131], v[130:131], off offset:256
	s_mov_b64 s[10:11], 0x90
	v_lshl_add_u64 v[172:173], s[30:31], 0, v[172:173]
	v_lshl_add_u64 v[172:173], v[172:173], 0, v[170:171]
	s_waitcnt vmcnt(0)
	v_lshlrev_b32_e32 v218, 16, v146
	v_and_b32_e32 v219, 0xffff0000, v146
	v_lshlrev_b32_e32 v220, 16, v148
	v_and_b32_e32 v221, 0xffff0000, v148
	v_lshlrev_b32_e32 v146, 16, v147
	v_and_b32_e32 v147, 0xffff0000, v147
	v_lshlrev_b32_e32 v222, 16, v182
	v_and_b32_e32 v223, 0xffff0000, v182
	v_lshlrev_b32_e32 v224, 16, v184
	v_and_b32_e32 v225, 0xffff0000, v184
	v_lshlrev_b32_e32 v182, 16, v183
	v_and_b32_e32 v183, 0xffff0000, v183
	v_pk_add_f32 v[124:125], v[124:125], v[218:219]
	v_pk_add_f32 v[120:121], v[120:121], v[220:221]
	v_pk_add_f32 v[126:127], v[126:127], v[146:147]
	v_pk_add_f32 v[116:117], v[116:117], v[222:223]
	v_pk_add_f32 v[146:147], v[112:113], v[224:225]
	v_pk_add_f32 v[118:119], v[118:119], v[182:183]
	v_pk_mul_f32 v[220:221], v[124:125], v[124:125]
	v_pk_mul_f32 v[222:223], v[126:127], v[126:127]
	v_cvt_pk_bf16_f32 v112, v124, v125
	v_cvt_pk_bf16_f32 v113, v126, v127
	v_pk_mul_f32 v[124:125], v[116:117], v[116:117]
	v_pk_mul_f32 v[126:127], v[118:119], v[118:119]
	v_pk_mul_f32 v[228:229], v[146:147], v[146:147]
	v_cvt_pk_bf16_f32 v116, v116, v117
	v_cvt_pk_bf16_f32 v117, v118, v119
	v_cvt_pk_bf16_f32 v118, v146, v147
	v_add_f32_e32 v146, v220, v221
	v_add_f32_e32 v146, v222, v146
	v_lshlrev_b32_e32 v148, 16, v149
	v_and_b32_e32 v149, 0xffff0000, v149
	v_pk_mul_f32 v[224:225], v[120:121], v[120:121]
	v_add_f32_e32 v146, v223, v146
	v_pk_add_f32 v[122:123], v[122:123], v[148:149]
	v_add_f32_e32 v146, v224, v146
	v_pk_mul_f32 v[226:227], v[122:123], v[122:123]
	v_add_f32_e32 v146, v225, v146
	v_add_f32_e32 v146, v226, v146
	v_add_f32_e32 v146, v227, v146
	v_add_f32_e32 v124, v124, v146
	v_add_f32_e32 v124, v125, v124
	v_add_f32_e32 v124, v126, v124
	v_lshlrev_b32_e32 v184, 16, v185
	v_and_b32_e32 v185, 0xffff0000, v185
	v_add_f32_e32 v124, v127, v124
	v_pk_add_f32 v[148:149], v[114:115], v[184:185]
	v_add_f32_e32 v124, v228, v124
	v_pk_mul_f32 v[230:231], v[148:149], v[148:149]
	v_add_f32_e32 v124, v229, v124
	v_add_f32_e32 v124, v230, v124
	v_add_f32_e32 v209, v231, v124
	v_lshlrev_b32_e32 v124, 16, v212
	v_and_b32_e32 v125, 0xffff0000, v212
	v_pk_add_f32 v[124:125], v[92:93], v[124:125]
	v_lshlrev_b32_e32 v92, 16, v211
	v_and_b32_e32 v93, 0xffff0000, v211
	v_pk_add_f32 v[102:103], v[102:103], v[92:93]
	v_lshlrev_b32_e32 v92, 16, v213
	v_and_b32_e32 v93, 0xffff0000, v213
	v_pk_add_f32 v[126:127], v[94:95], v[92:93]
	v_lshlrev_b32_e32 v92, 16, v214
	v_and_b32_e32 v93, 0xffff0000, v214
	v_pk_add_f32 v[92:93], v[96:97], v[92:93]
	v_lshlrev_b32_e32 v96, 16, v217
	v_and_b32_e32 v97, 0xffff0000, v217
	v_lshlrev_b32_e32 v94, 16, v216
	v_and_b32_e32 v95, 0xffff0000, v216
	v_pk_add_f32 v[90:91], v[90:91], v[96:97]
	v_lshlrev_b32_e32 v96, 16, v136
	v_and_b32_e32 v97, 0xffff0000, v136
	v_lshlrev_b32_e32 v182, 16, v194
	v_and_b32_e32 v183, 0xffff0000, v194
	v_pk_add_f32 v[88:89], v[88:89], v[94:95]
	v_lshlrev_b32_e32 v94, 16, v215
	v_and_b32_e32 v95, 0xffff0000, v215
	v_pk_add_f32 v[96:97], v[76:77], v[96:97]
	v_lshl_add_u64 v[76:77], v[168:169], 0, s[36:37]
	v_lshlrev_b32_e32 v184, 16, v196
	v_and_b32_e32 v185, 0xffff0000, v196
	v_cvt_pk_bf16_f32 v114, v120, v121
	v_pk_add_f32 v[120:121], v[108:109], v[182:183]
	v_pk_add_f32 v[94:95], v[98:99], v[94:95]
	v_lshlrev_b64 v[182:183], 11, v[76:77]
	v_lshlrev_b32_e32 v98, 16, v138
	v_and_b32_e32 v99, 0xffff0000, v138
	v_pk_add_f32 v[108:109], v[104:105], v[184:185]
	v_lshl_add_u64 v[184:185], v[174:175], 0, v[182:183]
	v_pk_add_f32 v[98:99], v[72:73], v[98:99]
	v_lshlrev_b32_e32 v72, 16, v137
	v_and_b32_e32 v73, 0xffff0000, v137
	v_lshlrev_b32_e32 v218, 16, v210
	v_and_b32_e32 v219, 0xffff0000, v210
	global_load_dwordx4 v[210:213], v[184:185], off
	v_pk_add_f32 v[136:137], v[78:79], v[72:73]
	v_lshlrev_b32_e32 v72, 16, v139
	v_and_b32_e32 v73, 0xffff0000, v139
	v_pk_add_f32 v[138:139], v[74:75], v[72:73]
	v_lshlrev_b32_e32 v72, 16, v132
	v_and_b32_e32 v73, 0xffff0000, v132
	v_pk_add_f32 v[74:75], v[84:85], v[72:73]
	v_lshlrev_b32_e32 v72, 16, v134
	v_and_b32_e32 v73, 0xffff0000, v134
	v_pk_add_f32 v[78:79], v[80:81], v[72:73]
	v_lshlrev_b32_e32 v72, 16, v133
	v_and_b32_e32 v73, 0xffff0000, v133
	v_pk_add_f32 v[100:101], v[100:101], v[218:219]
	global_load_dwordx4 v[218:221], v[184:185], off offset:256
	v_pk_add_f32 v[80:81], v[86:87], v[72:73]
	v_lshlrev_b32_e32 v72, 16, v135
	v_and_b32_e32 v73, 0xffff0000, v135
	v_pk_add_f32 v[82:83], v[82:83], v[72:73]
	v_lshl_add_u64 v[72:73], v[168:169], 0, s[10:11]
	v_lshlrev_b64 v[132:133], 11, v[72:73]
	v_lshl_add_u64 v[134:135], v[174:175], 0, v[132:133]
	v_lshlrev_b32_e32 v84, 16, v128
	v_and_b32_e32 v85, 0xffff0000, v128
	global_load_dwordx4 v[226:229], v[134:135], off
	global_load_dwordx4 v[234:237], v[134:135], off offset:256
	v_pk_add_f32 v[84:85], v[68:69], v[84:85]
	v_lshlrev_b32_e32 v68, 16, v130
	v_and_b32_e32 v69, 0xffff0000, v130
	v_pk_add_f32 v[86:87], v[64:65], v[68:69]
	v_lshlrev_b32_e32 v64, 16, v129
	v_and_b32_e32 v65, 0xffff0000, v129
	s_mov_b64 s[10:11], 0xa0
	v_pk_add_f32 v[128:129], v[70:71], v[64:65]
	v_lshl_add_u64 v[70:71], v[168:169], 0, s[10:11]
	s_mov_b64 s[10:11], 0xb0
	v_lshlrev_b32_e32 v64, 16, v131
	v_and_b32_e32 v65, 0xffff0000, v131
	v_lshlrev_b64 v[134:135], 11, v[70:71]
	v_lshl_add_u64 v[68:69], v[168:169], 0, s[10:11]
	v_pk_add_f32 v[130:131], v[66:67], v[64:65]
	v_lshl_add_u64 v[64:65], v[174:175], 0, v[134:135]
	v_lshlrev_b64 v[184:185], 11, v[68:69]
	global_load_dwordx4 v[238:241], v[64:65], off
	global_load_dwordx4 v[242:245], v[64:65], off offset:256
	v_lshl_add_u64 v[64:65], v[174:175], 0, v[184:185]
	global_load_dwordx4 v[246:249], v[64:65], off
	s_nop 0
	global_load_dwordx4 v[64:67], v[64:65], off offset:256
	v_lshlrev_b32_e32 v194, 16, v195
	v_and_b32_e32 v195, 0xffff0000, v195
	v_lshlrev_b32_e32 v196, 16, v197
	v_and_b32_e32 v197, 0xffff0000, v197
	v_cvt_pk_bf16_f32 v115, v122, v123
	v_cvt_pk_bf16_f32 v119, v148, v149
	v_pk_add_f32 v[122:123], v[110:111], v[194:195]
	v_pk_add_f32 v[110:111], v[106:107], v[196:197]
	global_store_dwordx4 v[172:173], v[112:115], off
	global_store_dwordx4 v[172:173], v[116:119], off offset:256
	v_cvt_pk_bf16_f32 v104, v120, v121
	v_lshl_add_u64 v[112:113], s[30:31], 0, v[176:177]
	v_cvt_pk_bf16_f32 v105, v122, v123
	v_cvt_pk_bf16_f32 v106, v108, v109
	v_cvt_pk_bf16_f32 v107, v110, v111
	v_lshl_add_u64 v[112:113], v[112:113], 0, v[170:171]
	v_cvt_pk_bf16_f32 v146, v100, v101
	v_cvt_pk_bf16_f32 v147, v102, v103
	v_cvt_pk_bf16_f32 v148, v124, v125
	v_cvt_pk_bf16_f32 v149, v126, v127
	global_store_dwordx4 v[112:113], v[104:107], off
	global_store_dwordx4 v[112:113], v[146:149], off offset:256
	v_cvt_pk_bf16_f32 v194, v92, v93
	v_lshl_add_u64 v[104:105], s[30:31], 0, v[180:181]
	v_cvt_pk_bf16_f32 v195, v94, v95
	v_cvt_pk_bf16_f32 v196, v88, v89
	v_cvt_pk_bf16_f32 v197, v90, v91
	v_lshl_add_u64 v[104:105], v[104:105], 0, v[170:171]
	v_cvt_pk_bf16_f32 v214, v96, v97
	v_cvt_pk_bf16_f32 v215, v136, v137
	v_cvt_pk_bf16_f32 v216, v98, v99
	v_cvt_pk_bf16_f32 v217, v138, v139
	global_store_dwordx4 v[104:105], v[194:197], off
	global_store_dwordx4 v[104:105], v[214:217], off offset:256
	v_lshl_add_u64 v[104:105], s[30:31], 0, v[178:179]
	v_cvt_pk_bf16_f32 v222, v74, v75
	v_cvt_pk_bf16_f32 v223, v80, v81
	v_cvt_pk_bf16_f32 v224, v78, v79
	v_cvt_pk_bf16_f32 v225, v82, v83
	v_lshl_add_u64 v[104:105], v[104:105], 0, v[170:171]
	v_cvt_pk_bf16_f32 v230, v84, v85
	v_cvt_pk_bf16_f32 v231, v128, v129
	v_cvt_pk_bf16_f32 v232, v86, v87
	v_cvt_pk_bf16_f32 v233, v130, v131
	global_store_dwordx4 v[104:105], v[222:225], off
	global_store_dwordx4 v[104:105], v[230:233], off offset:256
	s_waitcnt vmcnt(8)
	v_lshlrev_b32_e32 v104, 16, v210
	v_and_b32_e32 v105, 0xffff0000, v210
	v_pk_add_f32 v[60:61], v[60:61], v[104:105]
	v_lshlrev_b32_e32 v104, 16, v212
	v_and_b32_e32 v105, 0xffff0000, v212
	v_pk_add_f32 v[56:57], v[56:57], v[104:105]
	v_lshlrev_b32_e32 v104, 16, v211
	v_and_b32_e32 v105, 0xffff0000, v211
	v_pk_add_f32 v[62:63], v[62:63], v[104:105]
	v_lshlrev_b32_e32 v104, 16, v213
	v_and_b32_e32 v105, 0xffff0000, v213
	v_pk_add_f32 v[58:59], v[58:59], v[104:105]
	v_lshlrev_b32_e32 v104, 16, v218
	v_and_b32_e32 v105, 0xffff0000, v218
	v_pk_add_f32 v[52:53], v[52:53], v[104:105]
	v_lshlrev_b32_e32 v104, 16, v220
	v_and_b32_e32 v105, 0xffff0000, v220
	v_pk_add_f32 v[104:105], v[44:45], v[104:105]
	v_lshlrev_b32_e32 v44, 16, v219
	v_and_b32_e32 v45, 0xffff0000, v219
	v_pk_add_f32 v[54:55], v[54:55], v[44:45]
	v_lshlrev_b32_e32 v44, 16, v221
	v_and_b32_e32 v45, 0xffff0000, v221
	v_pk_add_f32 v[106:107], v[46:47], v[44:45]
	v_lshlrev_b32_e32 v44, 16, v226
	v_and_b32_e32 v45, 0xffff0000, v226
	v_pk_add_f32 v[44:45], v[48:49], v[44:45]
	v_lshlrev_b32_e32 v48, 16, v229
	v_and_b32_e32 v49, 0xffff0000, v229
	v_pk_add_f32 v[42:43], v[42:43], v[48:49]
	v_lshlrev_b32_e32 v48, 16, v234
	v_and_b32_e32 v49, 0xffff0000, v234
	v_pk_add_f32 v[36:37], v[36:37], v[48:49]
	v_lshlrev_b32_e32 v48, 16, v236
	v_and_b32_e32 v49, 0xffff0000, v236
	v_lshlrev_b32_e32 v46, 16, v228
	v_and_b32_e32 v47, 0xffff0000, v228
	v_pk_add_f32 v[48:49], v[28:29], v[48:49]
	v_lshlrev_b32_e32 v28, 16, v235
	v_and_b32_e32 v29, 0xffff0000, v235
	v_pk_add_f32 v[40:41], v[40:41], v[46:47]
	v_lshlrev_b32_e32 v46, 16, v227
	v_and_b32_e32 v47, 0xffff0000, v227
	v_pk_add_f32 v[38:39], v[38:39], v[28:29]
	v_lshlrev_b32_e32 v28, 16, v237
	v_and_b32_e32 v29, 0xffff0000, v237
	v_pk_add_f32 v[46:47], v[50:51], v[46:47]
	v_pk_add_f32 v[50:51], v[30:31], v[28:29]
	v_lshlrev_b32_e32 v28, 16, v238
	v_and_b32_e32 v29, 0xffff0000, v238
	v_lshlrev_b32_e32 v180, 16, v64
	v_and_b32_e32 v181, 0xffff0000, v64
	v_pk_add_f32 v[28:29], v[32:33], v[28:29]
	v_lshlrev_b32_e32 v32, 16, v241
	v_and_b32_e32 v33, 0xffff0000, v241
	v_pk_add_f32 v[4:5], v[4:5], v[180:181]
	v_lshlrev_b32_e32 v180, 16, v66
	v_and_b32_e32 v181, 0xffff0000, v66
	v_pk_add_f32 v[26:27], v[26:27], v[32:33]
	v_lshlrev_b32_e32 v32, 16, v242
	v_and_b32_e32 v33, 0xffff0000, v242
	v_pk_add_f32 v[0:1], v[0:1], v[180:181]
	v_lshl_add_u64 v[180:181], s[30:31], 0, v[182:183]
	v_cvt_pk_bf16_f32 v112, v60, v61
	v_cvt_pk_bf16_f32 v113, v62, v63
	v_cvt_pk_bf16_f32 v114, v56, v57
	v_cvt_pk_bf16_f32 v115, v58, v59
	v_pk_add_f32 v[20:21], v[20:21], v[32:33]
	v_lshlrev_b32_e32 v32, 16, v244
	v_and_b32_e32 v33, 0xffff0000, v244
	v_lshl_add_u64 v[180:181], v[180:181], 0, v[170:171]
	v_cvt_pk_bf16_f32 v116, v52, v53
	v_cvt_pk_bf16_f32 v117, v54, v55
	v_cvt_pk_bf16_f32 v118, v104, v105
	v_cvt_pk_bf16_f32 v119, v106, v107
	v_lshlrev_b32_e32 v30, 16, v240
	v_and_b32_e32 v31, 0xffff0000, v240
	v_pk_add_f32 v[32:33], v[12:13], v[32:33]
	v_lshlrev_b32_e32 v12, 16, v243
	v_and_b32_e32 v13, 0xffff0000, v243
	global_store_dwordx4 v[180:181], v[112:115], off
	global_store_dwordx4 v[180:181], v[116:119], off offset:256
	v_cvt_pk_bf16_f32 v146, v44, v45
	v_lshl_add_u64 v[112:113], s[30:31], 0, v[132:133]
	v_cvt_pk_bf16_f32 v147, v46, v47
	v_cvt_pk_bf16_f32 v148, v40, v41
	v_cvt_pk_bf16_f32 v149, v42, v43
	v_pk_add_f32 v[24:25], v[24:25], v[30:31]
	v_lshlrev_b32_e32 v30, 16, v239
	v_and_b32_e32 v31, 0xffff0000, v239
	v_pk_add_f32 v[22:23], v[22:23], v[12:13]
	v_lshlrev_b32_e32 v12, 16, v245
	v_and_b32_e32 v13, 0xffff0000, v245
	v_lshl_add_u64 v[112:113], v[112:113], 0, v[170:171]
	v_cvt_pk_bf16_f32 v172, v36, v37
	v_cvt_pk_bf16_f32 v173, v38, v39
	v_cvt_pk_bf16_f32 v174, v48, v49
	v_cvt_pk_bf16_f32 v175, v50, v51
	v_pk_add_f32 v[30:31], v[34:35], v[30:31]
	v_pk_add_f32 v[34:35], v[14:15], v[12:13]
	v_lshlrev_b32_e32 v12, 16, v246
	v_and_b32_e32 v13, 0xffff0000, v246
	v_lshlrev_b32_e32 v14, 16, v248
	v_and_b32_e32 v15, 0xffff0000, v248
	global_store_dwordx4 v[112:113], v[146:149], off
	global_store_dwordx4 v[112:113], v[172:175], off offset:256
	v_lshl_add_u64 v[112:113], s[30:31], 0, v[134:135]
	v_cvt_pk_bf16_f32 v176, v28, v29
	v_cvt_pk_bf16_f32 v177, v30, v31
	v_cvt_pk_bf16_f32 v178, v24, v25
	v_cvt_pk_bf16_f32 v179, v26, v27
	v_pk_add_f32 v[12:13], v[16:17], v[12:13]
	v_pk_add_f32 v[8:9], v[8:9], v[14:15]
	v_lshlrev_b32_e32 v14, 16, v247
	v_and_b32_e32 v15, 0xffff0000, v247
	v_lshlrev_b32_e32 v16, 16, v249
	v_and_b32_e32 v17, 0xffff0000, v249
	v_lshlrev_b32_e32 v64, 16, v65
	v_and_b32_e32 v65, 0xffff0000, v65
	v_lshl_add_u64 v[112:113], v[112:113], 0, v[170:171]
	v_cvt_pk_bf16_f32 v194, v20, v21
	v_cvt_pk_bf16_f32 v195, v22, v23
	v_cvt_pk_bf16_f32 v196, v32, v33
	v_cvt_pk_bf16_f32 v197, v34, v35
	v_pk_add_f32 v[14:15], v[18:19], v[14:15]
	v_pk_add_f32 v[10:11], v[10:11], v[16:17]
	v_pk_add_f32 v[6:7], v[6:7], v[64:65]
	v_lshlrev_b32_e32 v64, 16, v67
	v_and_b32_e32 v65, 0xffff0000, v67
	global_store_dwordx4 v[112:113], v[176:179], off
	global_store_dwordx4 v[112:113], v[194:197], off offset:256
	v_lshl_add_u64 v[112:113], s[30:31], 0, v[184:185]
	v_cvt_pk_bf16_f32 v16, v12, v13
	v_cvt_pk_bf16_f32 v17, v14, v15
	v_cvt_pk_bf16_f32 v18, v8, v9
	v_cvt_pk_bf16_f32 v19, v10, v11
	v_pk_add_f32 v[2:3], v[2:3], v[64:65]
	v_lshl_add_u64 v[112:113], v[112:113], 0, v[170:171]
	v_cvt_pk_bf16_f32 v64, v4, v5
	v_cvt_pk_bf16_f32 v65, v6, v7
	v_cvt_pk_bf16_f32 v66, v0, v1
	v_cvt_pk_bf16_f32 v67, v2, v3
	global_store_dwordx4 v[112:113], v[16:19], off
	global_store_dwordx4 v[112:113], v[64:67], off offset:256
	s_lshl_b32 s10, s81, 2
	v_and_b32_e32 v17, 64, v188
	v_xor_b32_e32 v16, 16, v188
	v_add_u32_e32 v17, 64, v17
	v_cmp_lt_i32_e32 vcc, v16, v17
	v_xor_b32_e32 v18, 32, v188
	s_ashr_i32 s11, s10, 31
	v_cndmask_b32_e32 v16, v188, v16, vcc
	v_lshlrev_b32_e32 v16, 2, v16
	v_mov_b32_e32 v132, v209
	v_cmp_lt_i32_e32 vcc, v18, v17
	s_lshl_b64 s[10:11], s[10:11], 2
	s_add_u32 s50, s75, s10
	v_cndmask_b32_e32 v17, v188, v18, vcc
	v_lshlrev_b32_e32 v17, 2, v17
	s_addc_u32 s51, s80, s11
	v_pk_mul_f32 v[18:19], v[120:121], v[120:121]
	v_pk_mul_f32 v[64:65], v[122:123], v[122:123]
	v_add_f32_e32 v18, v18, v19
	v_add_f32_e32 v18, v64, v18
	v_pk_mul_f32 v[66:67], v[108:109], v[108:109]
	v_add_f32_e32 v18, v65, v18
	v_add_f32_e32 v18, v66, v18
	v_pk_mul_f32 v[108:109], v[110:111], v[110:111]
	v_add_f32_e32 v18, v67, v18
	v_add_f32_e32 v18, v108, v18
	v_pk_mul_f32 v[100:101], v[100:101], v[100:101]
	v_add_f32_e32 v18, v109, v18
	v_add_f32_e32 v18, v100, v18
	v_pk_mul_f32 v[102:103], v[102:103], v[102:103]
	v_add_f32_e32 v18, v101, v18
	v_add_f32_e32 v18, v102, v18
	v_pk_mul_f32 v[110:111], v[124:125], v[124:125]
	v_add_f32_e32 v18, v103, v18
	v_add_f32_e32 v18, v110, v18
	v_pk_mul_f32 v[112:113], v[126:127], v[126:127]
	v_add_f32_e32 v18, v111, v18
	v_add_f32_e32 v18, v112, v18
	v_add_f32_e32 v18, v113, v18
	v_mov_b32_e32 v133, v18
	v_pk_mul_f32 v[18:19], v[92:93], v[92:93]
	v_pk_mul_f32 v[64:65], v[94:95], v[94:95]
	v_add_f32_e32 v18, v18, v19
	v_add_f32_e32 v18, v64, v18
	v_pk_mul_f32 v[66:67], v[88:89], v[88:89]
	v_add_f32_e32 v18, v65, v18
	v_add_f32_e32 v18, v66, v18
	v_pk_mul_f32 v[88:89], v[90:91], v[90:91]
	v_add_f32_e32 v18, v67, v18
	v_add_f32_e32 v18, v88, v18
	v_pk_mul_f32 v[90:91], v[96:97], v[96:97]
	v_add_f32_e32 v18, v89, v18
	v_add_f32_e32 v18, v90, v18
	v_pk_mul_f32 v[92:93], v[136:137], v[136:137]
	v_add_f32_e32 v18, v91, v18
	v_add_f32_e32 v18, v92, v18
	v_pk_mul_f32 v[94:95], v[98:99], v[98:99]
	v_add_f32_e32 v18, v93, v18
	v_add_f32_e32 v18, v94, v18
	v_pk_mul_f32 v[96:97], v[138:139], v[138:139]
	v_add_f32_e32 v18, v95, v18
	v_add_f32_e32 v18, v96, v18
	v_add_f32_e32 v18, v97, v18
	v_mov_b32_e32 v134, v18
	v_pk_mul_f32 v[18:19], v[74:75], v[74:75]
	v_pk_mul_f32 v[210:211], v[60:61], v[60:61]
	v_pk_mul_f32 v[64:65], v[80:81], v[80:81]
	v_pk_mul_f32 v[60:61], v[62:63], v[62:63]
	v_add_f32_e32 v18, v18, v19
	v_add_f32_e32 v210, v210, v211
	v_add_f32_e32 v18, v64, v18
	v_add_f32_e32 v210, v60, v210
	v_pk_mul_f32 v[66:67], v[78:79], v[78:79]
	v_pk_mul_f32 v[56:57], v[56:57], v[56:57]
	v_add_f32_e32 v18, v65, v18
	v_add_f32_e32 v210, v61, v210
	v_add_f32_e32 v18, v66, v18
	v_add_f32_e32 v210, v56, v210
	v_pk_mul_f32 v[74:75], v[82:83], v[82:83]
	v_pk_mul_f32 v[58:59], v[58:59], v[58:59]
	v_add_f32_e32 v18, v67, v18
	v_add_f32_e32 v210, v57, v210
	v_add_f32_e32 v18, v74, v18
	v_add_f32_e32 v210, v58, v210
	v_pk_mul_f32 v[78:79], v[84:85], v[84:85]
	v_pk_mul_f32 v[52:53], v[52:53], v[52:53]
	v_add_f32_e32 v18, v75, v18
	v_add_f32_e32 v210, v59, v210
	v_add_f32_e32 v18, v78, v18
	v_add_f32_e32 v210, v52, v210
	v_pk_mul_f32 v[80:81], v[128:129], v[128:129]
	v_pk_mul_f32 v[54:55], v[54:55], v[54:55]
	v_add_f32_e32 v18, v79, v18
	v_add_f32_e32 v210, v53, v210
	v_add_f32_e32 v18, v80, v18
	v_add_f32_e32 v210, v54, v210
	v_pk_mul_f32 v[82:83], v[86:87], v[86:87]
	v_pk_mul_f32 v[62:63], v[104:105], v[104:105]
	v_add_f32_e32 v18, v81, v18
	v_add_f32_e32 v210, v55, v210
	v_add_f32_e32 v18, v82, v18
	v_add_f32_e32 v210, v62, v210
	v_pk_mul_f32 v[84:85], v[130:131], v[130:131]
	v_pk_mul_f32 v[212:213], v[106:107], v[106:107]
	v_add_f32_e32 v18, v83, v18
	v_add_f32_e32 v210, v63, v210
	v_add_f32_e32 v18, v84, v18
	v_add_f32_e32 v210, v212, v210
	v_add_f32_e32 v18, v85, v18
	v_add_f32_e32 v210, v213, v210
	v_mov_b32_e32 v135, v18
	v_mov_b32_e32 v146, v210
	v_pk_mul_f32 v[18:19], v[44:45], v[44:45]
	v_pk_mul_f32 v[210:211], v[28:29], v[28:29]
	v_pk_mul_f32 v[44:45], v[46:47], v[46:47]
	v_pk_mul_f32 v[28:29], v[30:31], v[30:31]
	v_add_f32_e32 v18, v18, v19
	v_add_f32_e32 v210, v210, v211
	v_add_f32_e32 v18, v44, v18
	v_add_f32_e32 v210, v28, v210
	v_pk_mul_f32 v[40:41], v[40:41], v[40:41]
	v_pk_mul_f32 v[24:25], v[24:25], v[24:25]
	v_add_f32_e32 v18, v45, v18
	v_add_f32_e32 v210, v29, v210
	v_add_f32_e32 v18, v40, v18
	v_add_f32_e32 v210, v24, v210
	v_pk_mul_f32 v[42:43], v[42:43], v[42:43]
	v_pk_mul_f32 v[26:27], v[26:27], v[26:27]
	v_add_f32_e32 v18, v41, v18
	v_add_f32_e32 v210, v25, v210
	v_add_f32_e32 v18, v42, v18
	v_add_f32_e32 v210, v26, v210
	v_pk_mul_f32 v[36:37], v[36:37], v[36:37]
	v_pk_mul_f32 v[20:21], v[20:21], v[20:21]
	v_add_f32_e32 v18, v43, v18
	v_add_f32_e32 v210, v27, v210
	v_add_f32_e32 v18, v36, v18
	v_add_f32_e32 v210, v20, v210
	v_pk_mul_f32 v[38:39], v[38:39], v[38:39]
	v_pk_mul_f32 v[22:23], v[22:23], v[22:23]
	v_add_f32_e32 v18, v37, v18
	v_add_f32_e32 v210, v21, v210
	v_add_f32_e32 v18, v38, v18
	v_add_f32_e32 v210, v22, v210
	v_pk_mul_f32 v[46:47], v[48:49], v[48:49]
	v_pk_mul_f32 v[30:31], v[32:33], v[32:33]
	v_add_f32_e32 v18, v39, v18
	v_add_f32_e32 v210, v23, v210
	v_add_f32_e32 v18, v46, v18
	v_add_f32_e32 v210, v30, v210
	v_pk_mul_f32 v[48:49], v[50:51], v[50:51]
	v_pk_mul_f32 v[32:33], v[34:35], v[34:35]
	v_add_f32_e32 v18, v47, v18
	v_add_f32_e32 v210, v31, v210
	v_add_f32_e32 v18, v48, v18
	v_add_f32_e32 v210, v32, v210
	v_add_f32_e32 v18, v49, v18
	v_add_f32_e32 v210, v33, v210
	v_mov_b32_e32 v147, v18
	v_mov_b32_e32 v148, v210
	v_pk_mul_f32 v[12:13], v[12:13], v[12:13]
	v_pk_mul_f32 v[14:15], v[14:15], v[14:15]
	v_add_f32_e32 v12, v12, v13
	v_add_f32_e32 v12, v14, v12
	v_pk_mul_f32 v[8:9], v[8:9], v[8:9]
	v_add_f32_e32 v12, v15, v12
	v_add_f32_e32 v8, v8, v12
	v_pk_mul_f32 v[10:11], v[10:11], v[10:11]
	v_add_f32_e32 v8, v9, v8
	v_add_f32_e32 v8, v10, v8
	v_pk_mul_f32 v[4:5], v[4:5], v[4:5]
	v_add_f32_e32 v8, v11, v8
	v_add_f32_e32 v4, v4, v8
	v_pk_mul_f32 v[6:7], v[6:7], v[6:7]
	v_add_f32_e32 v4, v5, v4
	v_add_f32_e32 v4, v6, v4
	v_pk_mul_f32 v[0:1], v[0:1], v[0:1]
	v_add_f32_e32 v4, v7, v4
	v_add_f32_e32 v0, v0, v4
	v_pk_mul_f32 v[2:3], v[2:3], v[2:3]
	v_add_f32_e32 v0, v1, v0
	v_add_f32_e32 v0, v2, v0
	v_add_f32_e32 v0, v3, v0
	v_mov_b32_e32 v149, v0
	ds_bpermute_b32 v172, v16, v132
	ds_bpermute_b32 v173, v16, v133
	ds_bpermute_b32 v174, v16, v134
	ds_bpermute_b32 v175, v16, v135
	ds_bpermute_b32 v180, v16, v146
	ds_bpermute_b32 v181, v16, v147
	ds_bpermute_b32 v182, v16, v148
	ds_bpermute_b32 v183, v16, v149
	s_waitcnt lgkmcnt(0)
	v_add_f32_e32 v132, v132, v172
	v_add_f32_e32 v133, v133, v173
	v_add_f32_e32 v134, v134, v174
	v_add_f32_e32 v135, v135, v175
	v_add_f32_e32 v146, v146, v180
	v_add_f32_e32 v147, v147, v181
	v_add_f32_e32 v148, v148, v182
	v_add_f32_e32 v149, v149, v183
	ds_bpermute_b32 v172, v17, v132
	ds_bpermute_b32 v173, v17, v133
	ds_bpermute_b32 v174, v17, v134
	ds_bpermute_b32 v175, v17, v135
	ds_bpermute_b32 v180, v17, v146
	ds_bpermute_b32 v181, v17, v147
	ds_bpermute_b32 v182, v17, v148
	ds_bpermute_b32 v183, v17, v149
	s_and_saveexec_b64 s[52:53], s[42:43]
	s_cbranch_execz .LBB0_240
	s_waitcnt lgkmcnt(0)
	v_add_f32_e32 v132, v132, v172
	v_lshlrev_b64 v[18:19], 6, v[168:169]
	v_lshl_add_u64 v[18:19], s[50:51], 0, v[18:19]
	global_store_dword v[18:19], v132, off
	v_add_f32_e32 v133, v133, v173
	v_lshlrev_b64 v[18:19], 6, v[166:167]
	v_lshl_add_u64 v[18:19], s[50:51], 0, v[18:19]
	global_store_dword v[18:19], v133, off
	v_add_f32_e32 v134, v134, v174
	v_lshlrev_b64 v[18:19], 6, v[164:165]
	v_lshl_add_u64 v[18:19], s[50:51], 0, v[18:19]
	global_store_dword v[18:19], v134, off
	v_add_f32_e32 v135, v135, v175
	v_lshlrev_b64 v[18:19], 6, v[162:163]
	v_lshl_add_u64 v[18:19], s[50:51], 0, v[18:19]
	global_store_dword v[18:19], v135, off
	v_add_f32_e32 v146, v146, v180
	v_lshlrev_b64 v[18:19], 6, v[76:77]
	v_lshl_add_u64 v[18:19], s[50:51], 0, v[18:19]
	global_store_dword v[18:19], v146, off
	v_add_f32_e32 v147, v147, v181
	v_lshlrev_b64 v[18:19], 6, v[72:73]
	v_lshl_add_u64 v[18:19], s[50:51], 0, v[18:19]
	global_store_dword v[18:19], v147, off
	v_add_f32_e32 v148, v148, v182
	v_lshlrev_b64 v[18:19], 6, v[70:71]
	v_lshl_add_u64 v[18:19], s[50:51], 0, v[18:19]
	global_store_dword v[18:19], v148, off
	v_add_f32_e32 v149, v149, v183
	v_lshlrev_b64 v[18:19], 6, v[68:69]
	v_lshl_add_u64 v[18:19], s[50:51], 0, v[18:19]
	global_store_dword v[18:19], v149, off
	s_branch .LBB0_240

.LBB0_341:
	s_add_u32 s46, s50, 0x100
	s_addc_u32 s47, s51, 0
	s_add_i32 s6, 0, 0x10000
	v_add_u32_e32 v146, s6, v206
	ds_read_b128 v[128:131], v146
	ds_read_b128 v[132:135], v146 offset:1024
	ds_read_b128 v[136:139], v146 offset:2048
	ds_read_b128 v[146:149], v146 offset:3072
	s_cmp_eq_u32 s12, 40
	s_cselect_b32 s53, s31, s47
	s_cselect_b32 s52, s30, s46
	s_cselect_b32 s49, s35, s11
	s_cselect_b32 s48, s34, s10
	v_lshl_add_u64 v[214:215], s[50:51], 0, v[158:159]
	s_add_i32 m0, s58, 0xc000
	ds_read_b128 v[162:165], v208
	ds_read_b128 v[166:169], v208 offset:1024
	ds_read_b128 v[170:173], v208 offset:2048
	ds_read_b128 v[174:177], v208 offset:3072
	ds_read_b128 v[178:181], v208 offset:4096
	ds_read_b128 v[182:185], v208 offset:5120
	ds_read_b128 v[194:197], v208 offset:6144
	ds_read_b128 v[210:213], v208 offset:7168
	global_load_lds_dwordx4 v[214:215], off
	v_lshl_add_u64 v[214:215], s[50:51], 0, v[160:161]
	s_add_i32 m0, s58, 0xe000
	s_nop 0
	global_load_lds_dwordx4 v[214:215], off
	s_add_i32 s19, 0, 0x14000
	v_add_u32_e32 v192, s19, v206
	ds_read_b128 v[214:217], v192
	ds_read_b128 v[218:221], v192 offset:1024
	ds_read_b128 v[222:225], v192 offset:2048
	ds_read_b128 v[226:229], v192 offset:3072
	s_nop 0
	s_waitcnt vmcnt(8)
	s_waitcnt lgkmcnt(0)
	s_barrier
	v_mfma_f32_16x16x32_bf16 v[124:127], v[128:131], v[162:165], v[124:127]
	v_mfma_f32_16x16x32_bf16 v[120:123], v[136:139], v[162:165], v[120:123]
	v_mfma_f32_16x16x32_bf16 v[108:111], v[128:131], v[170:173], v[108:111]
	v_mfma_f32_16x16x32_bf16 v[104:107], v[136:139], v[170:173], v[104:107]
	v_mfma_f32_16x16x32_bf16 v[96:99], v[128:131], v[178:181], v[96:99]
	v_mfma_f32_16x16x32_bf16 v[88:91], v[136:139], v[178:181], v[88:91]
	v_mfma_f32_16x16x32_bf16 v[84:87], v[128:131], v[194:197], v[84:87]
	v_mfma_f32_16x16x32_bf16 v[80:83], v[136:139], v[194:197], v[80:83]
	v_mfma_f32_16x16x32_bf16 v[124:127], v[132:135], v[166:169], v[124:127]
	v_mfma_f32_16x16x32_bf16 v[120:123], v[146:149], v[166:169], v[120:123]
	v_mfma_f32_16x16x32_bf16 v[108:111], v[132:135], v[174:177], v[108:111]
	v_mfma_f32_16x16x32_bf16 v[104:107], v[146:149], v[174:177], v[104:107]
	v_mfma_f32_16x16x32_bf16 v[96:99], v[132:135], v[182:185], v[96:99]
	v_mfma_f32_16x16x32_bf16 v[88:91], v[146:149], v[182:185], v[88:91]
	v_mfma_f32_16x16x32_bf16 v[84:87], v[132:135], v[210:213], v[84:87]
	v_mfma_f32_16x16x32_bf16 v[80:83], v[146:149], v[210:213], v[80:83]
	v_mfma_f32_16x16x32_bf16 v[116:119], v[214:217], v[162:165], v[116:119]
	v_mfma_f32_16x16x32_bf16 v[112:115], v[222:225], v[162:165], v[112:115]
	v_mfma_f32_16x16x32_bf16 v[100:103], v[214:217], v[170:173], v[100:103]
	v_mfma_f32_16x16x32_bf16 v[92:95], v[222:225], v[170:173], v[92:95]
	v_mfma_f32_16x16x32_bf16 v[76:79], v[214:217], v[178:181], v[76:79]
	v_mfma_f32_16x16x32_bf16 v[72:75], v[222:225], v[178:181], v[72:75]
	v_mfma_f32_16x16x32_bf16 v[68:71], v[214:217], v[194:197], v[68:71]
	v_mfma_f32_16x16x32_bf16 v[64:67], v[222:225], v[194:197], v[64:67]
	v_mfma_f32_16x16x32_bf16 v[116:119], v[218:221], v[166:169], v[116:119]
	v_mfma_f32_16x16x32_bf16 v[112:115], v[226:229], v[166:169], v[112:115]
	v_mfma_f32_16x16x32_bf16 v[100:103], v[218:221], v[174:177], v[100:103]
	v_mfma_f32_16x16x32_bf16 v[92:95], v[226:229], v[174:177], v[92:95]
	v_mfma_f32_16x16x32_bf16 v[76:79], v[218:221], v[182:185], v[76:79]
	v_mfma_f32_16x16x32_bf16 v[72:75], v[226:229], v[182:185], v[72:75]
	v_mfma_f32_16x16x32_bf16 v[68:71], v[218:221], v[210:213], v[68:71]
	v_mfma_f32_16x16x32_bf16 v[64:67], v[226:229], v[210:213], v[64:67]
	s_barrier
	s_add_i32 s6, s6, s57
	v_lshl_add_u64 v[230:231], s[48:49], 0, v[140:141]
	s_mov_b32 m0, s6
	s_nop 0
	global_load_lds_dwordx4 v[230:231], off
	v_lshl_add_u64 v[232:233], s[48:49], 0, v[150:151]
	s_add_i32 m0, s6, 0x2000
	s_nop 0
	global_load_lds_dwordx4 v[232:233], off
	s_mov_b32 m0, s58
	v_lshl_add_u64 v[234:235], s[52:53], 0, v[154:155]
	ds_read_b128 v[162:165], v208 offset:16384
	ds_read_b128 v[166:169], v208 offset:17408
	ds_read_b128 v[170:173], v208 offset:18432
	ds_read_b128 v[174:177], v208 offset:19456
	ds_read_b128 v[178:181], v208 offset:20480
	ds_read_b128 v[182:185], v208 offset:21504
	ds_read_b128 v[194:197], v208 offset:22528
	ds_read_b128 v[210:213], v208 offset:23552
	global_load_lds_dwordx4 v[234:235], off
	v_lshl_add_u64 v[236:237], s[52:53], 0, v[152:153]
	s_mov_b32 m0, s59
	s_nop 0
	global_load_lds_dwordx4 v[236:237], off
	s_add_u32 s50, s48, 0xb0000
	s_addc_u32 s51, s49, 0
	s_add_i32 s6, s19, s57
	v_lshl_add_u64 v[250:251], s[50:51], 0, v[140:141]
	s_mov_b32 m0, s6
	s_nop 0
	global_load_lds_dwordx4 v[250:251], off
	v_lshl_add_u64 v[250:251], s[50:51], 0, v[150:151]
	s_add_i32 m0, s6, 0x2000
	s_nop 0
	global_load_lds_dwordx4 v[250:251], off
	s_waitcnt vmcnt(8)
	s_waitcnt lgkmcnt(0)
	s_barrier
	v_mfma_f32_16x16x32_bf16 v[60:63], v[128:131], v[162:165], v[60:63]
	v_mfma_f32_16x16x32_bf16 v[56:59], v[136:139], v[162:165], v[56:59]
	v_mfma_f32_16x16x32_bf16 v[48:51], v[128:131], v[170:173], v[48:51]
	v_mfma_f32_16x16x32_bf16 v[40:43], v[136:139], v[170:173], v[40:43]
	v_mfma_f32_16x16x32_bf16 v[32:35], v[128:131], v[178:181], v[32:35]
	v_mfma_f32_16x16x32_bf16 v[24:27], v[136:139], v[178:181], v[24:27]
	v_mfma_f32_16x16x32_bf16 v[16:19], v[128:131], v[194:197], v[16:19]
	v_mfma_f32_16x16x32_bf16 v[8:11], v[136:139], v[194:197], v[8:11]
	v_mfma_f32_16x16x32_bf16 v[60:63], v[132:135], v[166:169], v[60:63]
	v_mfma_f32_16x16x32_bf16 v[56:59], v[146:149], v[166:169], v[56:59]
	v_mfma_f32_16x16x32_bf16 v[48:51], v[132:135], v[174:177], v[48:51]
	v_mfma_f32_16x16x32_bf16 v[40:43], v[146:149], v[174:177], v[40:43]
	v_mfma_f32_16x16x32_bf16 v[32:35], v[132:135], v[182:185], v[32:35]
	v_mfma_f32_16x16x32_bf16 v[24:27], v[146:149], v[182:185], v[24:27]
	v_mfma_f32_16x16x32_bf16 v[16:19], v[132:135], v[210:213], v[16:19]
	v_mfma_f32_16x16x32_bf16 v[8:11], v[146:149], v[210:213], v[8:11]
	v_mfma_f32_16x16x32_bf16 v[52:55], v[214:217], v[162:165], v[52:55]
	v_mfma_f32_16x16x32_bf16 v[44:47], v[222:225], v[162:165], v[44:47]
	v_mfma_f32_16x16x32_bf16 v[36:39], v[214:217], v[170:173], v[36:39]
	v_mfma_f32_16x16x32_bf16 v[28:31], v[222:225], v[170:173], v[28:31]
	v_mfma_f32_16x16x32_bf16 v[20:23], v[214:217], v[178:181], v[20:23]
	v_mfma_f32_16x16x32_bf16 v[12:15], v[222:225], v[178:181], v[12:15]
	v_mfma_f32_16x16x32_bf16 v[4:7], v[214:217], v[194:197], v[4:7]
	v_mfma_f32_16x16x32_bf16 v[0:3], v[222:225], v[194:197], v[0:3]
	v_mfma_f32_16x16x32_bf16 v[52:55], v[218:221], v[166:169], v[52:55]
	v_mfma_f32_16x16x32_bf16 v[44:47], v[226:229], v[166:169], v[44:47]
	v_mfma_f32_16x16x32_bf16 v[36:39], v[218:221], v[174:177], v[36:39]
	v_mfma_f32_16x16x32_bf16 v[28:31], v[226:229], v[174:177], v[28:31]
	v_mfma_f32_16x16x32_bf16 v[20:23], v[218:221], v[182:185], v[20:23]
	v_mfma_f32_16x16x32_bf16 v[12:15], v[226:229], v[182:185], v[12:15]
	v_mfma_f32_16x16x32_bf16 v[4:7], v[218:221], v[210:213], v[4:7]
	v_mfma_f32_16x16x32_bf16 v[0:3], v[226:229], v[210:213], v[0:3]
	s_barrier
	s_add_i32 s6, 0, 0x18000
	v_add_u32_e32 v146, s6, v206
	ds_read_b128 v[128:131], v146
	ds_read_b128 v[132:135], v146 offset:1024
	ds_read_b128 v[136:139], v146 offset:2048
	ds_read_b128 v[146:149], v146 offset:3072
	s_add_u32 s50, s52, 0xb0000
	s_addc_u32 s51, s53, 0
	s_mov_b32 m0, s68
	v_lshl_add_u64 v[214:215], s[50:51], 0, v[154:155]
	ds_read_b128 v[162:165], v208 offset:32768
	ds_read_b128 v[166:169], v208 offset:33792
	ds_read_b128 v[170:173], v208 offset:34816
	ds_read_b128 v[174:177], v208 offset:35840
	ds_read_b128 v[178:181], v208 offset:36864
	ds_read_b128 v[182:185], v208 offset:37888
	ds_read_b128 v[194:197], v208 offset:38912
	ds_read_b128 v[210:213], v208 offset:39936
	global_load_lds_dwordx4 v[214:215], off
	v_lshl_add_u64 v[214:215], s[50:51], 0, v[152:153]
	s_mov_b32 m0, s69
	s_nop 0
	global_load_lds_dwordx4 v[214:215], off
	s_add_i32 s19, 0, 0x1c000
	v_add_u32_e32 v192, s19, v206
	ds_read_b128 v[214:217], v192
	ds_read_b128 v[218:221], v192 offset:1024
	ds_read_b128 v[222:225], v192 offset:2048
	ds_read_b128 v[226:229], v192 offset:3072
	s_waitcnt vmcnt(8)
	s_waitcnt lgkmcnt(0)
	s_barrier
	v_mfma_f32_16x16x32_bf16 v[124:127], v[128:131], v[162:165], v[124:127]
	v_mfma_f32_16x16x32_bf16 v[120:123], v[136:139], v[162:165], v[120:123]
	v_mfma_f32_16x16x32_bf16 v[108:111], v[128:131], v[170:173], v[108:111]
	v_mfma_f32_16x16x32_bf16 v[104:107], v[136:139], v[170:173], v[104:107]
	v_mfma_f32_16x16x32_bf16 v[96:99], v[128:131], v[178:181], v[96:99]
	v_mfma_f32_16x16x32_bf16 v[88:91], v[136:139], v[178:181], v[88:91]
	v_mfma_f32_16x16x32_bf16 v[84:87], v[128:131], v[194:197], v[84:87]
	v_mfma_f32_16x16x32_bf16 v[80:83], v[136:139], v[194:197], v[80:83]
	v_mfma_f32_16x16x32_bf16 v[124:127], v[132:135], v[166:169], v[124:127]
	v_mfma_f32_16x16x32_bf16 v[120:123], v[146:149], v[166:169], v[120:123]
	v_mfma_f32_16x16x32_bf16 v[108:111], v[132:135], v[174:177], v[108:111]
	v_mfma_f32_16x16x32_bf16 v[104:107], v[146:149], v[174:177], v[104:107]
	v_mfma_f32_16x16x32_bf16 v[96:99], v[132:135], v[182:185], v[96:99]
	v_mfma_f32_16x16x32_bf16 v[88:91], v[146:149], v[182:185], v[88:91]
	v_mfma_f32_16x16x32_bf16 v[84:87], v[132:135], v[210:213], v[84:87]
	v_mfma_f32_16x16x32_bf16 v[80:83], v[146:149], v[210:213], v[80:83]
	v_mfma_f32_16x16x32_bf16 v[116:119], v[214:217], v[162:165], v[116:119]
	v_mfma_f32_16x16x32_bf16 v[112:115], v[222:225], v[162:165], v[112:115]
	v_mfma_f32_16x16x32_bf16 v[100:103], v[214:217], v[170:173], v[100:103]
	v_mfma_f32_16x16x32_bf16 v[92:95], v[222:225], v[170:173], v[92:95]
	v_mfma_f32_16x16x32_bf16 v[76:79], v[214:217], v[178:181], v[76:79]
	v_mfma_f32_16x16x32_bf16 v[72:75], v[222:225], v[178:181], v[72:75]
	v_mfma_f32_16x16x32_bf16 v[68:71], v[214:217], v[194:197], v[68:71]
	v_mfma_f32_16x16x32_bf16 v[64:67], v[222:225], v[194:197], v[64:67]
	v_mfma_f32_16x16x32_bf16 v[116:119], v[218:221], v[166:169], v[116:119]
	v_mfma_f32_16x16x32_bf16 v[112:115], v[226:229], v[166:169], v[112:115]
	v_mfma_f32_16x16x32_bf16 v[100:103], v[218:221], v[174:177], v[100:103]
	v_mfma_f32_16x16x32_bf16 v[92:95], v[226:229], v[174:177], v[92:95]
	v_mfma_f32_16x16x32_bf16 v[76:79], v[218:221], v[182:185], v[76:79]
	v_mfma_f32_16x16x32_bf16 v[72:75], v[226:229], v[182:185], v[72:75]
	v_mfma_f32_16x16x32_bf16 v[68:71], v[218:221], v[210:213], v[68:71]
	v_mfma_f32_16x16x32_bf16 v[64:67], v[226:229], v[210:213], v[64:67]
	s_barrier
	s_add_i32 s6, s6, s57
	v_lshl_add_u64 v[230:231], v[230:231], 0, s[36:37]
	s_mov_b32 m0, s6
	s_nop 0
	global_load_lds_dwordx4 v[230:231], off
	v_lshl_add_u64 v[230:231], v[232:233], 0, s[36:37]
	s_add_i32 m0, s6, 0x2000
	s_nop 0
	global_load_lds_dwordx4 v[230:231], off
	s_mov_b32 m0, s70
	v_lshl_add_u64 v[230:231], v[234:235], 0, s[36:37]
	ds_read_b128 v[162:165], v208 offset:49152
	ds_read_b128 v[166:169], v208 offset:50176
	ds_read_b128 v[170:173], v208 offset:51200
	ds_read_b128 v[174:177], v208 offset:52224
	ds_read_b128 v[178:181], v208 offset:53248
	ds_read_b128 v[182:185], v208 offset:54272
	ds_read_b128 v[194:197], v208 offset:55296
	ds_read_b128 v[210:213], v208 offset:56320
	global_load_lds_dwordx4 v[230:231], off
	v_lshl_add_u64 v[230:231], v[236:237], 0, s[36:37]
	s_mov_b32 m0, s71
	s_nop 0
	global_load_lds_dwordx4 v[230:231], off
	s_add_u32 s48, s48, 0xb0080
	s_addc_u32 s49, s49, 0
	s_add_i32 s6, s19, s57
	v_lshl_add_u64 v[250:251], s[48:49], 0, v[140:141]
	s_mov_b32 m0, s6
	s_nop 0
	global_load_lds_dwordx4 v[250:251], off
	v_lshl_add_u64 v[250:251], s[48:49], 0, v[150:151]
	s_add_i32 m0, s6, 0x2000
	s_nop 0
	global_load_lds_dwordx4 v[250:251], off
	s_add_i32 s12, s12, 2
	s_add_u32 s10, s10, 0x100
	s_addc_u32 s11, s11, 0
	s_cmp_gt_u32 s12, 41
	s_mov_b64 s[50:51], s[46:47]
	s_waitcnt vmcnt(8)
	s_waitcnt lgkmcnt(0)
	s_barrier
	v_mfma_f32_16x16x32_bf16 v[60:63], v[128:131], v[162:165], v[60:63]
	v_mfma_f32_16x16x32_bf16 v[56:59], v[136:139], v[162:165], v[56:59]
	v_mfma_f32_16x16x32_bf16 v[48:51], v[128:131], v[170:173], v[48:51]
	v_mfma_f32_16x16x32_bf16 v[40:43], v[136:139], v[170:173], v[40:43]
	v_mfma_f32_16x16x32_bf16 v[32:35], v[128:131], v[178:181], v[32:35]
	v_mfma_f32_16x16x32_bf16 v[24:27], v[136:139], v[178:181], v[24:27]
	v_mfma_f32_16x16x32_bf16 v[16:19], v[128:131], v[194:197], v[16:19]
	v_mfma_f32_16x16x32_bf16 v[8:11], v[136:139], v[194:197], v[8:11]
	v_mfma_f32_16x16x32_bf16 v[60:63], v[132:135], v[166:169], v[60:63]
	v_mfma_f32_16x16x32_bf16 v[56:59], v[146:149], v[166:169], v[56:59]
	v_mfma_f32_16x16x32_bf16 v[48:51], v[132:135], v[174:177], v[48:51]
	v_mfma_f32_16x16x32_bf16 v[40:43], v[146:149], v[174:177], v[40:43]
	v_mfma_f32_16x16x32_bf16 v[32:35], v[132:135], v[182:185], v[32:35]
	v_mfma_f32_16x16x32_bf16 v[24:27], v[146:149], v[182:185], v[24:27]
	v_mfma_f32_16x16x32_bf16 v[16:19], v[132:135], v[210:213], v[16:19]
	v_mfma_f32_16x16x32_bf16 v[8:11], v[146:149], v[210:213], v[8:11]
	v_mfma_f32_16x16x32_bf16 v[52:55], v[214:217], v[162:165], v[52:55]
	v_mfma_f32_16x16x32_bf16 v[44:47], v[222:225], v[162:165], v[44:47]
	v_mfma_f32_16x16x32_bf16 v[36:39], v[214:217], v[170:173], v[36:39]
	v_mfma_f32_16x16x32_bf16 v[28:31], v[222:225], v[170:173], v[28:31]
	v_mfma_f32_16x16x32_bf16 v[20:23], v[214:217], v[178:181], v[20:23]
	v_mfma_f32_16x16x32_bf16 v[12:15], v[222:225], v[178:181], v[12:15]
	v_mfma_f32_16x16x32_bf16 v[4:7], v[214:217], v[194:197], v[4:7]
	v_mfma_f32_16x16x32_bf16 v[0:3], v[222:225], v[194:197], v[0:3]
	v_mfma_f32_16x16x32_bf16 v[52:55], v[218:221], v[166:169], v[52:55]
	v_mfma_f32_16x16x32_bf16 v[44:47], v[226:229], v[166:169], v[44:47]
	v_mfma_f32_16x16x32_bf16 v[36:39], v[218:221], v[174:177], v[36:39]
	v_mfma_f32_16x16x32_bf16 v[28:31], v[226:229], v[174:177], v[28:31]
	v_mfma_f32_16x16x32_bf16 v[20:23], v[218:221], v[182:185], v[20:23]
	v_mfma_f32_16x16x32_bf16 v[12:15], v[226:229], v[182:185], v[12:15]
	v_mfma_f32_16x16x32_bf16 v[4:7], v[218:221], v[210:213], v[4:7]
	v_mfma_f32_16x16x32_bf16 v[0:3], v[226:229], v[210:213], v[0:3]
	s_barrier
	s_cbranch_scc0 .LBB0_341
	s_mov_b32 s100, 1
	s_ashr_i32 s39, s38, 31
	v_lshl_or_b32 v128, s81, 8, v207
	s_lshl_b64 s[10:11], s[38:39], 8
	v_ashrrev_i32_e32 v129, 31, v128
	v_lshl_add_u64 v[168:169], s[10:11], 0, v[156:157]
	v_lshlrev_b64 v[170:171], 1, v[128:129]
	v_lshl_add_u64 v[174:175], s[26:27], 0, v[170:171]
	v_lshlrev_b64 v[172:173], 11, v[168:169]
	v_lshl_add_u64 v[128:129], v[174:175], 0, v[172:173]
	global_load_dwordx4 v[182:185], v[128:129], off
	global_load_dwordx4 v[210:213], v[128:129], off offset:256
	v_or_b32_e32 v166, 16, v168
	v_mov_b32_e32 v167, v169
	v_lshlrev_b64 v[176:177], 11, v[166:167]
	v_lshl_add_u64 v[128:129], v[174:175], 0, v[176:177]
	global_load_dwordx4 v[214:217], v[128:129], off
	global_load_dwordx4 v[218:221], v[128:129], off offset:256
	v_or_b32_e32 v164, 32, v168
	v_mov_b32_e32 v165, v169
	v_or_b32_e32 v162, 48, v168
	v_mov_b32_e32 v163, v169
	v_lshlrev_b64 v[180:181], 11, v[164:165]
	v_lshlrev_b64 v[178:179], 11, v[162:163]
	v_lshl_add_u64 v[128:129], v[174:175], 0, v[180:181]
	v_lshl_add_u64 v[130:131], v[174:175], 0, v[178:179]
	global_load_dwordx4 v[222:225], v[128:129], off
	global_load_dwordx4 v[136:139], v[128:129], off offset:256
	global_load_dwordx4 v[132:135], v[130:131], off
	s_nop 0
	global_load_dwordx4 v[128:131], v[130:131], off offset:256
	s_mov_b64 s[10:11], 0x90
	v_lshl_add_u64 v[172:173], s[28:29], 0, v[172:173]
	v_lshl_add_u64 v[172:173], v[172:173], 0, v[170:171]
	s_waitcnt vmcnt(0)
	v_lshlrev_b32_e32 v146, 16, v182
	v_and_b32_e32 v147, 0xffff0000, v182
	v_lshlrev_b32_e32 v148, 16, v184
	v_and_b32_e32 v149, 0xffff0000, v184
	v_lshlrev_b32_e32 v182, 16, v183
	v_and_b32_e32 v183, 0xffff0000, v183
	v_lshlrev_b32_e32 v194, 16, v210
	v_and_b32_e32 v195, 0xffff0000, v210
	v_lshlrev_b32_e32 v196, 16, v212
	v_and_b32_e32 v197, 0xffff0000, v212
	v_lshlrev_b32_e32 v210, 16, v211
	v_and_b32_e32 v211, 0xffff0000, v211
	v_lshlrev_b32_e32 v212, 16, v213
	v_and_b32_e32 v213, 0xffff0000, v213
	v_pk_fma_f32 v[124:125], v[124:125], 0.5, v[146:147] op_sel_hi:[1,0,1]
	v_pk_fma_f32 v[120:121], v[120:121], 0.5, v[148:149] op_sel_hi:[1,0,1]
	v_pk_fma_f32 v[126:127], v[126:127], 0.5, v[182:183] op_sel_hi:[1,0,1]
	v_pk_fma_f32 v[116:117], v[116:117], 0.5, v[194:195] op_sel_hi:[1,0,1]
	v_pk_fma_f32 v[146:147], v[112:113], 0.5, v[196:197] op_sel_hi:[1,0,1]
	v_pk_fma_f32 v[118:119], v[118:119], 0.5, v[210:211] op_sel_hi:[1,0,1]
	v_pk_fma_f32 v[148:149], v[114:115], 0.5, v[212:213] op_sel_hi:[1,0,1]
	v_pk_mul_f32 v[212:213], v[124:125], v[124:125]
	v_lshlrev_b32_e32 v182, 16, v214
	v_and_b32_e32 v183, 0xffff0000, v214
	v_lshlrev_b32_e32 v194, 16, v215
	v_and_b32_e32 v195, 0xffff0000, v215
	v_pk_mul_f32 v[214:215], v[126:127], v[126:127]
	v_cvt_pk_bf16_f32 v112, v124, v125
	v_cvt_pk_bf16_f32 v113, v126, v127
	v_pk_mul_f32 v[124:125], v[116:117], v[116:117]
	v_pk_mul_f32 v[126:127], v[118:119], v[118:119]
	v_pk_mul_f32 v[228:229], v[146:147], v[146:147]
	v_cvt_pk_bf16_f32 v116, v116, v117
	v_cvt_pk_bf16_f32 v117, v118, v119
	v_cvt_pk_bf16_f32 v118, v146, v147
	v_add_f32_e32 v146, v212, v213
	v_lshlrev_b32_e32 v184, 16, v185
	v_and_b32_e32 v185, 0xffff0000, v185
	v_add_f32_e32 v146, v214, v146
	v_pk_fma_f32 v[122:123], v[122:123], 0.5, v[184:185] op_sel_hi:[1,0,1]
	v_lshlrev_b32_e32 v184, 16, v216
	v_and_b32_e32 v185, 0xffff0000, v216
	v_lshlrev_b32_e32 v196, 16, v217
	v_and_b32_e32 v197, 0xffff0000, v217
	v_pk_mul_f32 v[216:217], v[120:121], v[120:121]
	v_add_f32_e32 v146, v215, v146
	v_add_f32_e32 v146, v216, v146
	v_pk_mul_f32 v[226:227], v[122:123], v[122:123]
	v_add_f32_e32 v146, v217, v146
	v_add_f32_e32 v146, v226, v146
	v_add_f32_e32 v146, v227, v146
	v_add_f32_e32 v124, v124, v146
	v_add_f32_e32 v124, v125, v124
	v_add_f32_e32 v124, v126, v124
	v_add_f32_e32 v124, v127, v124
	v_add_f32_e32 v124, v228, v124
	v_pk_mul_f32 v[230:231], v[148:149], v[148:149]
	v_add_f32_e32 v124, v229, v124
	v_add_f32_e32 v124, v230, v124
	v_add_f32_e32 v209, v231, v124
	v_lshlrev_b32_e32 v124, 16, v220
	v_and_b32_e32 v125, 0xffff0000, v220
	v_pk_fma_f32 v[124:125], v[92:93], 0.5, v[124:125] op_sel_hi:[1,0,1]
	v_lshlrev_b32_e32 v92, 16, v219
	v_and_b32_e32 v93, 0xffff0000, v219
	v_pk_fma_f32 v[102:103], v[102:103], 0.5, v[92:93] op_sel_hi:[1,0,1]
	v_lshlrev_b32_e32 v92, 16, v221
	v_and_b32_e32 v93, 0xffff0000, v221
	v_pk_fma_f32 v[126:127], v[94:95], 0.5, v[92:93] op_sel_hi:[1,0,1]
	v_lshlrev_b32_e32 v92, 16, v222
	v_and_b32_e32 v93, 0xffff0000, v222
	v_pk_fma_f32 v[92:93], v[96:97], 0.5, v[92:93] op_sel_hi:[1,0,1]
	v_lshlrev_b32_e32 v96, 16, v225
	v_and_b32_e32 v97, 0xffff0000, v225
	v_lshlrev_b32_e32 v94, 16, v224
	v_and_b32_e32 v95, 0xffff0000, v224
	v_pk_fma_f32 v[90:91], v[90:91], 0.5, v[96:97] op_sel_hi:[1,0,1]
	v_lshlrev_b32_e32 v96, 16, v136
	v_and_b32_e32 v97, 0xffff0000, v136
	v_pk_fma_f32 v[88:89], v[88:89], 0.5, v[94:95] op_sel_hi:[1,0,1]
	v_lshlrev_b32_e32 v94, 16, v223
	v_and_b32_e32 v95, 0xffff0000, v223
	v_pk_fma_f32 v[96:97], v[76:77], 0.5, v[96:97] op_sel_hi:[1,0,1]
	v_lshl_add_u64 v[76:77], v[168:169], 0, s[36:37]
	v_cvt_pk_bf16_f32 v114, v120, v121
	v_pk_fma_f32 v[120:121], v[108:109], 0.5, v[182:183] op_sel_hi:[1,0,1]
	v_pk_fma_f32 v[94:95], v[98:99], 0.5, v[94:95] op_sel_hi:[1,0,1]
	v_lshlrev_b64 v[182:183], 11, v[76:77]
	v_lshlrev_b32_e32 v98, 16, v138
	v_and_b32_e32 v99, 0xffff0000, v138
	v_lshl_add_u64 v[146:147], v[174:175], 0, v[182:183]
	v_pk_fma_f32 v[98:99], v[72:73], 0.5, v[98:99] op_sel_hi:[1,0,1]
	v_lshlrev_b32_e32 v72, 16, v137
	v_and_b32_e32 v73, 0xffff0000, v137
	v_lshlrev_b32_e32 v210, 16, v218
	v_and_b32_e32 v211, 0xffff0000, v218
	global_load_dwordx4 v[218:221], v[146:147], off
	global_load_dwordx4 v[226:229], v[146:147], off offset:256
	v_pk_fma_f32 v[136:137], v[78:79], 0.5, v[72:73] op_sel_hi:[1,0,1]
	v_lshlrev_b32_e32 v72, 16, v139
	v_and_b32_e32 v73, 0xffff0000, v139
	v_pk_fma_f32 v[138:139], v[74:75], 0.5, v[72:73] op_sel_hi:[1,0,1]
	v_lshlrev_b32_e32 v72, 16, v132
	v_and_b32_e32 v73, 0xffff0000, v132
	v_pk_fma_f32 v[74:75], v[84:85], 0.5, v[72:73] op_sel_hi:[1,0,1]
	v_lshlrev_b32_e32 v72, 16, v134
	v_and_b32_e32 v73, 0xffff0000, v134
	v_pk_fma_f32 v[78:79], v[80:81], 0.5, v[72:73] op_sel_hi:[1,0,1]
	v_lshlrev_b32_e32 v72, 16, v133
	v_and_b32_e32 v73, 0xffff0000, v133
	v_pk_fma_f32 v[80:81], v[86:87], 0.5, v[72:73] op_sel_hi:[1,0,1]
	v_lshlrev_b32_e32 v72, 16, v135
	v_and_b32_e32 v73, 0xffff0000, v135
	v_pk_fma_f32 v[82:83], v[82:83], 0.5, v[72:73] op_sel_hi:[1,0,1]
	v_lshl_add_u64 v[72:73], v[168:169], 0, s[10:11]
	v_lshlrev_b64 v[132:133], 11, v[72:73]
	v_lshl_add_u64 v[134:135], v[174:175], 0, v[132:133]
	global_load_dwordx4 v[234:237], v[134:135], off
	global_load_dwordx4 v[242:245], v[134:135], off offset:256
	v_lshlrev_b32_e32 v84, 16, v128
	v_and_b32_e32 v85, 0xffff0000, v128
	v_pk_fma_f32 v[84:85], v[68:69], 0.5, v[84:85] op_sel_hi:[1,0,1]
	v_lshlrev_b32_e32 v68, 16, v130
	v_and_b32_e32 v69, 0xffff0000, v130
	v_pk_fma_f32 v[86:87], v[64:65], 0.5, v[68:69] op_sel_hi:[1,0,1]
	v_lshlrev_b32_e32 v64, 16, v129
	v_and_b32_e32 v65, 0xffff0000, v129
	s_mov_b64 s[10:11], 0xa0
	v_pk_fma_f32 v[128:129], v[70:71], 0.5, v[64:65] op_sel_hi:[1,0,1]
	v_lshl_add_u64 v[70:71], v[168:169], 0, s[10:11]
	v_lshlrev_b32_e32 v64, 16, v131
	v_and_b32_e32 v65, 0xffff0000, v131
	v_lshlrev_b64 v[134:135], 11, v[70:71]
	v_pk_fma_f32 v[130:131], v[66:67], 0.5, v[64:65] op_sel_hi:[1,0,1]
	v_lshl_add_u64 v[64:65], v[174:175], 0, v[134:135]
	v_cvt_pk_bf16_f32 v115, v122, v123
	v_pk_fma_f32 v[122:123], v[110:111], 0.5, v[194:195] op_sel_hi:[1,0,1]
	v_pk_fma_f32 v[110:111], v[106:107], 0.5, v[196:197] op_sel_hi:[1,0,1]
	global_load_dwordx4 v[246:249], v[64:65], off
	global_load_dwordx4 v[194:197], v[64:65], off offset:256
	s_mov_b64 s[10:11], 0xb0
	v_lshl_add_u64 v[68:69], v[168:169], 0, s[10:11]
	v_pk_fma_f32 v[108:109], v[104:105], 0.5, v[184:185] op_sel_hi:[1,0,1]
	v_lshlrev_b64 v[184:185], 11, v[68:69]
	v_lshl_add_u64 v[64:65], v[174:175], 0, v[184:185]
	v_cvt_pk_bf16_f32 v119, v148, v149
	global_load_dwordx4 v[146:149], v[64:65], off
	s_nop 0
	global_load_dwordx4 v[64:67], v[64:65], off offset:256
	global_store_dwordx4 v[172:173], v[112:115], off
	global_store_dwordx4 v[172:173], v[116:119], off offset:256
	v_cvt_pk_bf16_f32 v104, v120, v121
	v_lshl_add_u64 v[112:113], s[28:29], 0, v[176:177]
	v_cvt_pk_bf16_f32 v105, v122, v123
	v_cvt_pk_bf16_f32 v106, v108, v109
	v_cvt_pk_bf16_f32 v107, v110, v111
	v_pk_fma_f32 v[100:101], v[100:101], 0.5, v[210:211] op_sel_hi:[1,0,1]
	v_lshl_add_u64 v[112:113], v[112:113], 0, v[170:171]
	v_cvt_pk_bf16_f32 v210, v100, v101
	v_cvt_pk_bf16_f32 v211, v102, v103
	v_cvt_pk_bf16_f32 v212, v124, v125
	v_cvt_pk_bf16_f32 v213, v126, v127
	global_store_dwordx4 v[112:113], v[104:107], off
	global_store_dwordx4 v[112:113], v[210:213], off offset:256
	v_cvt_pk_bf16_f32 v214, v92, v93
	v_lshl_add_u64 v[104:105], s[28:29], 0, v[180:181]
	v_cvt_pk_bf16_f32 v215, v94, v95
	v_cvt_pk_bf16_f32 v216, v88, v89
	v_cvt_pk_bf16_f32 v217, v90, v91
	v_lshl_add_u64 v[104:105], v[104:105], 0, v[170:171]
	v_cvt_pk_bf16_f32 v222, v96, v97
	v_cvt_pk_bf16_f32 v223, v136, v137
	v_cvt_pk_bf16_f32 v224, v98, v99
	v_cvt_pk_bf16_f32 v225, v138, v139
	global_store_dwordx4 v[104:105], v[214:217], off
	global_store_dwordx4 v[104:105], v[222:225], off offset:256
	v_lshl_add_u64 v[104:105], s[28:29], 0, v[178:179]
	v_cvt_pk_bf16_f32 v230, v74, v75
	v_cvt_pk_bf16_f32 v231, v80, v81
	v_cvt_pk_bf16_f32 v232, v78, v79
	v_cvt_pk_bf16_f32 v233, v82, v83
	v_lshl_add_u64 v[104:105], v[104:105], 0, v[170:171]
	v_cvt_pk_bf16_f32 v238, v84, v85
	v_cvt_pk_bf16_f32 v239, v128, v129
	v_cvt_pk_bf16_f32 v240, v86, v87
	v_cvt_pk_bf16_f32 v241, v130, v131
	global_store_dwordx4 v[104:105], v[230:233], off
	global_store_dwordx4 v[104:105], v[238:241], off offset:256
	s_waitcnt vmcnt(8)
	v_lshlrev_b32_e32 v104, 16, v218
	v_and_b32_e32 v105, 0xffff0000, v218
	v_pk_fma_f32 v[60:61], v[60:61], 0.5, v[104:105] op_sel_hi:[1,0,1]
	v_lshlrev_b32_e32 v104, 16, v220
	v_and_b32_e32 v105, 0xffff0000, v220
	v_pk_fma_f32 v[56:57], v[56:57], 0.5, v[104:105] op_sel_hi:[1,0,1]
	v_lshlrev_b32_e32 v104, 16, v219
	v_and_b32_e32 v105, 0xffff0000, v219
	v_pk_fma_f32 v[62:63], v[62:63], 0.5, v[104:105] op_sel_hi:[1,0,1]
	v_lshlrev_b32_e32 v104, 16, v221
	v_and_b32_e32 v105, 0xffff0000, v221
	v_pk_fma_f32 v[58:59], v[58:59], 0.5, v[104:105] op_sel_hi:[1,0,1]
	v_lshlrev_b32_e32 v104, 16, v226
	v_and_b32_e32 v105, 0xffff0000, v226
	v_pk_fma_f32 v[52:53], v[52:53], 0.5, v[104:105] op_sel_hi:[1,0,1]
	v_lshlrev_b32_e32 v104, 16, v228
	v_and_b32_e32 v105, 0xffff0000, v228
	v_pk_fma_f32 v[104:105], v[44:45], 0.5, v[104:105] op_sel_hi:[1,0,1]
	v_lshlrev_b32_e32 v44, 16, v227
	v_and_b32_e32 v45, 0xffff0000, v227
	v_pk_fma_f32 v[54:55], v[54:55], 0.5, v[44:45] op_sel_hi:[1,0,1]
	v_lshlrev_b32_e32 v44, 16, v229
	v_and_b32_e32 v45, 0xffff0000, v229
	v_pk_fma_f32 v[106:107], v[46:47], 0.5, v[44:45] op_sel_hi:[1,0,1]
	v_lshlrev_b32_e32 v44, 16, v234
	v_and_b32_e32 v45, 0xffff0000, v234
	v_pk_fma_f32 v[44:45], v[48:49], 0.5, v[44:45] op_sel_hi:[1,0,1]
	v_lshlrev_b32_e32 v48, 16, v237
	v_and_b32_e32 v49, 0xffff0000, v237
	v_pk_fma_f32 v[42:43], v[42:43], 0.5, v[48:49] op_sel_hi:[1,0,1]
	v_lshlrev_b32_e32 v48, 16, v242
	v_and_b32_e32 v49, 0xffff0000, v242
	v_pk_fma_f32 v[36:37], v[36:37], 0.5, v[48:49] op_sel_hi:[1,0,1]
	v_lshlrev_b32_e32 v48, 16, v244
	v_and_b32_e32 v49, 0xffff0000, v244
	v_lshlrev_b32_e32 v46, 16, v236
	v_and_b32_e32 v47, 0xffff0000, v236
	v_pk_fma_f32 v[48:49], v[28:29], 0.5, v[48:49] op_sel_hi:[1,0,1]
	v_lshlrev_b32_e32 v28, 16, v243
	v_and_b32_e32 v29, 0xffff0000, v243
	v_pk_fma_f32 v[40:41], v[40:41], 0.5, v[46:47] op_sel_hi:[1,0,1]
	v_lshlrev_b32_e32 v46, 16, v235
	v_and_b32_e32 v47, 0xffff0000, v235
	v_pk_fma_f32 v[38:39], v[38:39], 0.5, v[28:29] op_sel_hi:[1,0,1]
	v_lshlrev_b32_e32 v28, 16, v245
	v_and_b32_e32 v29, 0xffff0000, v245
	v_pk_fma_f32 v[46:47], v[50:51], 0.5, v[46:47] op_sel_hi:[1,0,1]
	v_pk_fma_f32 v[50:51], v[30:31], 0.5, v[28:29] op_sel_hi:[1,0,1]
	v_lshlrev_b32_e32 v28, 16, v246
	v_and_b32_e32 v29, 0xffff0000, v246
	v_pk_fma_f32 v[28:29], v[32:33], 0.5, v[28:29] op_sel_hi:[1,0,1]
	v_lshlrev_b32_e32 v32, 16, v249
	v_and_b32_e32 v33, 0xffff0000, v249
	v_pk_fma_f32 v[26:27], v[26:27], 0.5, v[32:33] op_sel_hi:[1,0,1]
	v_lshlrev_b32_e32 v32, 16, v194
	v_and_b32_e32 v33, 0xffff0000, v194
	v_pk_fma_f32 v[20:21], v[20:21], 0.5, v[32:33] op_sel_hi:[1,0,1]
	v_lshlrev_b32_e32 v32, 16, v196
	v_and_b32_e32 v33, 0xffff0000, v196
	v_lshlrev_b32_e32 v30, 16, v248
	v_and_b32_e32 v31, 0xffff0000, v248
	v_pk_fma_f32 v[32:33], v[12:13], 0.5, v[32:33] op_sel_hi:[1,0,1]
	v_lshlrev_b32_e32 v12, 16, v195
	v_and_b32_e32 v13, 0xffff0000, v195
	v_pk_fma_f32 v[24:25], v[24:25], 0.5, v[30:31] op_sel_hi:[1,0,1]
	v_lshlrev_b32_e32 v30, 16, v247
	v_and_b32_e32 v31, 0xffff0000, v247
	v_pk_fma_f32 v[22:23], v[22:23], 0.5, v[12:13] op_sel_hi:[1,0,1]
	v_lshlrev_b32_e32 v12, 16, v197
	v_and_b32_e32 v13, 0xffff0000, v197
	v_pk_fma_f32 v[30:31], v[34:35], 0.5, v[30:31] op_sel_hi:[1,0,1]
	v_pk_fma_f32 v[34:35], v[14:15], 0.5, v[12:13] op_sel_hi:[1,0,1]
	v_lshlrev_b32_e32 v14, 16, v148
	v_and_b32_e32 v15, 0xffff0000, v148
	v_lshlrev_b32_e32 v12, 16, v146
	v_and_b32_e32 v13, 0xffff0000, v146
	v_pk_fma_f32 v[8:9], v[8:9], 0.5, v[14:15] op_sel_hi:[1,0,1]
	v_lshlrev_b32_e32 v14, 16, v147
	v_and_b32_e32 v15, 0xffff0000, v147
	v_lshlrev_b32_e32 v146, 16, v64
	v_and_b32_e32 v147, 0xffff0000, v64
	v_pk_fma_f32 v[4:5], v[4:5], 0.5, v[146:147] op_sel_hi:[1,0,1]
	v_lshlrev_b32_e32 v146, 16, v66
	v_and_b32_e32 v147, 0xffff0000, v66
	v_pk_fma_f32 v[0:1], v[0:1], 0.5, v[146:147] op_sel_hi:[1,0,1]
	v_lshl_add_u64 v[146:147], s[28:29], 0, v[182:183]
	v_cvt_pk_bf16_f32 v112, v60, v61
	v_cvt_pk_bf16_f32 v113, v62, v63
	v_cvt_pk_bf16_f32 v114, v56, v57
	v_cvt_pk_bf16_f32 v115, v58, v59
	v_lshl_add_u64 v[146:147], v[146:147], 0, v[170:171]
	v_cvt_pk_bf16_f32 v116, v52, v53
	v_cvt_pk_bf16_f32 v117, v54, v55
	v_cvt_pk_bf16_f32 v118, v104, v105
	v_cvt_pk_bf16_f32 v119, v106, v107
	global_store_dwordx4 v[146:147], v[112:115], off
	global_store_dwordx4 v[146:147], v[116:119], off offset:256
	v_cvt_pk_bf16_f32 v172, v44, v45
	v_lshl_add_u64 v[112:113], s[28:29], 0, v[132:133]
	v_cvt_pk_bf16_f32 v173, v46, v47
	v_cvt_pk_bf16_f32 v174, v40, v41
	v_cvt_pk_bf16_f32 v175, v42, v43
	v_lshl_add_u64 v[112:113], v[112:113], 0, v[170:171]
	v_cvt_pk_bf16_f32 v176, v36, v37
	v_cvt_pk_bf16_f32 v177, v38, v39
	v_cvt_pk_bf16_f32 v178, v48, v49
	v_cvt_pk_bf16_f32 v179, v50, v51
	global_store_dwordx4 v[112:113], v[172:175], off
	global_store_dwordx4 v[112:113], v[176:179], off offset:256
	v_lshl_add_u64 v[112:113], s[28:29], 0, v[134:135]
	v_cvt_pk_bf16_f32 v210, v28, v29
	v_cvt_pk_bf16_f32 v211, v30, v31
	v_cvt_pk_bf16_f32 v212, v24, v25
	v_cvt_pk_bf16_f32 v213, v26, v27
	v_pk_fma_f32 v[12:13], v[16:17], 0.5, v[12:13] op_sel_hi:[1,0,1]
	v_lshlrev_b32_e32 v16, 16, v149
	v_and_b32_e32 v17, 0xffff0000, v149
	v_lshlrev_b32_e32 v64, 16, v65
	v_and_b32_e32 v65, 0xffff0000, v65
	v_lshl_add_u64 v[112:113], v[112:113], 0, v[170:171]
	v_cvt_pk_bf16_f32 v194, v20, v21
	v_cvt_pk_bf16_f32 v195, v22, v23
	v_cvt_pk_bf16_f32 v196, v32, v33
	v_cvt_pk_bf16_f32 v197, v34, v35
	v_pk_fma_f32 v[14:15], v[18:19], 0.5, v[14:15] op_sel_hi:[1,0,1]
	v_pk_fma_f32 v[10:11], v[10:11], 0.5, v[16:17] op_sel_hi:[1,0,1]
	v_pk_fma_f32 v[6:7], v[6:7], 0.5, v[64:65] op_sel_hi:[1,0,1]
	v_lshlrev_b32_e32 v64, 16, v67
	v_and_b32_e32 v65, 0xffff0000, v67
	global_store_dwordx4 v[112:113], v[210:213], off
	global_store_dwordx4 v[112:113], v[194:197], off offset:256
	v_lshl_add_u64 v[112:113], s[28:29], 0, v[184:185]
	v_cvt_pk_bf16_f32 v16, v12, v13
	v_cvt_pk_bf16_f32 v17, v14, v15
	v_cvt_pk_bf16_f32 v18, v8, v9
	v_cvt_pk_bf16_f32 v19, v10, v11
	v_pk_fma_f32 v[2:3], v[2:3], 0.5, v[64:65] op_sel_hi:[1,0,1]
	v_lshl_add_u64 v[112:113], v[112:113], 0, v[170:171]
	v_cvt_pk_bf16_f32 v64, v4, v5
	v_cvt_pk_bf16_f32 v65, v6, v7
	v_cvt_pk_bf16_f32 v66, v0, v1
	v_cvt_pk_bf16_f32 v67, v2, v3
	global_store_dwordx4 v[112:113], v[16:19], off
	global_store_dwordx4 v[112:113], v[64:67], off offset:256
	s_lshl_b32 s10, s81, 2
	v_and_b32_e32 v17, 64, v188
	v_xor_b32_e32 v16, 16, v188
	v_add_u32_e32 v17, 64, v17
	v_cmp_lt_i32_e32 vcc, v16, v17
	v_xor_b32_e32 v18, 32, v188
	s_ashr_i32 s11, s10, 31
	v_cndmask_b32_e32 v16, v188, v16, vcc
	v_lshlrev_b32_e32 v16, 2, v16
	v_mov_b32_e32 v132, v209
	v_cmp_lt_i32_e32 vcc, v18, v17
	s_lshl_b64 s[10:11], s[10:11], 2
	s_add_u32 s38, s73, s10
	v_cndmask_b32_e32 v17, v188, v18, vcc
	v_lshlrev_b32_e32 v17, 2, v17
	s_addc_u32 s39, s74, s11
	v_pk_mul_f32 v[18:19], v[120:121], v[120:121]
	v_pk_mul_f32 v[64:65], v[122:123], v[122:123]
	v_add_f32_e32 v18, v18, v19
	v_add_f32_e32 v18, v64, v18
	v_pk_mul_f32 v[66:67], v[108:109], v[108:109]
	v_add_f32_e32 v18, v65, v18
	v_add_f32_e32 v18, v66, v18
	v_pk_mul_f32 v[108:109], v[110:111], v[110:111]
	v_add_f32_e32 v18, v67, v18
	v_add_f32_e32 v18, v108, v18
	v_pk_mul_f32 v[100:101], v[100:101], v[100:101]
	v_add_f32_e32 v18, v109, v18
	v_add_f32_e32 v18, v100, v18
	v_pk_mul_f32 v[102:103], v[102:103], v[102:103]
	v_add_f32_e32 v18, v101, v18
	v_add_f32_e32 v18, v102, v18
	v_pk_mul_f32 v[110:111], v[124:125], v[124:125]
	v_add_f32_e32 v18, v103, v18
	v_add_f32_e32 v18, v110, v18
	v_pk_mul_f32 v[112:113], v[126:127], v[126:127]
	v_add_f32_e32 v18, v111, v18
	v_add_f32_e32 v18, v112, v18
	v_add_f32_e32 v18, v113, v18
	v_mov_b32_e32 v133, v18
	v_pk_mul_f32 v[18:19], v[92:93], v[92:93]
	v_pk_mul_f32 v[64:65], v[94:95], v[94:95]
	v_add_f32_e32 v18, v18, v19
	v_add_f32_e32 v18, v64, v18
	v_pk_mul_f32 v[66:67], v[88:89], v[88:89]
	v_add_f32_e32 v18, v65, v18
	v_add_f32_e32 v18, v66, v18
	v_pk_mul_f32 v[88:89], v[90:91], v[90:91]
	v_add_f32_e32 v18, v67, v18
	v_add_f32_e32 v18, v88, v18
	v_pk_mul_f32 v[90:91], v[96:97], v[96:97]
	v_add_f32_e32 v18, v89, v18
	v_add_f32_e32 v18, v90, v18
	v_pk_mul_f32 v[92:93], v[136:137], v[136:137]
	v_add_f32_e32 v18, v91, v18
	v_add_f32_e32 v18, v92, v18
	v_pk_mul_f32 v[94:95], v[98:99], v[98:99]
	v_add_f32_e32 v18, v93, v18
	v_add_f32_e32 v18, v94, v18
	v_pk_mul_f32 v[96:97], v[138:139], v[138:139]
	v_add_f32_e32 v18, v95, v18
	v_add_f32_e32 v18, v96, v18
	v_add_f32_e32 v18, v97, v18
	v_mov_b32_e32 v134, v18
	v_pk_mul_f32 v[18:19], v[74:75], v[74:75]
	v_pk_mul_f32 v[180:181], v[60:61], v[60:61]
	v_pk_mul_f32 v[64:65], v[80:81], v[80:81]
	v_pk_mul_f32 v[60:61], v[62:63], v[62:63]
	v_add_f32_e32 v18, v18, v19
	v_add_f32_e32 v180, v180, v181
	v_add_f32_e32 v18, v64, v18
	v_add_f32_e32 v180, v60, v180
	v_pk_mul_f32 v[66:67], v[78:79], v[78:79]
	v_pk_mul_f32 v[56:57], v[56:57], v[56:57]
	v_add_f32_e32 v18, v65, v18
	v_add_f32_e32 v180, v61, v180
	v_add_f32_e32 v18, v66, v18
	v_add_f32_e32 v180, v56, v180
	v_pk_mul_f32 v[74:75], v[82:83], v[82:83]
	v_pk_mul_f32 v[58:59], v[58:59], v[58:59]
	v_add_f32_e32 v18, v67, v18
	v_add_f32_e32 v180, v57, v180
	v_add_f32_e32 v18, v74, v18
	v_add_f32_e32 v180, v58, v180
	v_pk_mul_f32 v[78:79], v[84:85], v[84:85]
	v_pk_mul_f32 v[52:53], v[52:53], v[52:53]
	v_add_f32_e32 v18, v75, v18
	v_add_f32_e32 v180, v59, v180
	v_add_f32_e32 v18, v78, v18
	v_add_f32_e32 v180, v52, v180
	v_pk_mul_f32 v[80:81], v[128:129], v[128:129]
	v_pk_mul_f32 v[54:55], v[54:55], v[54:55]
	v_add_f32_e32 v18, v79, v18
	v_add_f32_e32 v180, v53, v180
	v_add_f32_e32 v18, v80, v18
	v_add_f32_e32 v180, v54, v180
	v_pk_mul_f32 v[82:83], v[86:87], v[86:87]
	v_pk_mul_f32 v[62:63], v[104:105], v[104:105]
	v_add_f32_e32 v18, v81, v18
	v_add_f32_e32 v180, v55, v180
	v_add_f32_e32 v18, v82, v18
	v_add_f32_e32 v180, v62, v180
	v_pk_mul_f32 v[84:85], v[130:131], v[130:131]
	v_pk_mul_f32 v[182:183], v[106:107], v[106:107]
	v_add_f32_e32 v18, v83, v18
	v_add_f32_e32 v180, v63, v180
	v_add_f32_e32 v18, v84, v18
	v_add_f32_e32 v180, v182, v180
	v_add_f32_e32 v18, v85, v18
	v_add_f32_e32 v180, v183, v180
	v_mov_b32_e32 v135, v18
	v_mov_b32_e32 v146, v180
	v_pk_mul_f32 v[18:19], v[44:45], v[44:45]
	v_pk_mul_f32 v[180:181], v[28:29], v[28:29]
	v_pk_mul_f32 v[44:45], v[46:47], v[46:47]
	v_pk_mul_f32 v[28:29], v[30:31], v[30:31]
	v_add_f32_e32 v18, v18, v19
	v_add_f32_e32 v180, v180, v181
	v_add_f32_e32 v18, v44, v18
	v_add_f32_e32 v180, v28, v180
	v_pk_mul_f32 v[40:41], v[40:41], v[40:41]
	v_pk_mul_f32 v[24:25], v[24:25], v[24:25]
	v_add_f32_e32 v18, v45, v18
	v_add_f32_e32 v180, v29, v180
	v_add_f32_e32 v18, v40, v18
	v_add_f32_e32 v180, v24, v180
	v_pk_mul_f32 v[42:43], v[42:43], v[42:43]
	v_pk_mul_f32 v[26:27], v[26:27], v[26:27]
	v_add_f32_e32 v18, v41, v18
	v_add_f32_e32 v180, v25, v180
	v_add_f32_e32 v18, v42, v18
	v_add_f32_e32 v180, v26, v180
	v_pk_mul_f32 v[36:37], v[36:37], v[36:37]
	v_pk_mul_f32 v[20:21], v[20:21], v[20:21]
	v_add_f32_e32 v18, v43, v18
	v_add_f32_e32 v180, v27, v180
	v_add_f32_e32 v18, v36, v18
	v_add_f32_e32 v180, v20, v180
	v_pk_mul_f32 v[38:39], v[38:39], v[38:39]
	v_pk_mul_f32 v[22:23], v[22:23], v[22:23]
	v_add_f32_e32 v18, v37, v18
	v_add_f32_e32 v180, v21, v180
	v_add_f32_e32 v18, v38, v18
	v_add_f32_e32 v180, v22, v180
	v_pk_mul_f32 v[46:47], v[48:49], v[48:49]
	v_pk_mul_f32 v[30:31], v[32:33], v[32:33]
	v_add_f32_e32 v18, v39, v18
	v_add_f32_e32 v180, v23, v180
	v_add_f32_e32 v18, v46, v18
	v_add_f32_e32 v180, v30, v180
	v_pk_mul_f32 v[48:49], v[50:51], v[50:51]
	v_pk_mul_f32 v[32:33], v[34:35], v[34:35]
	v_add_f32_e32 v18, v47, v18
	v_add_f32_e32 v180, v31, v180
	v_add_f32_e32 v18, v48, v18
	v_add_f32_e32 v180, v32, v180
	v_add_f32_e32 v18, v49, v18
	v_add_f32_e32 v180, v33, v180
	v_mov_b32_e32 v147, v18
	v_mov_b32_e32 v148, v180
	v_pk_mul_f32 v[12:13], v[12:13], v[12:13]
	v_pk_mul_f32 v[14:15], v[14:15], v[14:15]
	v_add_f32_e32 v12, v12, v13
	v_add_f32_e32 v12, v14, v12
	v_pk_mul_f32 v[8:9], v[8:9], v[8:9]
	v_add_f32_e32 v12, v15, v12
	v_add_f32_e32 v8, v8, v12
	v_pk_mul_f32 v[10:11], v[10:11], v[10:11]
	v_add_f32_e32 v8, v9, v8
	v_add_f32_e32 v8, v10, v8
	v_pk_mul_f32 v[4:5], v[4:5], v[4:5]
	v_add_f32_e32 v8, v11, v8
	v_add_f32_e32 v4, v4, v8
	v_pk_mul_f32 v[6:7], v[6:7], v[6:7]
	v_add_f32_e32 v4, v5, v4
	v_add_f32_e32 v4, v6, v4
	v_pk_mul_f32 v[0:1], v[0:1], v[0:1]
	v_add_f32_e32 v4, v7, v4
	v_add_f32_e32 v0, v0, v4
	v_pk_mul_f32 v[2:3], v[2:3], v[2:3]
	v_add_f32_e32 v0, v1, v0
	v_add_f32_e32 v0, v2, v0
	v_add_f32_e32 v0, v3, v0
	v_mov_b32_e32 v149, v0
	ds_bpermute_b32 v172, v16, v132
	ds_bpermute_b32 v173, v16, v133
	ds_bpermute_b32 v174, v16, v134
	ds_bpermute_b32 v175, v16, v135
	ds_bpermute_b32 v176, v16, v146
	ds_bpermute_b32 v177, v16, v147
	ds_bpermute_b32 v178, v16, v148
	ds_bpermute_b32 v179, v16, v149
	s_waitcnt lgkmcnt(0)
	v_add_f32_e32 v132, v132, v172
	v_add_f32_e32 v133, v133, v173
	v_add_f32_e32 v134, v134, v174
	v_add_f32_e32 v135, v135, v175
	v_add_f32_e32 v146, v146, v176
	v_add_f32_e32 v147, v147, v177
	v_add_f32_e32 v148, v148, v178
	v_add_f32_e32 v149, v149, v179
	ds_bpermute_b32 v172, v17, v132
	ds_bpermute_b32 v173, v17, v133
	ds_bpermute_b32 v174, v17, v134
	ds_bpermute_b32 v175, v17, v135
	ds_bpermute_b32 v176, v17, v146
	ds_bpermute_b32 v177, v17, v147
	ds_bpermute_b32 v178, v17, v148
	ds_bpermute_b32 v179, v17, v149
	s_and_saveexec_b64 s[46:47], s[42:43]
	s_cbranch_execz .LBB0_329
	s_waitcnt lgkmcnt(0)
	v_add_f32_e32 v132, v132, v172
	v_lshlrev_b64 v[18:19], 6, v[168:169]
	v_lshl_add_u64 v[18:19], s[38:39], 0, v[18:19]
	global_store_dword v[18:19], v132, off
	v_add_f32_e32 v133, v133, v173
	v_lshlrev_b64 v[18:19], 6, v[166:167]
	v_lshl_add_u64 v[18:19], s[38:39], 0, v[18:19]
	global_store_dword v[18:19], v133, off
	v_add_f32_e32 v134, v134, v174
	v_lshlrev_b64 v[18:19], 6, v[164:165]
	v_lshl_add_u64 v[18:19], s[38:39], 0, v[18:19]
	global_store_dword v[18:19], v134, off
	v_add_f32_e32 v135, v135, v175
	v_lshlrev_b64 v[18:19], 6, v[162:163]
	v_lshl_add_u64 v[18:19], s[38:39], 0, v[18:19]
	global_store_dword v[18:19], v135, off
	v_add_f32_e32 v146, v146, v176
	v_lshlrev_b64 v[18:19], 6, v[76:77]
	v_lshl_add_u64 v[18:19], s[38:39], 0, v[18:19]
	global_store_dword v[18:19], v146, off
	v_add_f32_e32 v147, v147, v177
	v_lshlrev_b64 v[18:19], 6, v[72:73]
	v_lshl_add_u64 v[18:19], s[38:39], 0, v[18:19]
	global_store_dword v[18:19], v147, off
	v_add_f32_e32 v148, v148, v178
	v_lshlrev_b64 v[18:19], 6, v[70:71]
	v_lshl_add_u64 v[18:19], s[38:39], 0, v[18:19]
	global_store_dword v[18:19], v148, off
	v_add_f32_e32 v149, v149, v179
	v_lshlrev_b64 v[18:19], 6, v[68:69]
	v_lshl_add_u64 v[18:19], s[38:39], 0, v[18:19]
	global_store_dword v[18:19], v149, off
	s_branch .LBB0_329

.LBB0_386:
	s_add_u32 s6, s28, s52
	s_addc_u32 s19, s29, s53
	s_add_u32 s6, s6, 0x100
	s_addc_u32 s19, s19, 0
	s_add_u32 s23, s10, s52
	s_addc_u32 s54, s11, s53
	s_add_i32 s82, 0, 0x10000
	v_add_u32_e32 v146, s82, v154
	ds_read_b128 v[158:161], v146
	ds_read_b128 v[162:165], v146 offset:1024
	ds_read_b128 v[166:169], v146 offset:2048
	ds_read_b128 v[170:173], v146 offset:3072
	s_cmpk_eq_i32 s52, 0x700
	s_cselect_b32 s59, s12, s19
	s_cselect_b32 s58, s35, s6
	s_cselect_b32 s55, s39, s54
	s_cselect_b32 s54, s47, s23
	v_lshl_add_u64 v[146:147], v[150:151], 0, s[52:53]
	s_add_i32 m0, s68, 0xc000
	ds_read_b128 v[174:177], v157
	ds_read_b128 v[178:181], v157 offset:1024
	ds_read_b128 v[182:185], v157 offset:2048
	ds_read_b128 v[206:209], v157 offset:3072
	ds_read_b128 v[210:213], v157 offset:4096
	ds_read_b128 v[214:217], v157 offset:5120
	ds_read_b128 v[218:221], v157 offset:6144
	ds_read_b128 v[222:225], v157 offset:7168
	global_load_lds_dwordx4 v[146:147], off
	v_lshl_add_u64 v[146:147], v[152:153], 0, s[52:53]
	s_add_i32 m0, s68, 0xe000
	s_nop 0
	global_load_lds_dwordx4 v[146:147], off
	s_add_i32 s6, 0, 0x14000
	v_add_u32_e32 v146, s6, v154
	ds_read_b128 v[226:229], v146
	ds_read_b128 v[230:233], v146 offset:1024
	ds_read_b128 v[234:237], v146 offset:2048
	ds_read_b128 v[238:241], v146 offset:3072
	s_nop 0
	s_waitcnt vmcnt(8)
	s_waitcnt lgkmcnt(0)
	s_barrier
	v_mfma_f32_16x16x32_bf16 v[124:127], v[158:161], v[174:177], v[124:127]
	v_mfma_f32_16x16x32_bf16 v[120:123], v[166:169], v[174:177], v[120:123]
	v_mfma_f32_16x16x32_bf16 v[116:119], v[158:161], v[182:185], v[116:119]
	v_mfma_f32_16x16x32_bf16 v[112:115], v[166:169], v[182:185], v[112:115]
	v_mfma_f32_16x16x32_bf16 v[108:111], v[158:161], v[210:213], v[108:111]
	v_mfma_f32_16x16x32_bf16 v[104:107], v[166:169], v[210:213], v[104:107]
	v_mfma_f32_16x16x32_bf16 v[100:103], v[158:161], v[218:221], v[100:103]
	v_mfma_f32_16x16x32_bf16 v[96:99], v[166:169], v[218:221], v[96:99]
	v_mfma_f32_16x16x32_bf16 v[124:127], v[162:165], v[178:181], v[124:127]
	v_mfma_f32_16x16x32_bf16 v[120:123], v[170:173], v[178:181], v[120:123]
	v_mfma_f32_16x16x32_bf16 v[116:119], v[162:165], v[206:209], v[116:119]
	v_mfma_f32_16x16x32_bf16 v[112:115], v[170:173], v[206:209], v[112:115]
	v_mfma_f32_16x16x32_bf16 v[108:111], v[162:165], v[214:217], v[108:111]
	v_mfma_f32_16x16x32_bf16 v[104:107], v[170:173], v[214:217], v[104:107]
	v_mfma_f32_16x16x32_bf16 v[100:103], v[162:165], v[222:225], v[100:103]
	v_mfma_f32_16x16x32_bf16 v[96:99], v[170:173], v[222:225], v[96:99]
	v_mfma_f32_16x16x32_bf16 v[92:95], v[226:229], v[174:177], v[92:95]
	v_mfma_f32_16x16x32_bf16 v[88:91], v[234:237], v[174:177], v[88:91]
	v_mfma_f32_16x16x32_bf16 v[84:87], v[226:229], v[182:185], v[84:87]
	v_mfma_f32_16x16x32_bf16 v[80:83], v[234:237], v[182:185], v[80:83]
	v_mfma_f32_16x16x32_bf16 v[76:79], v[226:229], v[210:213], v[76:79]
	v_mfma_f32_16x16x32_bf16 v[72:75], v[234:237], v[210:213], v[72:75]
	v_mfma_f32_16x16x32_bf16 v[68:71], v[226:229], v[218:221], v[68:71]
	v_mfma_f32_16x16x32_bf16 v[64:67], v[234:237], v[218:221], v[64:67]
	v_mfma_f32_16x16x32_bf16 v[92:95], v[230:233], v[178:181], v[92:95]
	v_mfma_f32_16x16x32_bf16 v[88:91], v[238:241], v[178:181], v[88:91]
	v_mfma_f32_16x16x32_bf16 v[84:87], v[230:233], v[206:209], v[84:87]
	v_mfma_f32_16x16x32_bf16 v[80:83], v[238:241], v[206:209], v[80:83]
	v_mfma_f32_16x16x32_bf16 v[76:79], v[230:233], v[214:217], v[76:79]
	v_mfma_f32_16x16x32_bf16 v[72:75], v[238:241], v[214:217], v[72:75]
	v_mfma_f32_16x16x32_bf16 v[68:71], v[230:233], v[222:225], v[68:71]
	v_mfma_f32_16x16x32_bf16 v[64:67], v[238:241], v[222:225], v[64:67]
	s_barrier
	s_add_i32 s19, s82, s57
	v_lshl_add_u64 v[146:147], s[54:55], 0, v[140:141]
	s_mov_b32 m0, s19
	v_lshl_add_u64 v[148:149], s[54:55], 0, v[132:133]
	global_load_lds_dwordx4 v[146:147], off
	s_add_i32 m0, s19, 0x2000
	s_nop 0
	global_load_lds_dwordx4 v[148:149], off
	s_mov_b32 m0, s68
	v_lshl_add_u64 v[194:195], s[58:59], 0, v[128:129]
	ds_read_b128 v[174:177], v157 offset:16384
	ds_read_b128 v[178:181], v157 offset:17408
	ds_read_b128 v[182:185], v157 offset:18432
	ds_read_b128 v[206:209], v157 offset:19456
	ds_read_b128 v[210:213], v157 offset:20480
	ds_read_b128 v[214:217], v157 offset:21504
	ds_read_b128 v[218:221], v157 offset:22528
	ds_read_b128 v[222:225], v157 offset:23552
	global_load_lds_dwordx4 v[194:195], off
	v_lshl_add_u64 v[196:197], s[58:59], 0, v[130:131]
	s_mov_b32 m0, s69
	s_nop 0
	global_load_lds_dwordx4 v[196:197], off
	s_add_u32 s82, s54, 0x40000
	s_addc_u32 s83, s55, 0
	s_add_i32 s6, s6, s57
	v_lshl_add_u64 v[250:251], s[82:83], 0, v[140:141]
	s_mov_b32 m0, s6
	s_nop 0
	global_load_lds_dwordx4 v[250:251], off
	v_lshl_add_u64 v[250:251], s[82:83], 0, v[132:133]
	s_add_i32 m0, s6, 0x2000
	s_nop 0
	global_load_lds_dwordx4 v[250:251], off
	s_nop 0
	s_waitcnt vmcnt(8)
	s_waitcnt lgkmcnt(0)
	s_barrier
	v_mfma_f32_16x16x32_bf16 v[60:63], v[158:161], v[174:177], v[60:63]
	v_mfma_f32_16x16x32_bf16 v[56:59], v[166:169], v[174:177], v[56:59]
	v_mfma_f32_16x16x32_bf16 v[52:55], v[158:161], v[182:185], v[52:55]
	v_mfma_f32_16x16x32_bf16 v[48:51], v[166:169], v[182:185], v[48:51]
	v_mfma_f32_16x16x32_bf16 v[44:47], v[158:161], v[210:213], v[44:47]
	v_mfma_f32_16x16x32_bf16 v[40:43], v[166:169], v[210:213], v[40:43]
	v_mfma_f32_16x16x32_bf16 v[36:39], v[158:161], v[218:221], v[36:39]
	v_mfma_f32_16x16x32_bf16 v[32:35], v[166:169], v[218:221], v[32:35]
	v_mfma_f32_16x16x32_bf16 v[60:63], v[162:165], v[178:181], v[60:63]
	v_mfma_f32_16x16x32_bf16 v[56:59], v[170:173], v[178:181], v[56:59]
	v_mfma_f32_16x16x32_bf16 v[52:55], v[162:165], v[206:209], v[52:55]
	v_mfma_f32_16x16x32_bf16 v[48:51], v[170:173], v[206:209], v[48:51]
	v_mfma_f32_16x16x32_bf16 v[44:47], v[162:165], v[214:217], v[44:47]
	v_mfma_f32_16x16x32_bf16 v[40:43], v[170:173], v[214:217], v[40:43]
	v_mfma_f32_16x16x32_bf16 v[36:39], v[162:165], v[222:225], v[36:39]
	v_mfma_f32_16x16x32_bf16 v[32:35], v[170:173], v[222:225], v[32:35]
	v_mfma_f32_16x16x32_bf16 v[28:31], v[226:229], v[174:177], v[28:31]
	v_mfma_f32_16x16x32_bf16 v[24:27], v[234:237], v[174:177], v[24:27]
	v_mfma_f32_16x16x32_bf16 v[20:23], v[226:229], v[182:185], v[20:23]
	v_mfma_f32_16x16x32_bf16 v[16:19], v[234:237], v[182:185], v[16:19]
	v_mfma_f32_16x16x32_bf16 v[12:15], v[226:229], v[210:213], v[12:15]
	v_mfma_f32_16x16x32_bf16 v[8:11], v[234:237], v[210:213], v[8:11]
	v_mfma_f32_16x16x32_bf16 v[4:7], v[226:229], v[218:221], v[4:7]
	v_mfma_f32_16x16x32_bf16 v[0:3], v[234:237], v[218:221], v[0:3]
	v_mfma_f32_16x16x32_bf16 v[28:31], v[230:233], v[178:181], v[28:31]
	v_mfma_f32_16x16x32_bf16 v[24:27], v[238:241], v[178:181], v[24:27]
	v_mfma_f32_16x16x32_bf16 v[20:23], v[230:233], v[206:209], v[20:23]
	v_mfma_f32_16x16x32_bf16 v[16:19], v[238:241], v[206:209], v[16:19]
	v_mfma_f32_16x16x32_bf16 v[12:15], v[230:233], v[214:217], v[12:15]
	v_mfma_f32_16x16x32_bf16 v[8:11], v[238:241], v[214:217], v[8:11]
	v_mfma_f32_16x16x32_bf16 v[4:7], v[230:233], v[222:225], v[4:7]
	v_mfma_f32_16x16x32_bf16 v[0:3], v[238:241], v[222:225], v[0:3]
	s_barrier
	s_add_i32 s6, 0, 0x18000
	v_add_u32_e32 v170, s6, v154
	ds_read_b128 v[158:161], v170
	ds_read_b128 v[162:165], v170 offset:1024
	ds_read_b128 v[166:169], v170 offset:2048
	ds_read_b128 v[170:173], v170 offset:3072
	s_add_u32 s58, s58, 0x40000
	s_addc_u32 s59, s59, 0
	s_mov_b32 m0, s70
	v_lshl_add_u64 v[226:227], s[58:59], 0, v[128:129]
	ds_read_b128 v[174:177], v157 offset:32768
	ds_read_b128 v[178:181], v157 offset:33792
	ds_read_b128 v[182:185], v157 offset:34816
	ds_read_b128 v[206:209], v157 offset:35840
	ds_read_b128 v[210:213], v157 offset:36864
	ds_read_b128 v[214:217], v157 offset:37888
	ds_read_b128 v[218:221], v157 offset:38912
	ds_read_b128 v[222:225], v157 offset:39936
	global_load_lds_dwordx4 v[226:227], off
	v_lshl_add_u64 v[226:227], s[58:59], 0, v[130:131]
	s_mov_b32 m0, s71
	s_nop 0
	global_load_lds_dwordx4 v[226:227], off
	s_add_i32 s19, 0, 0x1c000
	v_add_u32_e32 v192, s19, v154
	ds_read_b128 v[226:229], v192
	ds_read_b128 v[230:233], v192 offset:1024
	ds_read_b128 v[234:237], v192 offset:2048
	ds_read_b128 v[238:241], v192 offset:3072
	s_waitcnt vmcnt(8)
	s_waitcnt lgkmcnt(0)
	s_barrier
	v_mfma_f32_16x16x32_bf16 v[124:127], v[158:161], v[174:177], v[124:127]
	v_mfma_f32_16x16x32_bf16 v[120:123], v[166:169], v[174:177], v[120:123]
	v_mfma_f32_16x16x32_bf16 v[116:119], v[158:161], v[182:185], v[116:119]
	v_mfma_f32_16x16x32_bf16 v[112:115], v[166:169], v[182:185], v[112:115]
	v_mfma_f32_16x16x32_bf16 v[108:111], v[158:161], v[210:213], v[108:111]
	v_mfma_f32_16x16x32_bf16 v[104:107], v[166:169], v[210:213], v[104:107]
	v_mfma_f32_16x16x32_bf16 v[100:103], v[158:161], v[218:221], v[100:103]
	v_mfma_f32_16x16x32_bf16 v[96:99], v[166:169], v[218:221], v[96:99]
	v_mfma_f32_16x16x32_bf16 v[124:127], v[162:165], v[178:181], v[124:127]
	v_mfma_f32_16x16x32_bf16 v[120:123], v[170:173], v[178:181], v[120:123]
	v_mfma_f32_16x16x32_bf16 v[116:119], v[162:165], v[206:209], v[116:119]
	v_mfma_f32_16x16x32_bf16 v[112:115], v[170:173], v[206:209], v[112:115]
	v_mfma_f32_16x16x32_bf16 v[108:111], v[162:165], v[214:217], v[108:111]
	v_mfma_f32_16x16x32_bf16 v[104:107], v[170:173], v[214:217], v[104:107]
	v_mfma_f32_16x16x32_bf16 v[100:103], v[162:165], v[222:225], v[100:103]
	v_mfma_f32_16x16x32_bf16 v[96:99], v[170:173], v[222:225], v[96:99]
	v_mfma_f32_16x16x32_bf16 v[92:95], v[226:229], v[174:177], v[92:95]
	v_mfma_f32_16x16x32_bf16 v[88:91], v[234:237], v[174:177], v[88:91]
	v_mfma_f32_16x16x32_bf16 v[84:87], v[226:229], v[182:185], v[84:87]
	v_mfma_f32_16x16x32_bf16 v[80:83], v[234:237], v[182:185], v[80:83]
	v_mfma_f32_16x16x32_bf16 v[76:79], v[226:229], v[210:213], v[76:79]
	v_mfma_f32_16x16x32_bf16 v[72:75], v[234:237], v[210:213], v[72:75]
	v_mfma_f32_16x16x32_bf16 v[68:71], v[226:229], v[218:221], v[68:71]
	v_mfma_f32_16x16x32_bf16 v[64:67], v[234:237], v[218:221], v[64:67]
	v_mfma_f32_16x16x32_bf16 v[92:95], v[230:233], v[178:181], v[92:95]
	v_mfma_f32_16x16x32_bf16 v[88:91], v[238:241], v[178:181], v[88:91]
	v_mfma_f32_16x16x32_bf16 v[84:87], v[230:233], v[206:209], v[84:87]
	v_mfma_f32_16x16x32_bf16 v[80:83], v[238:241], v[206:209], v[80:83]
	v_mfma_f32_16x16x32_bf16 v[76:79], v[230:233], v[214:217], v[76:79]
	v_mfma_f32_16x16x32_bf16 v[72:75], v[238:241], v[214:217], v[72:75]
	v_mfma_f32_16x16x32_bf16 v[68:71], v[230:233], v[222:225], v[68:71]
	v_mfma_f32_16x16x32_bf16 v[64:67], v[238:241], v[222:225], v[64:67]
	s_barrier
	s_add_i32 s6, s6, s57
	v_lshl_add_u64 v[146:147], v[146:147], 0, s[36:37]
	s_mov_b32 m0, s6
	s_nop 0
	global_load_lds_dwordx4 v[146:147], off
	v_lshl_add_u64 v[146:147], v[148:149], 0, s[36:37]
	s_add_i32 m0, s6, 0x2000
	s_nop 0
	global_load_lds_dwordx4 v[146:147], off
	s_mov_b32 m0, s72
	v_lshl_add_u64 v[146:147], v[194:195], 0, s[36:37]
	ds_read_b128 v[174:177], v157 offset:49152
	ds_read_b128 v[178:181], v157 offset:50176
	ds_read_b128 v[182:185], v157 offset:51200
	ds_read_b128 v[206:209], v157 offset:52224
	ds_read_b128 v[210:213], v157 offset:53248
	ds_read_b128 v[214:217], v157 offset:54272
	ds_read_b128 v[218:221], v157 offset:55296
	ds_read_b128 v[222:225], v157 offset:56320
	global_load_lds_dwordx4 v[146:147], off
	v_lshl_add_u64 v[146:147], v[196:197], 0, s[36:37]
	s_mov_b32 m0, s73
	s_nop 0
	global_load_lds_dwordx4 v[146:147], off
	s_add_u32 s54, s54, 0x40080
	s_addc_u32 s55, s55, 0
	s_add_i32 s6, s19, s57
	v_lshl_add_u64 v[146:147], s[54:55], 0, v[140:141]
	s_mov_b32 m0, s6
	s_nop 0
	global_load_lds_dwordx4 v[146:147], off
	v_lshl_add_u64 v[146:147], s[54:55], 0, v[132:133]
	s_add_i32 m0, s6, 0x2000
	s_nop 0
	global_load_lds_dwordx4 v[146:147], off
	s_add_i32 s81, s81, 2
	s_add_u32 s52, s52, 0x100
	s_addc_u32 s53, s53, 0
	s_cmp_gt_u32 s81, 13
	s_nop 0
	s_waitcnt vmcnt(8)
	s_waitcnt lgkmcnt(0)
	s_barrier
	v_mfma_f32_16x16x32_bf16 v[60:63], v[158:161], v[174:177], v[60:63]
	v_mfma_f32_16x16x32_bf16 v[56:59], v[166:169], v[174:177], v[56:59]
	v_mfma_f32_16x16x32_bf16 v[52:55], v[158:161], v[182:185], v[52:55]
	v_mfma_f32_16x16x32_bf16 v[48:51], v[166:169], v[182:185], v[48:51]
	v_mfma_f32_16x16x32_bf16 v[44:47], v[158:161], v[210:213], v[44:47]
	v_mfma_f32_16x16x32_bf16 v[40:43], v[166:169], v[210:213], v[40:43]
	v_mfma_f32_16x16x32_bf16 v[36:39], v[158:161], v[218:221], v[36:39]
	v_mfma_f32_16x16x32_bf16 v[32:35], v[166:169], v[218:221], v[32:35]
	v_mfma_f32_16x16x32_bf16 v[60:63], v[162:165], v[178:181], v[60:63]
	v_mfma_f32_16x16x32_bf16 v[56:59], v[170:173], v[178:181], v[56:59]
	v_mfma_f32_16x16x32_bf16 v[52:55], v[162:165], v[206:209], v[52:55]
	v_mfma_f32_16x16x32_bf16 v[48:51], v[170:173], v[206:209], v[48:51]
	v_mfma_f32_16x16x32_bf16 v[44:47], v[162:165], v[214:217], v[44:47]
	v_mfma_f32_16x16x32_bf16 v[40:43], v[170:173], v[214:217], v[40:43]
	v_mfma_f32_16x16x32_bf16 v[36:39], v[162:165], v[222:225], v[36:39]
	v_mfma_f32_16x16x32_bf16 v[32:35], v[170:173], v[222:225], v[32:35]
	v_mfma_f32_16x16x32_bf16 v[28:31], v[226:229], v[174:177], v[28:31]
	v_mfma_f32_16x16x32_bf16 v[24:27], v[234:237], v[174:177], v[24:27]
	v_mfma_f32_16x16x32_bf16 v[20:23], v[226:229], v[182:185], v[20:23]
	v_mfma_f32_16x16x32_bf16 v[16:19], v[234:237], v[182:185], v[16:19]
	v_mfma_f32_16x16x32_bf16 v[12:15], v[226:229], v[210:213], v[12:15]
	v_mfma_f32_16x16x32_bf16 v[8:11], v[234:237], v[210:213], v[8:11]
	v_mfma_f32_16x16x32_bf16 v[4:7], v[226:229], v[218:221], v[4:7]
	v_mfma_f32_16x16x32_bf16 v[0:3], v[234:237], v[218:221], v[0:3]
	v_mfma_f32_16x16x32_bf16 v[28:31], v[230:233], v[178:181], v[28:31]
	v_mfma_f32_16x16x32_bf16 v[24:27], v[238:241], v[178:181], v[24:27]
	v_mfma_f32_16x16x32_bf16 v[20:23], v[230:233], v[206:209], v[20:23]
	v_mfma_f32_16x16x32_bf16 v[16:19], v[238:241], v[206:209], v[16:19]
	v_mfma_f32_16x16x32_bf16 v[12:15], v[230:233], v[214:217], v[12:15]
	v_mfma_f32_16x16x32_bf16 v[8:11], v[238:241], v[214:217], v[8:11]
	v_mfma_f32_16x16x32_bf16 v[4:7], v[230:233], v[222:225], v[4:7]
	v_mfma_f32_16x16x32_bf16 v[0:3], v[238:241], v[222:225], v[0:3]
	s_barrier
	s_cbranch_scc0 .LBB0_386
	s_mov_b32 s100, 1
	v_lshl_add_u32 v158, s75, 10, v155
	ds_read2_b32 v[146:147], v158 offset1:16
	ds_read2_b32 v[208:209], v158 offset0:32 offset1:48
	ds_read2_b32 v[210:211], v158 offset0:128 offset1:144
	ds_read2_b32 v[212:213], v158 offset0:160 offset1:176
	s_add_u32 s52, s10, 0xffffff00
	s_addc_u32 s53, s11, -1
	s_ashr_i32 s35, s34, 31
	s_lshl_b64 s[10:11], s[34:35], 8
	s_waitcnt lgkmcnt(0)
	v_mul_f32_e32 v184, 0xbfb8aa3b, v146
	v_mul_f32_e32 v206, v146, v146
	v_pk_mul_f32 v[168:169], v[124:125], v[184:185] op_sel_hi:[1,0]
	v_pk_mul_f32 v[170:171], v[126:127], v[184:185] op_sel_hi:[1,0]
	v_pk_mul_f32 v[172:173], v[120:121], v[184:185] op_sel_hi:[1,0]
	v_pk_mul_f32 v[174:175], v[122:123], v[184:185] op_sel_hi:[1,0]
	v_exp_f32_e32 v168, v168
	v_exp_f32_e32 v169, v169
	v_exp_f32_e32 v170, v170
	v_exp_f32_e32 v171, v171
	v_exp_f32_e32 v172, v172
	v_exp_f32_e32 v173, v173
	v_exp_f32_e32 v174, v174
	v_exp_f32_e32 v175, v175
	v_pk_mul_f32 v[176:177], v[124:125], v[92:93]
	v_pk_mul_f32 v[178:179], v[126:127], v[94:95]
	v_pk_mul_f32 v[180:181], v[120:121], v[88:89]
	v_pk_mul_f32 v[182:183], v[122:123], v[90:91]
	v_pk_add_f32 v[168:169], v[168:169], 1.0 op_sel_hi:[1,0]
	v_pk_add_f32 v[170:171], v[170:171], 1.0 op_sel_hi:[1,0]
	v_pk_add_f32 v[172:173], v[172:173], 1.0 op_sel_hi:[1,0]
	v_pk_add_f32 v[174:175], v[174:175], 1.0 op_sel_hi:[1,0]
	v_rcp_f32_e32 v168, v168
	v_rcp_f32_e32 v169, v169
	v_rcp_f32_e32 v170, v170
	v_rcp_f32_e32 v171, v171
	v_rcp_f32_e32 v172, v172
	v_rcp_f32_e32 v173, v173
	v_rcp_f32_e32 v174, v174
	v_rcp_f32_e32 v175, v175
	v_pk_mul_f32 v[176:177], v[176:177], v[206:207] op_sel_hi:[1,0]
	v_pk_mul_f32 v[178:179], v[178:179], v[206:207] op_sel_hi:[1,0]
	v_pk_mul_f32 v[180:181], v[180:181], v[206:207] op_sel_hi:[1,0]
	v_pk_mul_f32 v[182:183], v[182:183], v[206:207] op_sel_hi:[1,0]
	v_pk_mul_f32 v[176:177], v[176:177], v[168:169]
	v_pk_mul_f32 v[178:179], v[178:179], v[170:171]
	v_pk_mul_f32 v[180:181], v[180:181], v[172:173]
	v_pk_mul_f32 v[182:183], v[182:183], v[174:175]
	v_cvt_pk_bf16_f32 v160, v176, v177
	v_cvt_pk_bf16_f32 v161, v178, v179
	v_cvt_pk_bf16_f32 v162, v180, v181
	v_cvt_pk_bf16_f32 v163, v182, v183
	v_lshl_add_u64 v[152:153], v[134:135], 0, s[10:11]
	s_movk_i32 s6, 0x1600
	v_lshl_or_b32 v150, s74, 7, v156
	v_ashrrev_i32_e32 v151, 31, v150
	s_nop 1
	v_mov_b64_e32 v[148:149], s[30:31]
	v_mad_u64_u32 v[148:149], s[10:11], v152, s6, v[148:149]
	v_mov_b32_e32 v146, v149
	v_mad_u64_u32 v[152:153], s[10:11], v153, s6, v[146:147]
	v_mov_b32_e32 v149, v152
	v_mov_b32_e32 v146, v147
	v_lshl_add_u64 v[150:151], v[150:151], 1, v[148:149]
	global_store_dwordx4 v[150:151], v[160:163], off
	v_mul_f32_e32 v184, 0xbfb8aa3b, v146
	v_mul_f32_e32 v206, v146, v146
	v_pk_mul_f32 v[168:169], v[116:117], v[184:185] op_sel_hi:[1,0]
	v_pk_mul_f32 v[170:171], v[118:119], v[184:185] op_sel_hi:[1,0]
	v_pk_mul_f32 v[172:173], v[112:113], v[184:185] op_sel_hi:[1,0]
	v_pk_mul_f32 v[174:175], v[114:115], v[184:185] op_sel_hi:[1,0]
	v_exp_f32_e32 v168, v168
	v_exp_f32_e32 v169, v169
	v_exp_f32_e32 v170, v170
	v_exp_f32_e32 v171, v171
	v_exp_f32_e32 v172, v172
	v_exp_f32_e32 v173, v173
	v_exp_f32_e32 v174, v174
	v_exp_f32_e32 v175, v175
	v_pk_mul_f32 v[176:177], v[116:117], v[84:85]
	v_pk_mul_f32 v[178:179], v[118:119], v[86:87]
	v_pk_mul_f32 v[180:181], v[112:113], v[80:81]
	v_pk_mul_f32 v[182:183], v[114:115], v[82:83]
	v_pk_add_f32 v[168:169], v[168:169], 1.0 op_sel_hi:[1,0]
	v_pk_add_f32 v[170:171], v[170:171], 1.0 op_sel_hi:[1,0]
	v_pk_add_f32 v[172:173], v[172:173], 1.0 op_sel_hi:[1,0]
	v_pk_add_f32 v[174:175], v[174:175], 1.0 op_sel_hi:[1,0]
	v_rcp_f32_e32 v168, v168
	v_rcp_f32_e32 v169, v169
	v_rcp_f32_e32 v170, v170
	v_rcp_f32_e32 v171, v171
	v_rcp_f32_e32 v172, v172
	v_rcp_f32_e32 v173, v173
	v_rcp_f32_e32 v174, v174
	v_rcp_f32_e32 v175, v175
	v_pk_mul_f32 v[176:177], v[176:177], v[206:207] op_sel_hi:[1,0]
	v_pk_mul_f32 v[178:179], v[178:179], v[206:207] op_sel_hi:[1,0]
	v_pk_mul_f32 v[180:181], v[180:181], v[206:207] op_sel_hi:[1,0]
	v_pk_mul_f32 v[182:183], v[182:183], v[206:207] op_sel_hi:[1,0]
	v_pk_mul_f32 v[176:177], v[176:177], v[168:169]
	v_pk_mul_f32 v[178:179], v[178:179], v[170:171]
	v_pk_mul_f32 v[180:181], v[180:181], v[172:173]
	v_pk_mul_f32 v[182:183], v[182:183], v[174:175]
	v_cvt_pk_bf16_f32 v160, v176, v177
	v_cvt_pk_bf16_f32 v161, v178, v179
	v_cvt_pk_bf16_f32 v162, v180, v181
	v_cvt_pk_bf16_f32 v163, v182, v183
	s_mov_b32 s6, 0x16000
	s_nop 1
	v_add_co_u32_e32 v146, vcc, s6, v150
	s_nop 0
	v_addc_co_u32_e32 v147, vcc, 0, v151, vcc
	global_store_dwordx4 v[146:147], v[160:163], off
	v_mov_b32_e32 v146, v208
	v_mov_b32_e32 v147, v209
	s_mov_b32 s6, 0x2c000
	s_waitcnt lgkmcnt(0)
	v_mul_f32_e32 v184, 0xbfb8aa3b, v146
	v_mul_f32_e32 v206, v146, v146
	v_pk_mul_f32 v[168:169], v[108:109], v[184:185] op_sel_hi:[1,0]
	v_pk_mul_f32 v[170:171], v[110:111], v[184:185] op_sel_hi:[1,0]
	v_pk_mul_f32 v[172:173], v[104:105], v[184:185] op_sel_hi:[1,0]
	v_pk_mul_f32 v[174:175], v[106:107], v[184:185] op_sel_hi:[1,0]
	v_exp_f32_e32 v168, v168
	v_exp_f32_e32 v169, v169
	v_exp_f32_e32 v170, v170
	v_exp_f32_e32 v171, v171
	v_exp_f32_e32 v172, v172
	v_exp_f32_e32 v173, v173
	v_exp_f32_e32 v174, v174
	v_exp_f32_e32 v175, v175
	v_pk_mul_f32 v[176:177], v[108:109], v[76:77]
	v_pk_mul_f32 v[178:179], v[110:111], v[78:79]
	v_pk_mul_f32 v[180:181], v[104:105], v[72:73]
	v_pk_mul_f32 v[182:183], v[106:107], v[74:75]
	v_pk_add_f32 v[168:169], v[168:169], 1.0 op_sel_hi:[1,0]
	v_pk_add_f32 v[170:171], v[170:171], 1.0 op_sel_hi:[1,0]
	v_pk_add_f32 v[172:173], v[172:173], 1.0 op_sel_hi:[1,0]
	v_pk_add_f32 v[174:175], v[174:175], 1.0 op_sel_hi:[1,0]
	v_rcp_f32_e32 v168, v168
	v_rcp_f32_e32 v169, v169
	v_rcp_f32_e32 v170, v170
	v_rcp_f32_e32 v171, v171
	v_rcp_f32_e32 v172, v172
	v_rcp_f32_e32 v173, v173
	v_rcp_f32_e32 v174, v174
	v_rcp_f32_e32 v175, v175
	v_pk_mul_f32 v[176:177], v[176:177], v[206:207] op_sel_hi:[1,0]
	v_pk_mul_f32 v[178:179], v[178:179], v[206:207] op_sel_hi:[1,0]
	v_pk_mul_f32 v[180:181], v[180:181], v[206:207] op_sel_hi:[1,0]
	v_pk_mul_f32 v[182:183], v[182:183], v[206:207] op_sel_hi:[1,0]
	v_pk_mul_f32 v[176:177], v[176:177], v[168:169]
	v_pk_mul_f32 v[178:179], v[178:179], v[170:171]
	v_pk_mul_f32 v[180:181], v[180:181], v[172:173]
	v_pk_mul_f32 v[182:183], v[182:183], v[174:175]
	v_cvt_pk_bf16_f32 v160, v176, v177
	v_cvt_pk_bf16_f32 v161, v178, v179
	v_cvt_pk_bf16_f32 v162, v180, v181
	v_cvt_pk_bf16_f32 v163, v182, v183
	s_nop 1
	v_mov_b32_e32 v146, v147
	v_add_co_u32_e32 v148, vcc, s6, v150
	v_addc_co_u32_e32 v149, vcc, 0, v151, vcc
	global_store_dwordx4 v[148:149], v[160:163], off
	v_mul_f32_e32 v184, 0xbfb8aa3b, v146
	v_mul_f32_e32 v206, v146, v146
	v_pk_mul_f32 v[168:169], v[100:101], v[184:185] op_sel_hi:[1,0]
	v_pk_mul_f32 v[170:171], v[102:103], v[184:185] op_sel_hi:[1,0]
	v_pk_mul_f32 v[172:173], v[96:97], v[184:185] op_sel_hi:[1,0]
	v_pk_mul_f32 v[174:175], v[98:99], v[184:185] op_sel_hi:[1,0]
	v_exp_f32_e32 v168, v168
	v_exp_f32_e32 v169, v169
	v_exp_f32_e32 v170, v170
	v_exp_f32_e32 v171, v171
	v_exp_f32_e32 v172, v172
	v_exp_f32_e32 v173, v173
	v_exp_f32_e32 v174, v174
	v_exp_f32_e32 v175, v175
	v_pk_mul_f32 v[176:177], v[100:101], v[68:69]
	v_pk_mul_f32 v[178:179], v[102:103], v[70:71]
	v_pk_mul_f32 v[180:181], v[96:97], v[64:65]
	v_pk_mul_f32 v[182:183], v[98:99], v[66:67]
	v_pk_add_f32 v[168:169], v[168:169], 1.0 op_sel_hi:[1,0]
	v_pk_add_f32 v[170:171], v[170:171], 1.0 op_sel_hi:[1,0]
	v_pk_add_f32 v[172:173], v[172:173], 1.0 op_sel_hi:[1,0]
	v_pk_add_f32 v[174:175], v[174:175], 1.0 op_sel_hi:[1,0]
	v_rcp_f32_e32 v168, v168
	v_rcp_f32_e32 v169, v169
	v_rcp_f32_e32 v170, v170
	v_rcp_f32_e32 v171, v171
	v_rcp_f32_e32 v172, v172
	v_rcp_f32_e32 v173, v173
	v_rcp_f32_e32 v174, v174
	v_rcp_f32_e32 v175, v175
	v_pk_mul_f32 v[176:177], v[176:177], v[206:207] op_sel_hi:[1,0]
	v_pk_mul_f32 v[178:179], v[178:179], v[206:207] op_sel_hi:[1,0]
	v_pk_mul_f32 v[180:181], v[180:181], v[206:207] op_sel_hi:[1,0]
	v_pk_mul_f32 v[182:183], v[182:183], v[206:207] op_sel_hi:[1,0]
	v_pk_mul_f32 v[176:177], v[176:177], v[168:169]
	v_pk_mul_f32 v[178:179], v[178:179], v[170:171]
	v_pk_mul_f32 v[180:181], v[180:181], v[172:173]
	v_pk_mul_f32 v[182:183], v[182:183], v[174:175]
	v_cvt_pk_bf16_f32 v160, v176, v177
	v_cvt_pk_bf16_f32 v161, v178, v179
	v_cvt_pk_bf16_f32 v162, v180, v181
	v_cvt_pk_bf16_f32 v163, v182, v183
	s_mov_b32 s6, 0x42000
	s_nop 1
	v_add_co_u32_e32 v146, vcc, s6, v150
	s_nop 0
	v_addc_co_u32_e32 v147, vcc, 0, v151, vcc
	global_store_dwordx4 v[146:147], v[160:163], off
	v_mov_b32_e32 v146, v210
	v_mov_b32_e32 v147, v211
	s_mov_b32 s6, 0xb0000
	s_waitcnt lgkmcnt(0)
	v_mul_f32_e32 v184, 0xbfb8aa3b, v146
	v_mul_f32_e32 v206, v146, v146
	v_pk_mul_f32 v[168:169], v[60:61], v[184:185] op_sel_hi:[1,0]
	v_pk_mul_f32 v[170:171], v[62:63], v[184:185] op_sel_hi:[1,0]
	v_pk_mul_f32 v[172:173], v[56:57], v[184:185] op_sel_hi:[1,0]
	v_pk_mul_f32 v[174:175], v[58:59], v[184:185] op_sel_hi:[1,0]
	v_exp_f32_e32 v168, v168
	v_exp_f32_e32 v169, v169
	v_exp_f32_e32 v170, v170
	v_exp_f32_e32 v171, v171
	v_exp_f32_e32 v172, v172
	v_exp_f32_e32 v173, v173
	v_exp_f32_e32 v174, v174
	v_exp_f32_e32 v175, v175
	v_pk_mul_f32 v[176:177], v[60:61], v[28:29]
	v_pk_mul_f32 v[178:179], v[62:63], v[30:31]
	v_pk_mul_f32 v[180:181], v[56:57], v[24:25]
	v_pk_mul_f32 v[182:183], v[58:59], v[26:27]
	v_pk_add_f32 v[168:169], v[168:169], 1.0 op_sel_hi:[1,0]
	v_pk_add_f32 v[170:171], v[170:171], 1.0 op_sel_hi:[1,0]
	v_pk_add_f32 v[172:173], v[172:173], 1.0 op_sel_hi:[1,0]
	v_pk_add_f32 v[174:175], v[174:175], 1.0 op_sel_hi:[1,0]
	v_rcp_f32_e32 v168, v168
	v_rcp_f32_e32 v169, v169
	v_rcp_f32_e32 v170, v170
	v_rcp_f32_e32 v171, v171
	v_rcp_f32_e32 v172, v172
	v_rcp_f32_e32 v173, v173
	v_rcp_f32_e32 v174, v174
	v_rcp_f32_e32 v175, v175
	v_pk_mul_f32 v[176:177], v[176:177], v[206:207] op_sel_hi:[1,0]
	v_pk_mul_f32 v[178:179], v[178:179], v[206:207] op_sel_hi:[1,0]
	v_pk_mul_f32 v[180:181], v[180:181], v[206:207] op_sel_hi:[1,0]
	v_pk_mul_f32 v[182:183], v[182:183], v[206:207] op_sel_hi:[1,0]
	v_pk_mul_f32 v[176:177], v[176:177], v[168:169]
	v_pk_mul_f32 v[178:179], v[178:179], v[170:171]
	v_pk_mul_f32 v[180:181], v[180:181], v[172:173]
	v_pk_mul_f32 v[182:183], v[182:183], v[174:175]
	v_cvt_pk_bf16_f32 v160, v176, v177
	v_cvt_pk_bf16_f32 v161, v178, v179
	v_cvt_pk_bf16_f32 v162, v180, v181
	v_cvt_pk_bf16_f32 v163, v182, v183
	s_nop 1
	v_mov_b32_e32 v146, v147
	v_add_co_u32_e32 v148, vcc, s6, v150
	v_addc_co_u32_e32 v149, vcc, 0, v151, vcc
	global_store_dwordx4 v[148:149], v[160:163], off
	v_mul_f32_e32 v184, 0xbfb8aa3b, v146
	v_mul_f32_e32 v206, v146, v146
	v_pk_mul_f32 v[168:169], v[52:53], v[184:185] op_sel_hi:[1,0]
	v_pk_mul_f32 v[170:171], v[54:55], v[184:185] op_sel_hi:[1,0]
	v_pk_mul_f32 v[172:173], v[48:49], v[184:185] op_sel_hi:[1,0]
	v_pk_mul_f32 v[174:175], v[50:51], v[184:185] op_sel_hi:[1,0]
	v_exp_f32_e32 v168, v168
	v_exp_f32_e32 v169, v169
	v_exp_f32_e32 v170, v170
	v_exp_f32_e32 v171, v171
	v_exp_f32_e32 v172, v172
	v_exp_f32_e32 v173, v173
	v_exp_f32_e32 v174, v174
	v_exp_f32_e32 v175, v175
	v_pk_mul_f32 v[176:177], v[52:53], v[20:21]
	v_pk_mul_f32 v[178:179], v[54:55], v[22:23]
	v_pk_mul_f32 v[180:181], v[48:49], v[16:17]
	v_pk_mul_f32 v[182:183], v[50:51], v[18:19]
	v_pk_add_f32 v[168:169], v[168:169], 1.0 op_sel_hi:[1,0]
	v_pk_add_f32 v[170:171], v[170:171], 1.0 op_sel_hi:[1,0]
	v_pk_add_f32 v[172:173], v[172:173], 1.0 op_sel_hi:[1,0]
	v_pk_add_f32 v[174:175], v[174:175], 1.0 op_sel_hi:[1,0]
	v_rcp_f32_e32 v168, v168
	v_rcp_f32_e32 v169, v169
	v_rcp_f32_e32 v170, v170
	v_rcp_f32_e32 v171, v171
	v_rcp_f32_e32 v172, v172
	v_rcp_f32_e32 v173, v173
	v_rcp_f32_e32 v174, v174
	v_rcp_f32_e32 v175, v175
	v_pk_mul_f32 v[176:177], v[176:177], v[206:207] op_sel_hi:[1,0]
	v_pk_mul_f32 v[178:179], v[178:179], v[206:207] op_sel_hi:[1,0]
	v_pk_mul_f32 v[180:181], v[180:181], v[206:207] op_sel_hi:[1,0]
	v_pk_mul_f32 v[182:183], v[182:183], v[206:207] op_sel_hi:[1,0]
	v_pk_mul_f32 v[176:177], v[176:177], v[168:169]
	v_pk_mul_f32 v[178:179], v[178:179], v[170:171]
	v_pk_mul_f32 v[180:181], v[180:181], v[172:173]
	v_pk_mul_f32 v[182:183], v[182:183], v[174:175]
	v_cvt_pk_bf16_f32 v160, v176, v177
	v_cvt_pk_bf16_f32 v161, v178, v179
	v_cvt_pk_bf16_f32 v162, v180, v181
	v_cvt_pk_bf16_f32 v163, v182, v183
	s_mov_b32 s6, 0xc6000
	s_nop 1
	v_add_co_u32_e32 v146, vcc, s6, v150
	s_nop 0
	v_addc_co_u32_e32 v147, vcc, 0, v151, vcc
	global_store_dwordx4 v[146:147], v[160:163], off
	v_mov_b32_e32 v146, v212
	v_mov_b32_e32 v147, v213
	s_mov_b32 s6, 0xdc000
	s_waitcnt lgkmcnt(0)
	v_mul_f32_e32 v184, 0xbfb8aa3b, v146
	v_mul_f32_e32 v206, v146, v146
	v_pk_mul_f32 v[168:169], v[44:45], v[184:185] op_sel_hi:[1,0]
	v_pk_mul_f32 v[170:171], v[46:47], v[184:185] op_sel_hi:[1,0]
	v_pk_mul_f32 v[172:173], v[40:41], v[184:185] op_sel_hi:[1,0]
	v_pk_mul_f32 v[174:175], v[42:43], v[184:185] op_sel_hi:[1,0]
	v_exp_f32_e32 v168, v168
	v_exp_f32_e32 v169, v169
	v_exp_f32_e32 v170, v170
	v_exp_f32_e32 v171, v171
	v_exp_f32_e32 v172, v172
	v_exp_f32_e32 v173, v173
	v_exp_f32_e32 v174, v174
	v_exp_f32_e32 v175, v175
	v_pk_mul_f32 v[176:177], v[44:45], v[12:13]
	v_pk_mul_f32 v[178:179], v[46:47], v[14:15]
	v_pk_mul_f32 v[180:181], v[40:41], v[8:9]
	v_pk_mul_f32 v[182:183], v[42:43], v[10:11]
	v_pk_add_f32 v[168:169], v[168:169], 1.0 op_sel_hi:[1,0]
	v_pk_add_f32 v[170:171], v[170:171], 1.0 op_sel_hi:[1,0]
	v_pk_add_f32 v[172:173], v[172:173], 1.0 op_sel_hi:[1,0]
	v_pk_add_f32 v[174:175], v[174:175], 1.0 op_sel_hi:[1,0]
	v_rcp_f32_e32 v168, v168
	v_rcp_f32_e32 v169, v169
	v_rcp_f32_e32 v170, v170
	v_rcp_f32_e32 v171, v171
	v_rcp_f32_e32 v172, v172
	v_rcp_f32_e32 v173, v173
	v_rcp_f32_e32 v174, v174
	v_rcp_f32_e32 v175, v175
	v_pk_mul_f32 v[176:177], v[176:177], v[206:207] op_sel_hi:[1,0]
	v_pk_mul_f32 v[178:179], v[178:179], v[206:207] op_sel_hi:[1,0]
	v_pk_mul_f32 v[180:181], v[180:181], v[206:207] op_sel_hi:[1,0]
	v_pk_mul_f32 v[182:183], v[182:183], v[206:207] op_sel_hi:[1,0]
	v_pk_mul_f32 v[176:177], v[176:177], v[168:169]
	v_pk_mul_f32 v[178:179], v[178:179], v[170:171]
	v_pk_mul_f32 v[180:181], v[180:181], v[172:173]
	v_pk_mul_f32 v[182:183], v[182:183], v[174:175]
	v_cvt_pk_bf16_f32 v158, v176, v177
	v_cvt_pk_bf16_f32 v159, v178, v179
	v_cvt_pk_bf16_f32 v160, v180, v181
	v_cvt_pk_bf16_f32 v161, v182, v183
	s_nop 1
	v_mov_b32_e32 v146, v147
	v_add_co_u32_e32 v148, vcc, s6, v150
	v_addc_co_u32_e32 v149, vcc, 0, v151, vcc
	global_store_dwordx4 v[148:149], v[158:161], off
	v_mul_f32_e32 v184, 0xbfb8aa3b, v146
	v_mul_f32_e32 v206, v146, v146
	v_pk_mul_f32 v[168:169], v[36:37], v[184:185] op_sel_hi:[1,0]
	v_pk_mul_f32 v[170:171], v[38:39], v[184:185] op_sel_hi:[1,0]
	v_pk_mul_f32 v[172:173], v[32:33], v[184:185] op_sel_hi:[1,0]
	v_pk_mul_f32 v[174:175], v[34:35], v[184:185] op_sel_hi:[1,0]
	v_exp_f32_e32 v168, v168
	v_exp_f32_e32 v169, v169
	v_exp_f32_e32 v170, v170
	v_exp_f32_e32 v171, v171
	v_exp_f32_e32 v172, v172
	v_exp_f32_e32 v173, v173
	v_exp_f32_e32 v174, v174
	v_exp_f32_e32 v175, v175
	v_pk_mul_f32 v[176:177], v[36:37], v[4:5]
	v_pk_mul_f32 v[178:179], v[38:39], v[6:7]
	v_pk_mul_f32 v[180:181], v[32:33], v[0:1]
	v_pk_mul_f32 v[182:183], v[34:35], v[2:3]
	v_pk_add_f32 v[168:169], v[168:169], 1.0 op_sel_hi:[1,0]
	v_pk_add_f32 v[170:171], v[170:171], 1.0 op_sel_hi:[1,0]
	v_pk_add_f32 v[172:173], v[172:173], 1.0 op_sel_hi:[1,0]
	v_pk_add_f32 v[174:175], v[174:175], 1.0 op_sel_hi:[1,0]
	v_rcp_f32_e32 v168, v168
	v_rcp_f32_e32 v169, v169
	v_rcp_f32_e32 v170, v170
	v_rcp_f32_e32 v171, v171
	v_rcp_f32_e32 v172, v172
	v_rcp_f32_e32 v173, v173
	v_rcp_f32_e32 v174, v174
	v_rcp_f32_e32 v175, v175
	v_pk_mul_f32 v[176:177], v[176:177], v[206:207] op_sel_hi:[1,0]
	v_pk_mul_f32 v[178:179], v[178:179], v[206:207] op_sel_hi:[1,0]
	v_pk_mul_f32 v[180:181], v[180:181], v[206:207] op_sel_hi:[1,0]
	v_pk_mul_f32 v[182:183], v[182:183], v[206:207] op_sel_hi:[1,0]
	v_pk_mul_f32 v[176:177], v[176:177], v[168:169]
	v_pk_mul_f32 v[178:179], v[178:179], v[170:171]
	v_pk_mul_f32 v[180:181], v[180:181], v[172:173]
	v_pk_mul_f32 v[182:183], v[182:183], v[174:175]
	v_cvt_pk_bf16_f32 v158, v176, v177
	v_cvt_pk_bf16_f32 v159, v178, v179
	v_cvt_pk_bf16_f32 v160, v180, v181
	v_cvt_pk_bf16_f32 v161, v182, v183
	s_nop 1
	v_add_co_u32_e32 v146, vcc, 0xf2000, v150
	s_nop 0
	v_addc_co_u32_e32 v147, vcc, 0, v151, vcc
	s_andn2_b64 vcc, exec, s[44:45]
	global_store_dwordx4 v[146:147], v[158:161], off
	s_cbranch_vccz .LBB0_382
	s_mov_b64 s[48:49], s[52:53]
	s_andn2_b64 vcc, exec, s[42:43]
	s_mov_b64 s[52:53], s[48:49]
	s_cbranch_vccnz .LBB0_383
